# A/B: 4-phase GEMM loops with inverted per-segment priority (load-role segment at prio 1, MFMA segment at prio 0)
# baseline (speedup 1.0000x reference)
; #define PG8_STAGE(bufoff, gbase, voff) do { _Pragma("unroll") for (int _i = 0; _i < 2; ++_i) \
;         __builtin_amdgcn_global_load_lds((const unsigned*)((const char*)(gbase) + (voff)[_i]), (LAS unsigned*)(lds + (bufoff) + ldsw + _i * 8192), 16, 0, 0); } while (0)
; #define PG8_LDA(dst, b, h) do { _Pragma("unroll") for (int m = 0; m < 4; ++m) _Pragma("unroll") for (int k = 0; k < 2; ++k) dst[m][k] = *(const LAS bf16x8*)(lds + PG8_SA(b, h) + aoff + m * 2048 + k * 1024); } while (0)
; #define PG8_LDB(dst, b, h) do { _Pragma("unroll") for (int n = 0; n < 2; ++n) _Pragma("unroll") for (int k = 0; k < 2; ++k) dst[n][k] = *(const LAS bf16x8*)(lds + PG8_SB(b, h) + boff + n * 2048 + k * 1024); } while (0)
; #define PG8_MMA(ai, bj, At, Bt) do { __builtin_amdgcn_s_setprio(1); _Pragma("unroll") for (int m = 0; m < 4; ++m) _Pragma("unroll") for (int n = 0; n < 2; ++n) _Pragma("unroll") for (int k = 0; k < 2; ++k) \
;         acc[ai][bj][m][n] = __builtin_amdgcn_mfma_f32_16x16x32_bf16(Bt[n][k], At[m][k], acc[ai][bj][m][n], 0, 0, 0); __builtin_amdgcn_s_setprio(0); } while (0)
; #define PG8_WAIT_V(n) asm volatile("s_waitcnt vmcnt(" #n ")" ::: "memory")
; #define PG8_WAIT_L(n) asm volatile("s_waitcnt lgkmcnt(" #n ")" ::: "memory")
; template <class Epi, class Sched>
; __device__ __forceinline__ void gemm_phase(LAS unsigned char* lds, const Gemm g, const Sched& S, const Epi& E) {
;     ...
;         for (int t = 0; t < nt; t += 2) {
;             const bool last = (t == nt - 2);
;             const char* a1 = cA + (size_t)(t + 1) * kstep;
;             const char* a2 = last ? nA : cA + (size_t)(t + 2) * kstep; const char* b2 = last ? nB : cB + (size_t)(t + 2) * kstep;
;             const char* a3 = a2 + kstep; const char* b3 = b2 + kstep;
;             PG8_LDB(B0, 0, 0); PG8_SCHED; PG8_LDA(At, 0, 0); PG8_STAGE(PG8_SA(1, 1), a1 + hstep, voffA);
;             PG8_WAIT_L(8); PG8_BAR; PG8_WAIT_L(0); PG8_MMA(0, 0, At, B0); PG8_BAR; PG8_SCHED;
;             PG8_LDB(B1, 0, 1); PG8_STAGE(PG8_SB(0, 0), b2, voffB);
;             PG8_BAR; PG8_WAIT_L(0); PG8_MMA(0, 1, At, B1); PG8_BAR;
;             PG8_LDA(At, 0, 1); PG8_STAGE(PG8_SA(0, 0), a2, voffA);
;             PG8_BAR; PG8_WAIT_L(0); PG8_MMA(1, 0, At, B0); PG8_BAR; PG8_SCHED;
;             PG8_STAGE(PG8_SB(0, 1), b2 + hstep, voffB);
;             PG8_WAIT_V(6); PG8_BAR; PG8_MMA(1, 1, At, B1); PG8_BAR;
.LBB0_44:
	s_add_u32 s50, s28, 0x100
	s_addc_u32 s51, s29, 0
	s_cmpk_eq_i32 s75, 0x7c
	s_cselect_b32 s55, s27, s51
	s_cselect_b32 s54, s71, s50
	s_cselect_b32 s53, s25, s74
	s_cselect_b32 s52, s72, s73
	v_lshl_add_u64 v[156:157], s[28:29], 0, v[150:151]
	s_add_i32 m0, s9, 0xc000
	s_nop 0
	global_load_lds_dwordx4 v[156:157], off
	v_lshl_add_u64 v[156:157], s[28:29], 0, v[148:149]
	s_add_i32 m0, s9, 0xe000
	s_nop 0
	global_load_lds_dwordx4 v[156:157], off
	s_add_i32 s38, 0, 0x10000
	v_add_u32_e32 v78, s38, v163
	ds_read_b128 v[66:69], v78
	ds_read_b128 v[70:73], v78 offset:1024
	ds_read_b128 v[74:77], v78 offset:2048
	ds_read_b128 v[78:81], v78 offset:3072
	ds_read_b128 v[152:155], v165
	ds_read_b128 v[166:169], v165 offset:1024
	ds_read_b128 v[170:173], v165 offset:2048
	ds_read_b128 v[174:177], v165 offset:3072
	ds_read_b128 v[178:181], v165 offset:4096
	ds_read_b128 v[182:185], v165 offset:5120
	ds_read_b128 v[186:189], v165 offset:6144
	ds_read_b128 v[190:193], v165 offset:7168
	s_add_i32 s39, 0, 0x14000
	v_add_u32_e32 v156, s39, v163
	ds_read_b128 v[194:197], v156
	ds_read_b128 v[198:201], v156 offset:1024
	ds_read_b128 v[202:205], v156 offset:2048
	ds_read_b128 v[210:213], v156 offset:3072
	s_waitcnt lgkmcnt(4)
	s_barrier
	s_waitcnt lgkmcnt(0)
	s_setprio 0
	v_mfma_f32_16x16x32_bf16 v[142:145], v[66:69], v[152:155], v[142:145]
	v_mfma_f32_16x16x32_bf16 v[138:141], v[74:77], v[152:155], v[138:141]
	v_mfma_f32_16x16x32_bf16 v[126:129], v[66:69], v[170:173], v[126:129]
	v_mfma_f32_16x16x32_bf16 v[122:125], v[74:77], v[170:173], v[122:125]
	v_mfma_f32_16x16x32_bf16 v[110:113], v[66:69], v[178:181], v[110:113]
	v_mfma_f32_16x16x32_bf16 v[106:109], v[74:77], v[178:181], v[106:109]
	v_mfma_f32_16x16x32_bf16 v[102:105], v[66:69], v[186:189], v[102:105]
	v_mfma_f32_16x16x32_bf16 v[98:101], v[74:77], v[186:189], v[98:101]
	v_mfma_f32_16x16x32_bf16 v[142:145], v[70:73], v[166:169], v[142:145]
	v_mfma_f32_16x16x32_bf16 v[138:141], v[78:81], v[166:169], v[138:141]
	v_mfma_f32_16x16x32_bf16 v[126:129], v[70:73], v[174:177], v[126:129]
	v_mfma_f32_16x16x32_bf16 v[122:125], v[78:81], v[174:177], v[122:125]
	v_mfma_f32_16x16x32_bf16 v[110:113], v[70:73], v[182:185], v[110:113]
	v_mfma_f32_16x16x32_bf16 v[106:109], v[78:81], v[182:185], v[106:109]
	v_mfma_f32_16x16x32_bf16 v[102:105], v[70:73], v[190:193], v[102:105]
	v_mfma_f32_16x16x32_bf16 v[98:101], v[78:81], v[190:193], v[98:101]
	v_mfma_f32_16x16x32_bf16 v[134:137], v[194:197], v[152:155], v[134:137]
	v_mfma_f32_16x16x32_bf16 v[130:133], v[202:205], v[152:155], v[130:133]
	v_mfma_f32_16x16x32_bf16 v[118:121], v[194:197], v[170:173], v[118:121]
	v_mfma_f32_16x16x32_bf16 v[114:117], v[202:205], v[170:173], v[114:117]
	v_mfma_f32_16x16x32_bf16 v[94:97], v[194:197], v[178:181], v[94:97]
	v_mfma_f32_16x16x32_bf16 v[90:93], v[202:205], v[178:181], v[90:93]
	v_mfma_f32_16x16x32_bf16 v[86:89], v[194:197], v[186:189], v[86:89]
	v_mfma_f32_16x16x32_bf16 v[82:85], v[202:205], v[186:189], v[82:85]
	v_mfma_f32_16x16x32_bf16 v[134:137], v[198:201], v[166:169], v[134:137]
	v_mfma_f32_16x16x32_bf16 v[130:133], v[210:213], v[166:169], v[130:133]
	v_mfma_f32_16x16x32_bf16 v[118:121], v[198:201], v[174:177], v[118:121]
	v_mfma_f32_16x16x32_bf16 v[114:117], v[210:213], v[174:177], v[114:117]
	v_mfma_f32_16x16x32_bf16 v[94:97], v[198:201], v[182:185], v[94:97]
	v_mfma_f32_16x16x32_bf16 v[90:93], v[210:213], v[182:185], v[90:93]
	v_mfma_f32_16x16x32_bf16 v[86:89], v[198:201], v[190:193], v[86:89]
	v_mfma_f32_16x16x32_bf16 v[82:85], v[210:213], v[190:193], v[82:85]
	s_setprio 1
	s_barrier
	s_add_i32 s28, s38, s60
	v_lshl_add_u64 v[156:157], s[52:53], 0, v[0:1]
	s_mov_b32 m0, s28
	v_lshl_add_u64 v[160:161], s[52:53], 0, v[146:147]
	global_load_lds_dwordx4 v[156:157], off
	s_add_i32 m0, s28, 0x2000
	s_nop 0
	global_load_lds_dwordx4 v[160:161], off
	s_mov_b32 m0, s9
	v_lshl_add_u64 v[206:207], s[54:55], 0, v[0:1]
	global_load_lds_dwordx4 v[206:207], off
	v_lshl_add_u64 v[214:215], s[54:55], 0, v[146:147]
	s_mov_b32 m0, s61
	s_nop 0
	global_load_lds_dwordx4 v[214:215], off
	ds_read_b128 v[152:155], v165 offset:16384
	ds_read_b128 v[166:169], v165 offset:17408
	ds_read_b128 v[170:173], v165 offset:18432
	ds_read_b128 v[174:177], v165 offset:19456
	ds_read_b128 v[178:181], v165 offset:20480
	ds_read_b128 v[182:185], v165 offset:21504
	ds_read_b128 v[186:189], v165 offset:22528
	ds_read_b128 v[190:193], v165 offset:23552
	s_waitcnt vmcnt(4)
	s_waitcnt lgkmcnt(0)
	s_barrier
	s_setprio 0
	v_mfma_f32_16x16x32_bf16 v[62:65], v[66:69], v[152:155], v[62:65]
	v_mfma_f32_16x16x32_bf16 v[58:61], v[74:77], v[152:155], v[58:61]
	v_mfma_f32_16x16x32_bf16 v[46:49], v[66:69], v[170:173], v[46:49]
	v_mfma_f32_16x16x32_bf16 v[42:45], v[74:77], v[170:173], v[42:45]
	v_mfma_f32_16x16x32_bf16 v[30:33], v[66:69], v[178:181], v[30:33]
	v_mfma_f32_16x16x32_bf16 v[26:29], v[74:77], v[178:181], v[26:29]
	v_mfma_f32_16x16x32_bf16 v[22:25], v[66:69], v[186:189], v[22:25]
	v_mfma_f32_16x16x32_bf16 v[14:17], v[74:77], v[186:189], v[14:17]
	v_mfma_f32_16x16x32_bf16 v[62:65], v[70:73], v[166:169], v[62:65]
	v_mfma_f32_16x16x32_bf16 v[58:61], v[78:81], v[166:169], v[58:61]
	v_mfma_f32_16x16x32_bf16 v[46:49], v[70:73], v[174:177], v[46:49]
	v_mfma_f32_16x16x32_bf16 v[42:45], v[78:81], v[174:177], v[42:45]
	v_mfma_f32_16x16x32_bf16 v[30:33], v[70:73], v[182:185], v[30:33]
	v_mfma_f32_16x16x32_bf16 v[26:29], v[78:81], v[182:185], v[26:29]
	v_mfma_f32_16x16x32_bf16 v[22:25], v[70:73], v[190:193], v[22:25]
	v_mfma_f32_16x16x32_bf16 v[14:17], v[78:81], v[190:193], v[14:17]
	v_mfma_f32_16x16x32_bf16 v[54:57], v[194:197], v[152:155], v[54:57]
	v_mfma_f32_16x16x32_bf16 v[50:53], v[202:205], v[152:155], v[50:53]
	v_mfma_f32_16x16x32_bf16 v[38:41], v[194:197], v[170:173], v[38:41]
	v_mfma_f32_16x16x32_bf16 v[34:37], v[202:205], v[170:173], v[34:37]
	v_mfma_f32_16x16x32_bf16 v[18:21], v[194:197], v[178:181], v[18:21]
	v_mfma_f32_16x16x32_bf16 v[10:13], v[202:205], v[178:181], v[10:13]
	v_mfma_f32_16x16x32_bf16 v[6:9], v[194:197], v[186:189], v[6:9]
	v_mfma_f32_16x16x32_bf16 v[2:5], v[202:205], v[186:189], v[2:5]
	v_mfma_f32_16x16x32_bf16 v[54:57], v[198:201], v[166:169], v[54:57]
	v_mfma_f32_16x16x32_bf16 v[50:53], v[210:213], v[166:169], v[50:53]
	v_mfma_f32_16x16x32_bf16 v[38:41], v[198:201], v[174:177], v[38:41]
	v_mfma_f32_16x16x32_bf16 v[34:37], v[210:213], v[174:177], v[34:37]
	v_mfma_f32_16x16x32_bf16 v[18:21], v[198:201], v[182:185], v[18:21]
	v_mfma_f32_16x16x32_bf16 v[10:13], v[210:213], v[182:185], v[10:13]
	v_mfma_f32_16x16x32_bf16 v[6:9], v[198:201], v[190:193], v[6:9]
	v_mfma_f32_16x16x32_bf16 v[2:5], v[210:213], v[190:193], v[2:5]
	s_setprio 1
	s_barrier
; #define PG8_STAGE(bufoff, gbase, voff) do { _Pragma("unroll") for (int _i = 0; _i < 2; ++_i) \
;         __builtin_amdgcn_global_load_lds((const unsigned*)((const char*)(gbase) + (voff)[_i]), (LAS unsigned*)(lds + (bufoff) + ldsw + _i * 8192), 16, 0, 0); } while (0)
; #define PG8_LDA(dst, b, h) do { _Pragma("unroll") for (int m = 0; m < 4; ++m) _Pragma("unroll") for (int k = 0; k < 2; ++k) dst[m][k] = *(const LAS bf16x8*)(lds + PG8_SA(b, h) + aoff + m * 2048 + k * 1024); } while (0)
; #define PG8_LDB(dst, b, h) do { _Pragma("unroll") for (int n = 0; n < 2; ++n) _Pragma("unroll") for (int k = 0; k < 2; ++k) dst[n][k] = *(const LAS bf16x8*)(lds + PG8_SB(b, h) + boff + n * 2048 + k * 1024); } while (0)
; #define PG8_MMA(ai, bj, At, Bt) do { __builtin_amdgcn_s_setprio(1); _Pragma("unroll") for (int m = 0; m < 4; ++m) _Pragma("unroll") for (int n = 0; n < 2; ++n) _Pragma("unroll") for (int k = 0; k < 2; ++k) \
;         acc[ai][bj][m][n] = __builtin_amdgcn_mfma_f32_16x16x32_bf16(Bt[n][k], At[m][k], acc[ai][bj][m][n], 0, 0, 0); __builtin_amdgcn_s_setprio(0); } while (0)
; #define PG8_WAIT_V(n) asm volatile("s_waitcnt vmcnt(" #n ")" ::: "memory")
; #define PG8_WAIT_L(n) asm volatile("s_waitcnt lgkmcnt(" #n ")" ::: "memory")
; #define PG8_BAR __builtin_amdgcn_s_barrier()
; #define PG8_SCHED __builtin_amdgcn_sched_barrier(0)
; template <class Epi, class Sched>
; __device__ __forceinline__ void gemm_phase(LAS unsigned char* lds, const Gemm g, const Sched& S, const Epi& E) {
;     ...
;             PG8_STAGE(PG8_SB(0, 1), b2 + hstep, voffB);
;             PG8_WAIT_V(6); PG8_BAR; PG8_MMA(1, 1, At, B1); PG8_BAR;
;             PG8_LDB(B0, 1, 0); PG8_SCHED; PG8_LDA(At, 1, 0); PG8_STAGE(PG8_SA(0, 1), a2 + hstep, voffA);
;             PG8_WAIT_L(8); PG8_BAR; PG8_WAIT_L(0); PG8_MMA(0, 0, At, B0); PG8_BAR; PG8_SCHED;
;             PG8_LDB(B1, 1, 1); PG8_STAGE(PG8_SB(1, 0), b3, voffB);
;             PG8_BAR; PG8_WAIT_L(0); PG8_MMA(0, 1, At, B1); PG8_BAR;
	s_add_u32 s28, s52, 0x200000
	s_addc_u32 s29, s53, 0
	s_add_i32 s38, s39, s60
	v_lshl_add_u64 v[66:67], s[28:29], 0, v[0:1]
	s_mov_b32 m0, s38
	s_nop 0
	global_load_lds_dwordx4 v[66:67], off
	v_lshl_add_u64 v[66:67], s[28:29], 0, v[146:147]
	s_add_i32 m0, s38, 0x2000
	s_nop 0
	global_load_lds_dwordx4 v[66:67], off
	s_add_u32 s28, s54, 0x200000
	s_addc_u32 s29, s55, 0
	s_mov_b32 m0, s62
	v_lshl_add_u64 v[194:195], s[28:29], 0, v[0:1]
	global_load_lds_dwordx4 v[194:195], off
	v_lshl_add_u64 v[194:195], s[28:29], 0, v[146:147]
	s_mov_b32 m0, s63
	s_nop 0
	global_load_lds_dwordx4 v[194:195], off
	s_add_i32 s38, 0, 0x18000
	v_add_u32_e32 v78, s38, v163
	ds_read_b128 v[66:69], v78
	ds_read_b128 v[70:73], v78 offset:1024
	ds_read_b128 v[74:77], v78 offset:2048
	ds_read_b128 v[78:81], v78 offset:3072
	ds_read_b128 v[152:155], v165 offset:32768
	ds_read_b128 v[166:169], v165 offset:33792
	ds_read_b128 v[170:173], v165 offset:34816
	ds_read_b128 v[174:177], v165 offset:35840
	ds_read_b128 v[178:181], v165 offset:36864
	ds_read_b128 v[182:185], v165 offset:37888
	ds_read_b128 v[186:189], v165 offset:38912
	ds_read_b128 v[190:193], v165 offset:39936
	s_add_i32 s39, 0, 0x1c000
	v_add_u32_e32 v210, s39, v163
	ds_read_b128 v[194:197], v210
	ds_read_b128 v[198:201], v210 offset:1024
	ds_read_b128 v[202:205], v210 offset:2048
	ds_read_b128 v[210:213], v210 offset:3072
	s_waitcnt lgkmcnt(4)
	s_barrier
	s_waitcnt lgkmcnt(0)
	s_setprio 0
	v_mfma_f32_16x16x32_bf16 v[142:145], v[66:69], v[152:155], v[142:145]
	v_mfma_f32_16x16x32_bf16 v[138:141], v[74:77], v[152:155], v[138:141]
	v_mfma_f32_16x16x32_bf16 v[126:129], v[66:69], v[170:173], v[126:129]
	v_mfma_f32_16x16x32_bf16 v[122:125], v[74:77], v[170:173], v[122:125]
	v_mfma_f32_16x16x32_bf16 v[110:113], v[66:69], v[178:181], v[110:113]
	v_mfma_f32_16x16x32_bf16 v[106:109], v[74:77], v[178:181], v[106:109]
	v_mfma_f32_16x16x32_bf16 v[102:105], v[66:69], v[186:189], v[102:105]
	v_mfma_f32_16x16x32_bf16 v[98:101], v[74:77], v[186:189], v[98:101]
	v_mfma_f32_16x16x32_bf16 v[142:145], v[70:73], v[166:169], v[142:145]
	v_mfma_f32_16x16x32_bf16 v[138:141], v[78:81], v[166:169], v[138:141]
	v_mfma_f32_16x16x32_bf16 v[126:129], v[70:73], v[174:177], v[126:129]
	v_mfma_f32_16x16x32_bf16 v[122:125], v[78:81], v[174:177], v[122:125]
	v_mfma_f32_16x16x32_bf16 v[110:113], v[70:73], v[182:185], v[110:113]
	v_mfma_f32_16x16x32_bf16 v[106:109], v[78:81], v[182:185], v[106:109]
	v_mfma_f32_16x16x32_bf16 v[102:105], v[70:73], v[190:193], v[102:105]
	v_mfma_f32_16x16x32_bf16 v[98:101], v[78:81], v[190:193], v[98:101]
	v_mfma_f32_16x16x32_bf16 v[134:137], v[194:197], v[152:155], v[134:137]
	v_mfma_f32_16x16x32_bf16 v[130:133], v[202:205], v[152:155], v[130:133]
	v_mfma_f32_16x16x32_bf16 v[118:121], v[194:197], v[170:173], v[118:121]
	v_mfma_f32_16x16x32_bf16 v[114:117], v[202:205], v[170:173], v[114:117]
	v_mfma_f32_16x16x32_bf16 v[94:97], v[194:197], v[178:181], v[94:97]
	v_mfma_f32_16x16x32_bf16 v[90:93], v[202:205], v[178:181], v[90:93]
	v_mfma_f32_16x16x32_bf16 v[86:89], v[194:197], v[186:189], v[86:89]
	v_mfma_f32_16x16x32_bf16 v[82:85], v[202:205], v[186:189], v[82:85]
	v_mfma_f32_16x16x32_bf16 v[134:137], v[198:201], v[166:169], v[134:137]
	v_mfma_f32_16x16x32_bf16 v[130:133], v[210:213], v[166:169], v[130:133]
	v_mfma_f32_16x16x32_bf16 v[118:121], v[198:201], v[174:177], v[118:121]
	v_mfma_f32_16x16x32_bf16 v[114:117], v[210:213], v[174:177], v[114:117]
	v_mfma_f32_16x16x32_bf16 v[94:97], v[198:201], v[182:185], v[94:97]
	v_mfma_f32_16x16x32_bf16 v[90:93], v[210:213], v[182:185], v[90:93]
	v_mfma_f32_16x16x32_bf16 v[86:89], v[198:201], v[190:193], v[86:89]
	v_mfma_f32_16x16x32_bf16 v[82:85], v[210:213], v[190:193], v[82:85]
	s_setprio 1
	s_barrier
; #define PG8_STAGE(bufoff, gbase, voff) do { _Pragma("unroll") for (int _i = 0; _i < 2; ++_i) \
;         __builtin_amdgcn_global_load_lds((const unsigned*)((const char*)(gbase) + (voff)[_i]), (LAS unsigned*)(lds + (bufoff) + ldsw + _i * 8192), 16, 0, 0); } while (0)
; #define PG8_LDA(dst, b, h) do { _Pragma("unroll") for (int m = 0; m < 4; ++m) _Pragma("unroll") for (int k = 0; k < 2; ++k) dst[m][k] = *(const LAS bf16x8*)(lds + PG8_SA(b, h) + aoff + m * 2048 + k * 1024); } while (0)
; #define PG8_LDB(dst, b, h) do { _Pragma("unroll") for (int n = 0; n < 2; ++n) _Pragma("unroll") for (int k = 0; k < 2; ++k) dst[n][k] = *(const LAS bf16x8*)(lds + PG8_SB(b, h) + boff + n * 2048 + k * 1024); } while (0)
; #define PG8_MMA(ai, bj, At, Bt) do { __builtin_amdgcn_s_setprio(1); _Pragma("unroll") for (int m = 0; m < 4; ++m) _Pragma("unroll") for (int n = 0; n < 2; ++n) _Pragma("unroll") for (int k = 0; k < 2; ++k) \
;         acc[ai][bj][m][n] = __builtin_amdgcn_mfma_f32_16x16x32_bf16(Bt[n][k], At[m][k], acc[ai][bj][m][n], 0, 0, 0); __builtin_amdgcn_s_setprio(0); } while (0)
; #define PG8_WAIT_V(n) asm volatile("s_waitcnt vmcnt(" #n ")" ::: "memory")
; #define PG8_WAIT_L(n) asm volatile("s_waitcnt lgkmcnt(" #n ")" ::: "memory")
; #define PG8_BAR __builtin_amdgcn_s_barrier()
; #define PG8_SCHED __builtin_amdgcn_sched_barrier(0)
; template <class Epi, class Sched>
; __device__ __forceinline__ void gemm_phase(LAS unsigned char* lds, const Gemm g, const Sched& S, const Epi& E) {
;     ...
;             PG8_LDB(B1, 1, 1); PG8_STAGE(PG8_SB(1, 0), b3, voffB);
;             PG8_BAR; PG8_WAIT_L(0); PG8_MMA(0, 1, At, B1); PG8_BAR;
;             PG8_LDA(At, 1, 1); PG8_STAGE(PG8_SA(1, 0), a3, voffA);
;             PG8_BAR; PG8_WAIT_L(0); PG8_MMA(1, 0, At, B0); PG8_BAR; PG8_SCHED;
;             PG8_STAGE(PG8_SB(1, 1), b3 + hstep, voffB);
;             PG8_WAIT_V(6); PG8_BAR; PG8_MMA(1, 1, At, B1); PG8_BAR;
;         }
;         E(acc, cur, wr, wc, fr, fq);
;         if (!has_next) break;
	s_add_i32 s28, s38, s60
	v_lshl_add_u64 v[156:157], v[156:157], 0, s[36:37]
	s_mov_b32 m0, s28
	s_nop 0
	global_load_lds_dwordx4 v[156:157], off
	v_lshl_add_u64 v[156:157], v[160:161], 0, s[36:37]
	s_add_i32 m0, s28, 0x2000
	s_nop 0
	global_load_lds_dwordx4 v[156:157], off
	s_mov_b32 m0, s66
	v_lshl_add_u64 v[156:157], v[206:207], 0, s[36:37]
	global_load_lds_dwordx4 v[156:157], off
	v_lshl_add_u64 v[156:157], v[214:215], 0, s[36:37]
	s_mov_b32 m0, s67
	s_nop 0
	global_load_lds_dwordx4 v[156:157], off
	ds_read_b128 v[152:155], v165 offset:49152
	ds_read_b128 v[166:169], v165 offset:50176
	ds_read_b128 v[170:173], v165 offset:51200
	ds_read_b128 v[174:177], v165 offset:52224
	ds_read_b128 v[178:181], v165 offset:53248
	ds_read_b128 v[182:185], v165 offset:54272
	ds_read_b128 v[186:189], v165 offset:55296
	ds_read_b128 v[190:193], v165 offset:56320
	s_waitcnt vmcnt(4)
	s_waitcnt lgkmcnt(0)
	s_barrier
	s_setprio 0
	v_mfma_f32_16x16x32_bf16 v[62:65], v[66:69], v[152:155], v[62:65]
	v_mfma_f32_16x16x32_bf16 v[58:61], v[74:77], v[152:155], v[58:61]
	v_mfma_f32_16x16x32_bf16 v[46:49], v[66:69], v[170:173], v[46:49]
	v_mfma_f32_16x16x32_bf16 v[42:45], v[74:77], v[170:173], v[42:45]
	v_mfma_f32_16x16x32_bf16 v[30:33], v[66:69], v[178:181], v[30:33]
	v_mfma_f32_16x16x32_bf16 v[26:29], v[74:77], v[178:181], v[26:29]
	v_mfma_f32_16x16x32_bf16 v[22:25], v[66:69], v[186:189], v[22:25]
	v_mfma_f32_16x16x32_bf16 v[14:17], v[74:77], v[186:189], v[14:17]
	v_mfma_f32_16x16x32_bf16 v[62:65], v[70:73], v[166:169], v[62:65]
	v_mfma_f32_16x16x32_bf16 v[58:61], v[78:81], v[166:169], v[58:61]
	v_mfma_f32_16x16x32_bf16 v[46:49], v[70:73], v[174:177], v[46:49]
	v_mfma_f32_16x16x32_bf16 v[42:45], v[78:81], v[174:177], v[42:45]
	v_mfma_f32_16x16x32_bf16 v[30:33], v[70:73], v[182:185], v[30:33]
	v_mfma_f32_16x16x32_bf16 v[26:29], v[78:81], v[182:185], v[26:29]
	v_mfma_f32_16x16x32_bf16 v[22:25], v[70:73], v[190:193], v[22:25]
	v_mfma_f32_16x16x32_bf16 v[14:17], v[78:81], v[190:193], v[14:17]
	s_add_u32 s28, s52, 0x200080
	s_addc_u32 s29, s53, 0
	s_add_i32 s38, s39, s60
	v_lshl_add_u64 v[66:67], s[28:29], 0, v[0:1]
	s_mov_b32 m0, s38
	s_nop 0
	global_load_lds_dwordx4 v[66:67], off
	v_lshl_add_u64 v[66:67], s[28:29], 0, v[146:147]
	s_add_i32 m0, s38, 0x2000
	s_nop 0
	global_load_lds_dwordx4 v[66:67], off
	v_mfma_f32_16x16x32_bf16 v[54:57], v[194:197], v[152:155], v[54:57]
	v_mfma_f32_16x16x32_bf16 v[50:53], v[202:205], v[152:155], v[50:53]
	v_mfma_f32_16x16x32_bf16 v[38:41], v[194:197], v[170:173], v[38:41]
	v_mfma_f32_16x16x32_bf16 v[34:37], v[202:205], v[170:173], v[34:37]
	v_mfma_f32_16x16x32_bf16 v[18:21], v[194:197], v[178:181], v[18:21]
	v_mfma_f32_16x16x32_bf16 v[10:13], v[202:205], v[178:181], v[10:13]
	v_mfma_f32_16x16x32_bf16 v[6:9], v[194:197], v[186:189], v[6:9]
	v_mfma_f32_16x16x32_bf16 v[2:5], v[202:205], v[186:189], v[2:5]
	v_mfma_f32_16x16x32_bf16 v[54:57], v[198:201], v[166:169], v[54:57]
	v_mfma_f32_16x16x32_bf16 v[50:53], v[210:213], v[166:169], v[50:53]
	v_mfma_f32_16x16x32_bf16 v[38:41], v[198:201], v[174:177], v[38:41]
	v_mfma_f32_16x16x32_bf16 v[34:37], v[210:213], v[174:177], v[34:37]
	v_mfma_f32_16x16x32_bf16 v[18:21], v[198:201], v[182:185], v[18:21]
	v_mfma_f32_16x16x32_bf16 v[10:13], v[210:213], v[182:185], v[10:13]
	v_mfma_f32_16x16x32_bf16 v[6:9], v[198:201], v[190:193], v[6:9]
	v_mfma_f32_16x16x32_bf16 v[2:5], v[210:213], v[190:193], v[2:5]
	s_setprio 1
	s_add_i32 s75, s75, 2
	s_add_u32 s73, s73, 0x100
	s_addc_u32 s74, s74, 0
	s_cmpk_gt_u32 s75, 0x7d
	s_mov_b64 s[28:29], s[50:51]
	s_barrier
	s_cbranch_scc0 .LBB0_44
	s_cmp_lt_i32 s8, 64
	s_cselect_b64 s[50:51], -1, 0
	s_cmp_gt_i32 s8, 63
	s_cbranch_scc0 .LBB0_35
	s_mov_b64 s[52:53], 0x18000
	s_mov_b64 s[28:29], s[46:47]
	s_branch .LBB0_36

; #define PG8_STAGE(bufoff, gbase, voff) do { _Pragma("unroll") for (int _i = 0; _i < 2; ++_i) \
;         __builtin_amdgcn_global_load_lds((const unsigned*)((const char*)(gbase) + (voff)[_i]), (LAS unsigned*)(lds + (bufoff) + ldsw + _i * 8192), 16, 0, 0); } while (0)
; #define PG8_LDA(dst, b, h) do { _Pragma("unroll") for (int m = 0; m < 4; ++m) _Pragma("unroll") for (int k = 0; k < 2; ++k) dst[m][k] = *(const LAS bf16x8*)(lds + PG8_SA(b, h) + aoff + m * 2048 + k * 1024); } while (0)
; #define PG8_LDB(dst, b, h) do { _Pragma("unroll") for (int n = 0; n < 2; ++n) _Pragma("unroll") for (int k = 0; k < 2; ++k) dst[n][k] = *(const LAS bf16x8*)(lds + PG8_SB(b, h) + boff + n * 2048 + k * 1024); } while (0)
; #define PG8_MMA(ai, bj, At, Bt) do { __builtin_amdgcn_s_setprio(1); _Pragma("unroll") for (int m = 0; m < 4; ++m) _Pragma("unroll") for (int n = 0; n < 2; ++n) _Pragma("unroll") for (int k = 0; k < 2; ++k) \
;         acc[ai][bj][m][n] = __builtin_amdgcn_mfma_f32_16x16x32_bf16(Bt[n][k], At[m][k], acc[ai][bj][m][n], 0, 0, 0); __builtin_amdgcn_s_setprio(0); } while (0)
; #define PG8_WAIT_V(n) asm volatile("s_waitcnt vmcnt(" #n ")" ::: "memory")
; #define PG8_WAIT_L(n) asm volatile("s_waitcnt lgkmcnt(" #n ")" ::: "memory")
; template <class Epi, class Sched>
; __device__ __forceinline__ void gemm_phase(LAS unsigned char* lds, const Gemm g, const Sched& S, const Epi& E) {
;     ...
;         for (int t = 0; t < nt; t += 2) {
;             const bool last = (t == nt - 2);
;             const char* a1 = cA + (size_t)(t + 1) * kstep;
;             const char* a2 = last ? nA : cA + (size_t)(t + 2) * kstep; const char* b2 = last ? nB : cB + (size_t)(t + 2) * kstep;
;             const char* a3 = a2 + kstep; const char* b3 = b2 + kstep;
;             PG8_LDB(B0, 0, 0); PG8_SCHED; PG8_LDA(At, 0, 0); PG8_STAGE(PG8_SA(1, 1), a1 + hstep, voffA);
;             PG8_WAIT_L(8); PG8_BAR; PG8_WAIT_L(0); PG8_MMA(0, 0, At, B0); PG8_BAR; PG8_SCHED;
;             PG8_LDB(B1, 0, 1); PG8_STAGE(PG8_SB(0, 0), b2, voffB);
;             PG8_BAR; PG8_WAIT_L(0); PG8_MMA(0, 1, At, B1); PG8_BAR;
;             PG8_LDA(At, 0, 1); PG8_STAGE(PG8_SA(0, 0), a2, voffA);
;             PG8_BAR; PG8_WAIT_L(0); PG8_MMA(1, 0, At, B0); PG8_BAR; PG8_SCHED;
;             PG8_STAGE(PG8_SB(0, 1), b2 + hstep, voffB);
;             PG8_WAIT_V(6); PG8_BAR; PG8_MMA(1, 1, At, B1); PG8_BAR;
.LBB0_58:
	s_add_u32 s52, s50, 0x100
	s_addc_u32 s53, s51, 0
	s_cmp_eq_u32 s71, 28
	s_cselect_b32 s57, s11, s53
	s_cselect_b32 s56, s29, s52
	s_cselect_b32 s55, s41, s70
	s_cselect_b32 s54, s43, s69
	v_lshl_add_u64 v[156:157], s[50:51], 0, v[134:135]
	s_add_i32 m0, s25, 0xc000
	s_nop 0
	global_load_lds_dwordx4 v[156:157], off
	v_lshl_add_u64 v[156:157], s[50:51], 0, v[132:133]
	s_add_i32 m0, s25, 0xe000
	s_nop 0
	global_load_lds_dwordx4 v[156:157], off
	s_add_i32 s38, 0, 0x10000
	v_add_u32_e32 v152, s38, v137
	ds_read_b128 v[140:143], v152
	ds_read_b128 v[144:147], v152 offset:1024
	ds_read_b128 v[148:151], v152 offset:2048
	ds_read_b128 v[152:155], v152 offset:3072
	ds_read_b128 v[160:163], v139
	ds_read_b128 v[164:167], v139 offset:1024
	ds_read_b128 v[168:171], v139 offset:2048
	ds_read_b128 v[172:175], v139 offset:3072
	ds_read_b128 v[176:179], v139 offset:4096
	ds_read_b128 v[180:183], v139 offset:5120
	ds_read_b128 v[184:187], v139 offset:6144
	ds_read_b128 v[188:191], v139 offset:7168
	s_add_i32 s50, 0, 0x14000
	v_add_u32_e32 v156, s50, v137
	ds_read_b128 v[192:195], v156
	ds_read_b128 v[196:199], v156 offset:1024
	ds_read_b128 v[200:203], v156 offset:2048
	ds_read_b128 v[204:207], v156 offset:3072
	s_waitcnt lgkmcnt(4)
	s_barrier
	s_waitcnt lgkmcnt(0)
	s_setprio 0
	v_mfma_f32_16x16x32_bf16 v[126:129], v[140:143], v[160:163], v[126:129]
	v_mfma_f32_16x16x32_bf16 v[122:125], v[148:151], v[160:163], v[122:125]
	v_mfma_f32_16x16x32_bf16 v[118:121], v[140:143], v[168:171], v[118:121]
	v_mfma_f32_16x16x32_bf16 v[114:117], v[148:151], v[168:171], v[114:117]
	v_mfma_f32_16x16x32_bf16 v[106:109], v[140:143], v[176:179], v[106:109]
	v_mfma_f32_16x16x32_bf16 v[98:101], v[148:151], v[176:179], v[98:101]
	v_mfma_f32_16x16x32_bf16 v[90:93], v[140:143], v[184:187], v[90:93]
	v_mfma_f32_16x16x32_bf16 v[82:85], v[148:151], v[184:187], v[82:85]
	v_mfma_f32_16x16x32_bf16 v[126:129], v[144:147], v[164:167], v[126:129]
	v_mfma_f32_16x16x32_bf16 v[122:125], v[152:155], v[164:167], v[122:125]
	v_mfma_f32_16x16x32_bf16 v[118:121], v[144:147], v[172:175], v[118:121]
	v_mfma_f32_16x16x32_bf16 v[114:117], v[152:155], v[172:175], v[114:117]
	v_mfma_f32_16x16x32_bf16 v[106:109], v[144:147], v[180:183], v[106:109]
	v_mfma_f32_16x16x32_bf16 v[98:101], v[152:155], v[180:183], v[98:101]
	v_mfma_f32_16x16x32_bf16 v[90:93], v[144:147], v[188:191], v[90:93]
	v_mfma_f32_16x16x32_bf16 v[82:85], v[152:155], v[188:191], v[82:85]
	v_mfma_f32_16x16x32_bf16 v[110:113], v[192:195], v[160:163], v[110:113]
	v_mfma_f32_16x16x32_bf16 v[102:105], v[200:203], v[160:163], v[102:105]
	v_mfma_f32_16x16x32_bf16 v[94:97], v[192:195], v[168:171], v[94:97]
	v_mfma_f32_16x16x32_bf16 v[86:89], v[200:203], v[168:171], v[86:89]
	v_mfma_f32_16x16x32_bf16 v[78:81], v[192:195], v[176:179], v[78:81]
	v_mfma_f32_16x16x32_bf16 v[74:77], v[200:203], v[176:179], v[74:77]
	v_mfma_f32_16x16x32_bf16 v[70:73], v[192:195], v[184:187], v[70:73]
	v_mfma_f32_16x16x32_bf16 v[66:69], v[200:203], v[184:187], v[66:69]
	v_mfma_f32_16x16x32_bf16 v[110:113], v[196:199], v[164:167], v[110:113]
	v_mfma_f32_16x16x32_bf16 v[102:105], v[204:207], v[164:167], v[102:105]
	v_mfma_f32_16x16x32_bf16 v[94:97], v[196:199], v[172:175], v[94:97]
	v_mfma_f32_16x16x32_bf16 v[86:89], v[204:207], v[172:175], v[86:89]
	v_mfma_f32_16x16x32_bf16 v[78:81], v[196:199], v[180:183], v[78:81]
	v_mfma_f32_16x16x32_bf16 v[74:77], v[204:207], v[180:183], v[74:77]
	v_mfma_f32_16x16x32_bf16 v[70:73], v[196:199], v[188:191], v[70:73]
	v_mfma_f32_16x16x32_bf16 v[66:69], v[204:207], v[188:191], v[66:69]
	s_setprio 1
	s_barrier
	s_add_i32 s38, s38, s63
	v_lshl_add_u64 v[156:157], s[54:55], 0, v[0:1]
	s_mov_b32 m0, s38
	v_lshl_add_u64 v[210:211], s[54:55], 0, v[130:131]
	global_load_lds_dwordx4 v[156:157], off
	s_add_i32 m0, s38, 0x2000
	s_nop 0
	global_load_lds_dwordx4 v[210:211], off
	s_mov_b32 m0, s25
	v_lshl_add_u64 v[212:213], s[56:57], 0, v[0:1]
	global_load_lds_dwordx4 v[212:213], off
	v_lshl_add_u64 v[214:215], s[56:57], 0, v[130:131]
	s_mov_b32 m0, s27
	s_nop 0
	global_load_lds_dwordx4 v[214:215], off
	ds_read_b128 v[160:163], v139 offset:16384
	ds_read_b128 v[164:167], v139 offset:17408
	ds_read_b128 v[168:171], v139 offset:18432
	ds_read_b128 v[172:175], v139 offset:19456
	ds_read_b128 v[176:179], v139 offset:20480
	ds_read_b128 v[180:183], v139 offset:21504
	ds_read_b128 v[184:187], v139 offset:22528
	ds_read_b128 v[188:191], v139 offset:23552
	s_waitcnt vmcnt(4)
	s_waitcnt lgkmcnt(0)
	s_barrier
	s_setprio 0
	v_mfma_f32_16x16x32_bf16 v[62:65], v[140:143], v[160:163], v[62:65]
	v_mfma_f32_16x16x32_bf16 v[58:61], v[148:151], v[160:163], v[58:61]
	v_mfma_f32_16x16x32_bf16 v[54:57], v[140:143], v[168:171], v[54:57]
	v_mfma_f32_16x16x32_bf16 v[50:53], v[148:151], v[168:171], v[50:53]
	v_mfma_f32_16x16x32_bf16 v[38:41], v[140:143], v[176:179], v[38:41]
	v_mfma_f32_16x16x32_bf16 v[34:37], v[148:151], v[176:179], v[34:37]
	v_mfma_f32_16x16x32_bf16 v[22:25], v[140:143], v[184:187], v[22:25]
	v_mfma_f32_16x16x32_bf16 v[18:21], v[148:151], v[184:187], v[18:21]
	v_mfma_f32_16x16x32_bf16 v[62:65], v[144:147], v[164:167], v[62:65]
	v_mfma_f32_16x16x32_bf16 v[58:61], v[152:155], v[164:167], v[58:61]
	v_mfma_f32_16x16x32_bf16 v[54:57], v[144:147], v[172:175], v[54:57]
	v_mfma_f32_16x16x32_bf16 v[50:53], v[152:155], v[172:175], v[50:53]
	v_mfma_f32_16x16x32_bf16 v[38:41], v[144:147], v[180:183], v[38:41]
	v_mfma_f32_16x16x32_bf16 v[34:37], v[152:155], v[180:183], v[34:37]
	v_mfma_f32_16x16x32_bf16 v[22:25], v[144:147], v[188:191], v[22:25]
	v_mfma_f32_16x16x32_bf16 v[18:21], v[152:155], v[188:191], v[18:21]
	v_mfma_f32_16x16x32_bf16 v[46:49], v[192:195], v[160:163], v[46:49]
	v_mfma_f32_16x16x32_bf16 v[42:45], v[200:203], v[160:163], v[42:45]
	v_mfma_f32_16x16x32_bf16 v[30:33], v[192:195], v[168:171], v[30:33]
	v_mfma_f32_16x16x32_bf16 v[26:29], v[200:203], v[168:171], v[26:29]
	v_mfma_f32_16x16x32_bf16 v[14:17], v[192:195], v[176:179], v[14:17]
	v_mfma_f32_16x16x32_bf16 v[10:13], v[200:203], v[176:179], v[10:13]
	v_mfma_f32_16x16x32_bf16 v[6:9], v[192:195], v[184:187], v[6:9]
	v_mfma_f32_16x16x32_bf16 v[2:5], v[200:203], v[184:187], v[2:5]
	v_mfma_f32_16x16x32_bf16 v[46:49], v[196:199], v[164:167], v[46:49]
	v_mfma_f32_16x16x32_bf16 v[42:45], v[204:207], v[164:167], v[42:45]
	v_mfma_f32_16x16x32_bf16 v[30:33], v[196:199], v[172:175], v[30:33]
	v_mfma_f32_16x16x32_bf16 v[26:29], v[204:207], v[172:175], v[26:29]
	v_mfma_f32_16x16x32_bf16 v[14:17], v[196:199], v[180:183], v[14:17]
	v_mfma_f32_16x16x32_bf16 v[10:13], v[204:207], v[180:183], v[10:13]
	v_mfma_f32_16x16x32_bf16 v[6:9], v[196:199], v[188:191], v[6:9]
	v_mfma_f32_16x16x32_bf16 v[2:5], v[204:207], v[188:191], v[2:5]
	s_setprio 1
	s_barrier
; #define PG8_STAGE(bufoff, gbase, voff) do { _Pragma("unroll") for (int _i = 0; _i < 2; ++_i) \
;         __builtin_amdgcn_global_load_lds((const unsigned*)((const char*)(gbase) + (voff)[_i]), (LAS unsigned*)(lds + (bufoff) + ldsw + _i * 8192), 16, 0, 0); } while (0)
; #define PG8_LDA(dst, b, h) do { _Pragma("unroll") for (int m = 0; m < 4; ++m) _Pragma("unroll") for (int k = 0; k < 2; ++k) dst[m][k] = *(const LAS bf16x8*)(lds + PG8_SA(b, h) + aoff + m * 2048 + k * 1024); } while (0)
; #define PG8_LDB(dst, b, h) do { _Pragma("unroll") for (int n = 0; n < 2; ++n) _Pragma("unroll") for (int k = 0; k < 2; ++k) dst[n][k] = *(const LAS bf16x8*)(lds + PG8_SB(b, h) + boff + n * 2048 + k * 1024); } while (0)
; #define PG8_MMA(ai, bj, At, Bt) do { __builtin_amdgcn_s_setprio(1); _Pragma("unroll") for (int m = 0; m < 4; ++m) _Pragma("unroll") for (int n = 0; n < 2; ++n) _Pragma("unroll") for (int k = 0; k < 2; ++k) \
;         acc[ai][bj][m][n] = __builtin_amdgcn_mfma_f32_16x16x32_bf16(Bt[n][k], At[m][k], acc[ai][bj][m][n], 0, 0, 0); __builtin_amdgcn_s_setprio(0); } while (0)
; #define PG8_WAIT_V(n) asm volatile("s_waitcnt vmcnt(" #n ")" ::: "memory")
; #define PG8_WAIT_L(n) asm volatile("s_waitcnt lgkmcnt(" #n ")" ::: "memory")
; #define PG8_BAR __builtin_amdgcn_s_barrier()
; #define PG8_SCHED __builtin_amdgcn_sched_barrier(0)
; template <class Epi, class Sched>
; __device__ __forceinline__ void gemm_phase(LAS unsigned char* lds, const Gemm g, const Sched& S, const Epi& E) {
;     ...
;             PG8_STAGE(PG8_SB(0, 1), b2 + hstep, voffB);
;             PG8_WAIT_V(6); PG8_BAR; PG8_MMA(1, 1, At, B1); PG8_BAR;
;             PG8_LDB(B0, 1, 0); PG8_SCHED; PG8_LDA(At, 1, 0); PG8_STAGE(PG8_SA(0, 1), a2 + hstep, voffA);
;             PG8_WAIT_L(8); PG8_BAR; PG8_WAIT_L(0); PG8_MMA(0, 0, At, B0); PG8_BAR; PG8_SCHED;
;             PG8_LDB(B1, 1, 1); PG8_STAGE(PG8_SB(1, 0), b3, voffB);
;             PG8_BAR; PG8_WAIT_L(0); PG8_MMA(0, 1, At, B1); PG8_BAR;
;             PG8_LDA(At, 1, 1); PG8_STAGE(PG8_SA(1, 0), a3, voffA);
;             PG8_BAR; PG8_WAIT_L(0); PG8_MMA(1, 0, At, B0); PG8_BAR; PG8_SCHED;
	s_add_u32 s38, s54, 0x200000
	s_addc_u32 s39, s55, 0
	s_add_i32 s50, s50, s63
	v_lshl_add_u64 v[140:141], s[38:39], 0, v[0:1]
	s_mov_b32 m0, s50
	s_nop 0
	global_load_lds_dwordx4 v[140:141], off
	v_lshl_add_u64 v[140:141], s[38:39], 0, v[130:131]
	s_add_i32 m0, s50, 0x2000
	s_nop 0
	global_load_lds_dwordx4 v[140:141], off
	s_add_u32 s38, s56, 0x200000
	s_addc_u32 s39, s57, 0
	s_mov_b32 m0, s64
	v_lshl_add_u64 v[192:193], s[38:39], 0, v[0:1]
	global_load_lds_dwordx4 v[192:193], off
	v_lshl_add_u64 v[192:193], s[38:39], 0, v[130:131]
	s_mov_b32 m0, s65
	s_nop 0
	global_load_lds_dwordx4 v[192:193], off
	s_add_i32 s50, 0, 0x18000
	v_add_u32_e32 v152, s50, v137
	ds_read_b128 v[140:143], v152
	ds_read_b128 v[144:147], v152 offset:1024
	ds_read_b128 v[148:151], v152 offset:2048
	ds_read_b128 v[152:155], v152 offset:3072
	ds_read_b128 v[160:163], v139 offset:32768
	ds_read_b128 v[164:167], v139 offset:33792
	ds_read_b128 v[168:171], v139 offset:34816
	ds_read_b128 v[172:175], v139 offset:35840
	ds_read_b128 v[176:179], v139 offset:36864
	ds_read_b128 v[180:183], v139 offset:37888
	ds_read_b128 v[184:187], v139 offset:38912
	ds_read_b128 v[188:191], v139 offset:39936
	s_add_i32 s51, 0, 0x1c000
	v_add_u32_e32 v204, s51, v137
	ds_read_b128 v[192:195], v204
	ds_read_b128 v[196:199], v204 offset:1024
	ds_read_b128 v[200:203], v204 offset:2048
	ds_read_b128 v[204:207], v204 offset:3072
	s_waitcnt lgkmcnt(4)
	s_barrier
	s_waitcnt lgkmcnt(0)
	s_setprio 0
	v_mfma_f32_16x16x32_bf16 v[126:129], v[140:143], v[160:163], v[126:129]
	v_mfma_f32_16x16x32_bf16 v[122:125], v[148:151], v[160:163], v[122:125]
	v_mfma_f32_16x16x32_bf16 v[118:121], v[140:143], v[168:171], v[118:121]
	v_mfma_f32_16x16x32_bf16 v[114:117], v[148:151], v[168:171], v[114:117]
	v_mfma_f32_16x16x32_bf16 v[106:109], v[140:143], v[176:179], v[106:109]
	v_mfma_f32_16x16x32_bf16 v[98:101], v[148:151], v[176:179], v[98:101]
	v_mfma_f32_16x16x32_bf16 v[90:93], v[140:143], v[184:187], v[90:93]
	v_mfma_f32_16x16x32_bf16 v[82:85], v[148:151], v[184:187], v[82:85]
	v_mfma_f32_16x16x32_bf16 v[126:129], v[144:147], v[164:167], v[126:129]
	v_mfma_f32_16x16x32_bf16 v[122:125], v[152:155], v[164:167], v[122:125]
	v_mfma_f32_16x16x32_bf16 v[118:121], v[144:147], v[172:175], v[118:121]
	v_mfma_f32_16x16x32_bf16 v[114:117], v[152:155], v[172:175], v[114:117]
	v_mfma_f32_16x16x32_bf16 v[106:109], v[144:147], v[180:183], v[106:109]
	v_mfma_f32_16x16x32_bf16 v[98:101], v[152:155], v[180:183], v[98:101]
	v_mfma_f32_16x16x32_bf16 v[90:93], v[144:147], v[188:191], v[90:93]
	v_mfma_f32_16x16x32_bf16 v[82:85], v[152:155], v[188:191], v[82:85]
	v_mfma_f32_16x16x32_bf16 v[110:113], v[192:195], v[160:163], v[110:113]
	v_mfma_f32_16x16x32_bf16 v[102:105], v[200:203], v[160:163], v[102:105]
	v_mfma_f32_16x16x32_bf16 v[94:97], v[192:195], v[168:171], v[94:97]
	v_mfma_f32_16x16x32_bf16 v[86:89], v[200:203], v[168:171], v[86:89]
	v_mfma_f32_16x16x32_bf16 v[78:81], v[192:195], v[176:179], v[78:81]
	v_mfma_f32_16x16x32_bf16 v[74:77], v[200:203], v[176:179], v[74:77]
	v_mfma_f32_16x16x32_bf16 v[70:73], v[192:195], v[184:187], v[70:73]
	v_mfma_f32_16x16x32_bf16 v[66:69], v[200:203], v[184:187], v[66:69]
	v_mfma_f32_16x16x32_bf16 v[110:113], v[196:199], v[164:167], v[110:113]
	v_mfma_f32_16x16x32_bf16 v[102:105], v[204:207], v[164:167], v[102:105]
	v_mfma_f32_16x16x32_bf16 v[94:97], v[196:199], v[172:175], v[94:97]
	v_mfma_f32_16x16x32_bf16 v[86:89], v[204:207], v[172:175], v[86:89]
	v_mfma_f32_16x16x32_bf16 v[78:81], v[196:199], v[180:183], v[78:81]
	v_mfma_f32_16x16x32_bf16 v[74:77], v[204:207], v[180:183], v[74:77]
	v_mfma_f32_16x16x32_bf16 v[70:73], v[196:199], v[188:191], v[70:73]
	v_mfma_f32_16x16x32_bf16 v[66:69], v[204:207], v[188:191], v[66:69]
	s_setprio 1
	s_barrier
	s_add_i32 s38, s50, s63
	v_lshl_add_u64 v[156:157], v[156:157], 0, s[36:37]
	s_mov_b32 m0, s38
	s_nop 0
	global_load_lds_dwordx4 v[156:157], off
	v_lshl_add_u64 v[156:157], v[210:211], 0, s[36:37]
	s_add_i32 m0, s38, 0x2000
	s_nop 0
	global_load_lds_dwordx4 v[156:157], off
	s_mov_b32 m0, s66
	v_lshl_add_u64 v[156:157], v[212:213], 0, s[36:37]
	global_load_lds_dwordx4 v[156:157], off
	v_lshl_add_u64 v[156:157], v[214:215], 0, s[36:37]
	s_mov_b32 m0, s67
	s_nop 0
	global_load_lds_dwordx4 v[156:157], off
	ds_read_b128 v[160:163], v139 offset:49152
	ds_read_b128 v[164:167], v139 offset:50176
	ds_read_b128 v[168:171], v139 offset:51200
	ds_read_b128 v[172:175], v139 offset:52224
	ds_read_b128 v[176:179], v139 offset:53248
	ds_read_b128 v[180:183], v139 offset:54272
	ds_read_b128 v[184:187], v139 offset:55296
	ds_read_b128 v[188:191], v139 offset:56320
	s_waitcnt vmcnt(4)
	s_waitcnt lgkmcnt(0)
	s_barrier
; #define PG8_STAGE(bufoff, gbase, voff) do { _Pragma("unroll") for (int _i = 0; _i < 2; ++_i) \
;         __builtin_amdgcn_global_load_lds((const unsigned*)((const char*)(gbase) + (voff)[_i]), (LAS unsigned*)(lds + (bufoff) + ldsw + _i * 8192), 16, 0, 0); } while (0)
; #define PG8_LDA(dst, b, h) do { _Pragma("unroll") for (int m = 0; m < 4; ++m) _Pragma("unroll") for (int k = 0; k < 2; ++k) dst[m][k] = *(const LAS bf16x8*)(lds + PG8_SA(b, h) + aoff + m * 2048 + k * 1024); } while (0)
; #define PG8_WAIT_V(n) asm volatile("s_waitcnt vmcnt(" #n ")" ::: "memory")
; #define PG8_WAIT_L(n) asm volatile("s_waitcnt lgkmcnt(" #n ")" ::: "memory")
;     __device__ __forceinline__ void operator()(const f32x4 (&acc)[2][2][4][2], const Unit& u, int wr, int wc, int fr, int fq) const {
;         const int row0 = u.pm * BM + wr * 64 + fr, col0 = u.pn * BM + wc * 32 + 4 * fq;
;         float* base = part + (size_t)u.ks * Mp * ldc;
; #pragma unroll
;         for (int ai = 0; ai < 2; ++ai)
; #pragma unroll
;             for (int m = 0; m < 4; ++m) { float* rowp = base + (size_t)(row0 + ai * HALF + m * 16) * ldc + col0;
; #pragma unroll
;                 for (int bj = 0; bj < 2; ++bj)
; #pragma unroll
;                     for (int n = 0; n < 2; ++n) *(f32x4*)(rowp + bj * HALF + n * 16) = acc[ai][bj][m][n]; }
;     }
; template <class Epi, class Sched>
; __device__ __forceinline__ void gemm_phase(LAS unsigned char* lds, const Gemm g, const Sched& S, const Epi& E) {
;     ...
;             PG8_LDB(B1, 1, 1); PG8_STAGE(PG8_SB(1, 0), b3, voffB);
;             PG8_BAR; PG8_WAIT_L(0); PG8_MMA(0, 1, At, B1); PG8_BAR;
;             PG8_LDA(At, 1, 1); PG8_STAGE(PG8_SA(1, 0), a3, voffA);
;             PG8_BAR; PG8_WAIT_L(0); PG8_MMA(1, 0, At, B0); PG8_BAR; PG8_SCHED;
;             PG8_STAGE(PG8_SB(1, 1), b3 + hstep, voffB);
;             PG8_WAIT_V(6); PG8_BAR; PG8_MMA(1, 1, At, B1); PG8_BAR;
;         }
;         E(acc, cur, wr, wc, fr, fq);
;         if (!has_next) break;
; #pragma unroll
;         for (int a = 0; a < 2; ++a)
; #pragma unroll
;             for (int b = 0; b < 2; ++b)
; #pragma unroll
;                 for (int m = 0; m < 4; ++m)
; #pragma unroll
;                     for (int n = 0; n < 2; ++n) acc[a][b][m][n] = (f32x4){0.f, 0.f, 0.f, 0.f};
;         cur = nxt; cA = nA; cB = nB; ++ui;
;     }
;     PG8_WAIT_V(0);
;     if (wr == 0) PG8_BAR;
;     PG8_BAR;
	s_setprio 0
	v_mfma_f32_16x16x32_bf16 v[62:65], v[140:143], v[160:163], v[62:65]
	v_mfma_f32_16x16x32_bf16 v[58:61], v[148:151], v[160:163], v[58:61]
	v_mfma_f32_16x16x32_bf16 v[54:57], v[140:143], v[168:171], v[54:57]
	v_mfma_f32_16x16x32_bf16 v[50:53], v[148:151], v[168:171], v[50:53]
	v_mfma_f32_16x16x32_bf16 v[38:41], v[140:143], v[176:179], v[38:41]
	v_mfma_f32_16x16x32_bf16 v[34:37], v[148:151], v[176:179], v[34:37]
	v_mfma_f32_16x16x32_bf16 v[22:25], v[140:143], v[184:187], v[22:25]
	v_mfma_f32_16x16x32_bf16 v[18:21], v[148:151], v[184:187], v[18:21]
	v_mfma_f32_16x16x32_bf16 v[62:65], v[144:147], v[164:167], v[62:65]
	v_mfma_f32_16x16x32_bf16 v[58:61], v[152:155], v[164:167], v[58:61]
	v_mfma_f32_16x16x32_bf16 v[54:57], v[144:147], v[172:175], v[54:57]
	v_mfma_f32_16x16x32_bf16 v[50:53], v[152:155], v[172:175], v[50:53]
	v_mfma_f32_16x16x32_bf16 v[38:41], v[144:147], v[180:183], v[38:41]
	v_mfma_f32_16x16x32_bf16 v[34:37], v[152:155], v[180:183], v[34:37]
	v_mfma_f32_16x16x32_bf16 v[22:25], v[144:147], v[188:191], v[22:25]
	v_mfma_f32_16x16x32_bf16 v[18:21], v[152:155], v[188:191], v[18:21]
	s_add_u32 s38, s54, 0x200080
	s_addc_u32 s39, s55, 0
	s_add_i32 s50, s51, s63
	v_lshl_add_u64 v[140:141], s[38:39], 0, v[0:1]
	s_mov_b32 m0, s50
	s_nop 0
	global_load_lds_dwordx4 v[140:141], off
	v_lshl_add_u64 v[140:141], s[38:39], 0, v[130:131]
	s_add_i32 m0, s50, 0x2000
	s_nop 0
	global_load_lds_dwordx4 v[140:141], off
	v_mfma_f32_16x16x32_bf16 v[46:49], v[192:195], v[160:163], v[46:49]
	v_mfma_f32_16x16x32_bf16 v[42:45], v[200:203], v[160:163], v[42:45]
	v_mfma_f32_16x16x32_bf16 v[30:33], v[192:195], v[168:171], v[30:33]
	v_mfma_f32_16x16x32_bf16 v[26:29], v[200:203], v[168:171], v[26:29]
	v_mfma_f32_16x16x32_bf16 v[14:17], v[192:195], v[176:179], v[14:17]
	v_mfma_f32_16x16x32_bf16 v[10:13], v[200:203], v[176:179], v[10:13]
	v_mfma_f32_16x16x32_bf16 v[6:9], v[192:195], v[184:187], v[6:9]
	v_mfma_f32_16x16x32_bf16 v[2:5], v[200:203], v[184:187], v[2:5]
	v_mfma_f32_16x16x32_bf16 v[46:49], v[196:199], v[164:167], v[46:49]
	v_mfma_f32_16x16x32_bf16 v[42:45], v[204:207], v[164:167], v[42:45]
	v_mfma_f32_16x16x32_bf16 v[30:33], v[196:199], v[172:175], v[30:33]
	v_mfma_f32_16x16x32_bf16 v[26:29], v[204:207], v[172:175], v[26:29]
	v_mfma_f32_16x16x32_bf16 v[14:17], v[196:199], v[180:183], v[14:17]
	v_mfma_f32_16x16x32_bf16 v[10:13], v[204:207], v[180:183], v[10:13]
	v_mfma_f32_16x16x32_bf16 v[6:9], v[196:199], v[188:191], v[6:9]
	v_mfma_f32_16x16x32_bf16 v[2:5], v[204:207], v[188:191], v[2:5]
	s_setprio 1
	s_add_i32 s71, s71, 2
	s_add_u32 s69, s69, 0x100
	s_addc_u32 s70, s70, 0
	s_cmp_gt_u32 s71, 29
	s_mov_b64 s[50:51], s[52:53]
	s_barrier
	s_cbranch_scc0 .LBB0_58
	s_ashr_i32 s11, s10, 31
	s_lshl_b64 s[10:11], s[10:11], 24
	v_lshl_or_b32 v140, s26, 8, v138
	s_add_u32 s10, s8, s10
	v_lshl_add_u32 v142, s24, 8, v136
	s_addc_u32 s11, s9, s11
	v_ashrrev_i32_e32 v141, 31, v140
	v_ashrrev_i32_e32 v143, 31, v142
	v_lshl_add_u64 v[140:141], v[140:141], 2, s[10:11]
	v_lshlrev_b64 v[144:145], 13, v[142:143]
	v_lshl_add_u64 v[144:145], v[140:141], 0, v[144:145]
	global_store_dwordx4 v[144:145], v[126:129], off
	global_store_dwordx4 v[144:145], v[122:125], off offset:64
	global_store_dwordx4 v[144:145], v[110:113], off offset:512
	global_store_dwordx4 v[144:145], v[102:105], off offset:576
	s_mov_b64 s[10:11], 0x100000
	s_mov_b32 s26, s40
	v_or_b32_e32 v102, 16, v142
	v_ashrrev_i32_e32 v103, 31, v102
	v_lshlrev_b64 v[102:103], 13, v[102:103]
	v_lshl_add_u64 v[102:103], v[140:141], 0, v[102:103]
	global_store_dwordx4 v[102:103], v[118:121], off
	global_store_dwordx4 v[102:103], v[114:117], off offset:64
	global_store_dwordx4 v[102:103], v[94:97], off offset:512
	global_store_dwordx4 v[102:103], v[86:89], off offset:576
	s_mov_b32 s24, s42
	s_mov_b64 s[52:53], s[48:49]
	v_or_b32_e32 v86, 32, v142
	v_ashrrev_i32_e32 v87, 31, v86
	v_lshlrev_b64 v[86:87], 13, v[86:87]
	v_lshl_add_u64 v[86:87], v[140:141], 0, v[86:87]
	global_store_dwordx4 v[86:87], v[106:109], off
	global_store_dwordx4 v[86:87], v[98:101], off offset:64
	global_store_dwordx4 v[86:87], v[78:81], off offset:512
	global_store_dwordx4 v[86:87], v[74:77], off offset:576
	s_mov_b64 s[50:51], s[46:47]
	s_nop 0
	v_or_b32_e32 v74, 48, v142
	v_ashrrev_i32_e32 v75, 31, v74
	v_lshlrev_b64 v[74:75], 13, v[74:75]
	v_lshl_add_u64 v[74:75], v[140:141], 0, v[74:75]
	global_store_dwordx4 v[74:75], v[90:93], off
	global_store_dwordx4 v[74:75], v[82:85], off offset:64
	global_store_dwordx4 v[74:75], v[70:73], off offset:512
	global_store_dwordx4 v[74:75], v[66:69], off offset:576
	s_nop 1
	v_add_co_u32_e32 v68, vcc, s93, v144
	v_lshl_add_u64 v[66:67], v[144:145], 0, s[10:11]
	s_nop 0
	v_addc_co_u32_e32 v69, vcc, 0, v145, vcc
	s_mov_b64 s[10:11], 0x120000
	global_store_dwordx4 v[68:69], v[62:65], off
	global_store_dwordx4 v[66:67], v[58:61], off offset:64
	global_store_dwordx4 v[66:67], v[46:49], off offset:512
	global_store_dwordx4 v[66:67], v[42:45], off offset:576
	s_nop 1
	v_lshl_add_u64 v[42:43], v[144:145], 0, s[10:11]
	s_mov_b32 s10, 0x120000
	v_add_co_u32_e32 v44, vcc, s10, v144
	s_mov_b64 s[10:11], 0x140000
	s_nop 0
	v_addc_co_u32_e32 v45, vcc, 0, v145, vcc
	global_store_dwordx4 v[44:45], v[54:57], off
	global_store_dwordx4 v[42:43], v[50:53], off offset:64
	global_store_dwordx4 v[42:43], v[30:33], off offset:512
	global_store_dwordx4 v[42:43], v[26:29], off offset:576
	s_nop 1
	v_lshl_add_u64 v[26:27], v[144:145], 0, s[10:11]
	s_mov_b32 s10, 0x140000
	v_add_co_u32_e32 v28, vcc, s10, v144
	s_mov_b64 s[10:11], 0x160000
	s_nop 0
	v_addc_co_u32_e32 v29, vcc, 0, v145, vcc
	global_store_dwordx4 v[28:29], v[38:41], off
	global_store_dwordx4 v[26:27], v[34:37], off offset:64
	global_store_dwordx4 v[26:27], v[14:17], off offset:512
	global_store_dwordx4 v[26:27], v[10:13], off offset:576
	s_nop 1
	v_add_co_u32_e32 v12, vcc, 0x160000, v144
	v_lshl_add_u64 v[10:11], v[144:145], 0, s[10:11]
	s_nop 0
	v_addc_co_u32_e32 v13, vcc, 0, v145, vcc
	s_and_b64 vcc, exec, s[44:45]
	s_mov_b32 s10, s28
	global_store_dwordx4 v[12:13], v[22:25], off
	global_store_dwordx4 v[10:11], v[18:21], off offset:64
	global_store_dwordx4 v[10:11], v[6:9], off offset:512
	global_store_dwordx4 v[10:11], v[2:5], off offset:576
	s_cbranch_vccz .LBB0_55
	s_waitcnt vmcnt(0)
	s_cmpk_gt_u32 s60, 0xff
	s_cbranch_scc1 .LBB0_62
	s_barrier

; #define PG8_STAGE(bufoff, gbase, voff) do { _Pragma("unroll") for (int _i = 0; _i < 2; ++_i) \
;         __builtin_amdgcn_global_load_lds((const unsigned*)((const char*)(gbase) + (voff)[_i]), (LAS unsigned*)(lds + (bufoff) + ldsw + _i * 8192), 16, 0, 0); } while (0)
; #define PG8_LDA(dst, b, h) do { _Pragma("unroll") for (int m = 0; m < 4; ++m) _Pragma("unroll") for (int k = 0; k < 2; ++k) dst[m][k] = *(const LAS bf16x8*)(lds + PG8_SA(b, h) + aoff + m * 2048 + k * 1024); } while (0)
; #define PG8_LDB(dst, b, h) do { _Pragma("unroll") for (int n = 0; n < 2; ++n) _Pragma("unroll") for (int k = 0; k < 2; ++k) dst[n][k] = *(const LAS bf16x8*)(lds + PG8_SB(b, h) + boff + n * 2048 + k * 1024); } while (0)
; #define PG8_MMA(ai, bj, At, Bt) do { __builtin_amdgcn_s_setprio(1); _Pragma("unroll") for (int m = 0; m < 4; ++m) _Pragma("unroll") for (int n = 0; n < 2; ++n) _Pragma("unroll") for (int k = 0; k < 2; ++k) \
;         acc[ai][bj][m][n] = __builtin_amdgcn_mfma_f32_16x16x32_bf16(Bt[n][k], At[m][k], acc[ai][bj][m][n], 0, 0, 0); __builtin_amdgcn_s_setprio(0); } while (0)
; #define PG8_WAIT_V(n) asm volatile("s_waitcnt vmcnt(" #n ")" ::: "memory")
; #define PG8_WAIT_L(n) asm volatile("s_waitcnt lgkmcnt(" #n ")" ::: "memory")
; template <class Epi, class Sched>
; __device__ __forceinline__ void gemm_phase(LAS unsigned char* lds, const Gemm g, const Sched& S, const Epi& E) {
;     ...
;         for (int t = 0; t < nt; t += 2) {
;             const bool last = (t == nt - 2);
;             const char* a1 = cA + (size_t)(t + 1) * kstep;
;             const char* a2 = last ? nA : cA + (size_t)(t + 2) * kstep; const char* b2 = last ? nB : cB + (size_t)(t + 2) * kstep;
;             const char* a3 = a2 + kstep; const char* b3 = b2 + kstep;
;             PG8_LDB(B0, 0, 0); PG8_SCHED; PG8_LDA(At, 0, 0); PG8_STAGE(PG8_SA(1, 1), a1 + hstep, voffA);
;             PG8_WAIT_L(8); PG8_BAR; PG8_WAIT_L(0); PG8_MMA(0, 0, At, B0); PG8_BAR; PG8_SCHED;
;             PG8_LDB(B1, 0, 1); PG8_STAGE(PG8_SB(0, 0), b2, voffB);
;             PG8_BAR; PG8_WAIT_L(0); PG8_MMA(0, 1, At, B1); PG8_BAR;
;             PG8_LDA(At, 0, 1); PG8_STAGE(PG8_SA(0, 0), a2, voffA);
;             PG8_BAR; PG8_WAIT_L(0); PG8_MMA(1, 0, At, B0); PG8_BAR; PG8_SCHED;
;             PG8_STAGE(PG8_SB(0, 1), b2 + hstep, voffB);
;             PG8_WAIT_V(6); PG8_BAR; PG8_MMA(1, 1, At, B1); PG8_BAR;
.LBB0_73:
	s_add_u32 s38, s46, 0xfff80080
	s_addc_u32 s39, s47, -1
	s_cmp_eq_u32 s73, 28
	s_cselect_b32 s51, s29, s39
	s_cselect_b32 s50, s69, s38
	s_cselect_b32 s49, s27, s72
	s_cselect_b32 s48, s70, s71
	v_lshl_add_u64 v[140:141], s[46:47], 0, v[138:139]
	s_add_i32 m0, s9, 0xc000
	s_nop 0
	global_load_lds_dwordx4 v[140:141], off
	v_lshl_add_u64 v[140:141], s[46:47], 0, v[136:137]
	s_add_i32 m0, s9, 0xe000
	s_nop 0
	global_load_lds_dwordx4 v[140:141], off
	s_add_i32 s74, 0, 0x10000
	v_add_u32_e32 v140, s74, v143
	ds_read_b128 v[146:149], v140
	ds_read_b128 v[150:153], v140 offset:1024
	ds_read_b128 v[154:157], v140 offset:2048
	ds_read_b128 v[160:163], v140 offset:3072
	ds_read_b128 v[164:167], v145
	ds_read_b128 v[168:171], v145 offset:1024
	ds_read_b128 v[172:175], v145 offset:2048
	ds_read_b128 v[176:179], v145 offset:3072
	ds_read_b128 v[180:183], v145 offset:4096
	ds_read_b128 v[184:187], v145 offset:5120
	ds_read_b128 v[188:191], v145 offset:6144
	ds_read_b128 v[192:195], v145 offset:7168
	s_add_i32 s75, 0, 0x14000
	v_add_u32_e32 v140, s75, v143
	ds_read_b128 v[196:199], v140
	ds_read_b128 v[200:203], v140 offset:1024
	ds_read_b128 v[204:207], v140 offset:2048
	ds_read_b128 v[210:213], v140 offset:3072
	s_waitcnt lgkmcnt(4)
	s_barrier
	s_waitcnt lgkmcnt(0)
	s_setprio 0
	v_mfma_f32_16x16x32_bf16 v[126:129], v[146:149], v[164:167], v[126:129]
	v_mfma_f32_16x16x32_bf16 v[122:125], v[154:157], v[164:167], v[122:125]
	v_mfma_f32_16x16x32_bf16 v[110:113], v[146:149], v[172:175], v[110:113]
	v_mfma_f32_16x16x32_bf16 v[106:109], v[154:157], v[172:175], v[106:109]
	v_mfma_f32_16x16x32_bf16 v[94:97], v[146:149], v[180:183], v[94:97]
	v_mfma_f32_16x16x32_bf16 v[90:93], v[154:157], v[180:183], v[90:93]
	v_mfma_f32_16x16x32_bf16 v[78:81], v[146:149], v[188:191], v[78:81]
	v_mfma_f32_16x16x32_bf16 v[74:77], v[154:157], v[188:191], v[74:77]
	v_mfma_f32_16x16x32_bf16 v[126:129], v[150:153], v[168:171], v[126:129]
	v_mfma_f32_16x16x32_bf16 v[122:125], v[160:163], v[168:171], v[122:125]
	v_mfma_f32_16x16x32_bf16 v[110:113], v[150:153], v[176:179], v[110:113]
	v_mfma_f32_16x16x32_bf16 v[106:109], v[160:163], v[176:179], v[106:109]
	v_mfma_f32_16x16x32_bf16 v[94:97], v[150:153], v[184:187], v[94:97]
	v_mfma_f32_16x16x32_bf16 v[90:93], v[160:163], v[184:187], v[90:93]
	v_mfma_f32_16x16x32_bf16 v[78:81], v[150:153], v[192:195], v[78:81]
	v_mfma_f32_16x16x32_bf16 v[74:77], v[160:163], v[192:195], v[74:77]
	v_mfma_f32_16x16x32_bf16 v[118:121], v[196:199], v[164:167], v[118:121]
	v_mfma_f32_16x16x32_bf16 v[114:117], v[204:207], v[164:167], v[114:117]
	v_mfma_f32_16x16x32_bf16 v[102:105], v[196:199], v[172:175], v[102:105]
	v_mfma_f32_16x16x32_bf16 v[98:101], v[204:207], v[172:175], v[98:101]
	v_mfma_f32_16x16x32_bf16 v[86:89], v[196:199], v[180:183], v[86:89]
	v_mfma_f32_16x16x32_bf16 v[82:85], v[204:207], v[180:183], v[82:85]
	v_mfma_f32_16x16x32_bf16 v[70:73], v[196:199], v[188:191], v[70:73]
	v_mfma_f32_16x16x32_bf16 v[66:69], v[204:207], v[188:191], v[66:69]
	v_mfma_f32_16x16x32_bf16 v[118:121], v[200:203], v[168:171], v[118:121]
	v_mfma_f32_16x16x32_bf16 v[114:117], v[210:213], v[168:171], v[114:117]
	v_mfma_f32_16x16x32_bf16 v[102:105], v[200:203], v[176:179], v[102:105]
	v_mfma_f32_16x16x32_bf16 v[98:101], v[210:213], v[176:179], v[98:101]
	v_mfma_f32_16x16x32_bf16 v[86:89], v[200:203], v[184:187], v[86:89]
	v_mfma_f32_16x16x32_bf16 v[82:85], v[210:213], v[184:187], v[82:85]
	v_mfma_f32_16x16x32_bf16 v[70:73], v[200:203], v[192:195], v[70:73]
	v_mfma_f32_16x16x32_bf16 v[66:69], v[210:213], v[192:195], v[66:69]
	s_setprio 1
	s_barrier
	s_add_i32 s38, s74, s56
	v_lshl_add_u64 v[140:141], s[48:49], 0, v[0:1]
	s_mov_b32 m0, s38
	v_lshl_add_u64 v[214:215], s[48:49], 0, v[130:131]
	global_load_lds_dwordx4 v[140:141], off
	s_add_i32 m0, s38, 0x2000
	s_nop 0
	global_load_lds_dwordx4 v[214:215], off
	s_mov_b32 m0, s9
	v_lshl_add_u64 v[216:217], s[50:51], 0, v[134:135]
	global_load_lds_dwordx4 v[216:217], off
	v_lshl_add_u64 v[224:225], s[50:51], 0, v[132:133]
	s_mov_b32 m0, s60
	s_nop 0
	global_load_lds_dwordx4 v[224:225], off
	ds_read_b128 v[164:167], v145 offset:16384
	ds_read_b128 v[168:171], v145 offset:17408
	ds_read_b128 v[172:175], v145 offset:18432
	ds_read_b128 v[176:179], v145 offset:19456
	ds_read_b128 v[180:183], v145 offset:20480
	ds_read_b128 v[184:187], v145 offset:21504
	ds_read_b128 v[188:191], v145 offset:22528
	ds_read_b128 v[192:195], v145 offset:23552
	s_waitcnt vmcnt(4)
	s_waitcnt lgkmcnt(0)
	s_barrier
	s_setprio 0
	v_mfma_f32_16x16x32_bf16 v[62:65], v[146:149], v[164:167], v[62:65]
	v_mfma_f32_16x16x32_bf16 v[58:61], v[154:157], v[164:167], v[58:61]
	v_mfma_f32_16x16x32_bf16 v[46:49], v[146:149], v[172:175], v[46:49]
	v_mfma_f32_16x16x32_bf16 v[42:45], v[154:157], v[172:175], v[42:45]
	v_mfma_f32_16x16x32_bf16 v[30:33], v[146:149], v[180:183], v[30:33]
	v_mfma_f32_16x16x32_bf16 v[26:29], v[154:157], v[180:183], v[26:29]
	v_mfma_f32_16x16x32_bf16 v[14:17], v[146:149], v[188:191], v[14:17]
	v_mfma_f32_16x16x32_bf16 v[10:13], v[154:157], v[188:191], v[10:13]
	v_mfma_f32_16x16x32_bf16 v[62:65], v[150:153], v[168:171], v[62:65]
	v_mfma_f32_16x16x32_bf16 v[58:61], v[160:163], v[168:171], v[58:61]
	v_mfma_f32_16x16x32_bf16 v[46:49], v[150:153], v[176:179], v[46:49]
	v_mfma_f32_16x16x32_bf16 v[42:45], v[160:163], v[176:179], v[42:45]
	v_mfma_f32_16x16x32_bf16 v[30:33], v[150:153], v[184:187], v[30:33]
	v_mfma_f32_16x16x32_bf16 v[26:29], v[160:163], v[184:187], v[26:29]
	v_mfma_f32_16x16x32_bf16 v[14:17], v[150:153], v[192:195], v[14:17]
	v_mfma_f32_16x16x32_bf16 v[10:13], v[160:163], v[192:195], v[10:13]
	v_mfma_f32_16x16x32_bf16 v[54:57], v[196:199], v[164:167], v[54:57]
	v_mfma_f32_16x16x32_bf16 v[50:53], v[204:207], v[164:167], v[50:53]
	v_mfma_f32_16x16x32_bf16 v[38:41], v[196:199], v[172:175], v[38:41]
	v_mfma_f32_16x16x32_bf16 v[34:37], v[204:207], v[172:175], v[34:37]
	v_mfma_f32_16x16x32_bf16 v[22:25], v[196:199], v[180:183], v[22:25]
	v_mfma_f32_16x16x32_bf16 v[18:21], v[204:207], v[180:183], v[18:21]
	v_mfma_f32_16x16x32_bf16 v[6:9], v[196:199], v[188:191], v[6:9]
	v_mfma_f32_16x16x32_bf16 v[2:5], v[204:207], v[188:191], v[2:5]
	v_mfma_f32_16x16x32_bf16 v[54:57], v[200:203], v[168:171], v[54:57]
	v_mfma_f32_16x16x32_bf16 v[50:53], v[210:213], v[168:171], v[50:53]
	v_mfma_f32_16x16x32_bf16 v[38:41], v[200:203], v[176:179], v[38:41]
	v_mfma_f32_16x16x32_bf16 v[34:37], v[210:213], v[176:179], v[34:37]
	v_mfma_f32_16x16x32_bf16 v[22:25], v[200:203], v[184:187], v[22:25]
	v_mfma_f32_16x16x32_bf16 v[18:21], v[210:213], v[184:187], v[18:21]
	v_mfma_f32_16x16x32_bf16 v[6:9], v[200:203], v[192:195], v[6:9]
	v_mfma_f32_16x16x32_bf16 v[2:5], v[210:213], v[192:195], v[2:5]
	s_setprio 1
	s_barrier
; #define PG8_STAGE(bufoff, gbase, voff) do { _Pragma("unroll") for (int _i = 0; _i < 2; ++_i) \
;         __builtin_amdgcn_global_load_lds((const unsigned*)((const char*)(gbase) + (voff)[_i]), (LAS unsigned*)(lds + (bufoff) + ldsw + _i * 8192), 16, 0, 0); } while (0)
; #define PG8_LDA(dst, b, h) do { _Pragma("unroll") for (int m = 0; m < 4; ++m) _Pragma("unroll") for (int k = 0; k < 2; ++k) dst[m][k] = *(const LAS bf16x8*)(lds + PG8_SA(b, h) + aoff + m * 2048 + k * 1024); } while (0)
; #define PG8_LDB(dst, b, h) do { _Pragma("unroll") for (int n = 0; n < 2; ++n) _Pragma("unroll") for (int k = 0; k < 2; ++k) dst[n][k] = *(const LAS bf16x8*)(lds + PG8_SB(b, h) + boff + n * 2048 + k * 1024); } while (0)
; #define PG8_MMA(ai, bj, At, Bt) do { __builtin_amdgcn_s_setprio(1); _Pragma("unroll") for (int m = 0; m < 4; ++m) _Pragma("unroll") for (int n = 0; n < 2; ++n) _Pragma("unroll") for (int k = 0; k < 2; ++k) \
;         acc[ai][bj][m][n] = __builtin_amdgcn_mfma_f32_16x16x32_bf16(Bt[n][k], At[m][k], acc[ai][bj][m][n], 0, 0, 0); __builtin_amdgcn_s_setprio(0); } while (0)
; #define PG8_WAIT_V(n) asm volatile("s_waitcnt vmcnt(" #n ")" ::: "memory")
; #define PG8_WAIT_L(n) asm volatile("s_waitcnt lgkmcnt(" #n ")" ::: "memory")
; #define PG8_BAR __builtin_amdgcn_s_barrier()
; #define PG8_SCHED __builtin_amdgcn_sched_barrier(0)
; template <class Epi, class Sched>
; __device__ __forceinline__ void gemm_phase(LAS unsigned char* lds, const Gemm g, const Sched& S, const Epi& E) {
;     ...
;             PG8_STAGE(PG8_SB(0, 1), b2 + hstep, voffB);
;             PG8_WAIT_V(6); PG8_BAR; PG8_MMA(1, 1, At, B1); PG8_BAR;
;             PG8_LDB(B0, 1, 0); PG8_SCHED; PG8_LDA(At, 1, 0); PG8_STAGE(PG8_SA(0, 1), a2 + hstep, voffA);
;             PG8_WAIT_L(8); PG8_BAR; PG8_WAIT_L(0); PG8_MMA(0, 0, At, B0); PG8_BAR; PG8_SCHED;
;             PG8_LDB(B1, 1, 1); PG8_STAGE(PG8_SB(1, 0), b3, voffB);
;             PG8_BAR; PG8_WAIT_L(0); PG8_MMA(0, 1, At, B1); PG8_BAR;
;             PG8_LDA(At, 1, 1); PG8_STAGE(PG8_SA(1, 0), a3, voffA);
;             PG8_BAR; PG8_WAIT_L(0); PG8_MMA(1, 0, At, B0); PG8_BAR; PG8_SCHED;
	s_add_u32 s38, s48, 0x80000
	s_addc_u32 s39, s49, 0
	s_add_i32 s74, s75, s56
	v_lshl_add_u64 v[146:147], s[38:39], 0, v[0:1]
	s_mov_b32 m0, s74
	s_nop 0
	global_load_lds_dwordx4 v[146:147], off
	v_lshl_add_u64 v[146:147], s[38:39], 0, v[130:131]
	s_add_i32 m0, s74, 0x2000
	s_nop 0
	global_load_lds_dwordx4 v[146:147], off
	s_add_u32 s38, s50, 0x80000
	s_addc_u32 s39, s51, 0
	s_mov_b32 m0, s61
	v_lshl_add_u64 v[196:197], s[38:39], 0, v[134:135]
	global_load_lds_dwordx4 v[196:197], off
	v_lshl_add_u64 v[196:197], s[38:39], 0, v[132:133]
	s_mov_b32 m0, s62
	s_nop 0
	global_load_lds_dwordx4 v[196:197], off
	s_add_i32 s74, 0, 0x18000
	v_add_u32_e32 v160, s74, v143
	ds_read_b128 v[146:149], v160
	ds_read_b128 v[150:153], v160 offset:1024
	ds_read_b128 v[154:157], v160 offset:2048
	ds_read_b128 v[160:163], v160 offset:3072
	ds_read_b128 v[164:167], v145 offset:32768
	ds_read_b128 v[168:171], v145 offset:33792
	ds_read_b128 v[172:175], v145 offset:34816
	ds_read_b128 v[176:179], v145 offset:35840
	ds_read_b128 v[180:183], v145 offset:36864
	ds_read_b128 v[184:187], v145 offset:37888
	ds_read_b128 v[188:191], v145 offset:38912
	ds_read_b128 v[192:195], v145 offset:39936
	s_add_i32 s50, 0, 0x1c000
	v_add_u32_e32 v210, s50, v143
	ds_read_b128 v[196:199], v210
	ds_read_b128 v[200:203], v210 offset:1024
	ds_read_b128 v[204:207], v210 offset:2048
	ds_read_b128 v[210:213], v210 offset:3072
	s_waitcnt lgkmcnt(4)
	s_barrier
	s_waitcnt lgkmcnt(0)
	s_setprio 0
	v_mfma_f32_16x16x32_bf16 v[126:129], v[146:149], v[164:167], v[126:129]
	v_mfma_f32_16x16x32_bf16 v[122:125], v[154:157], v[164:167], v[122:125]
	v_mfma_f32_16x16x32_bf16 v[110:113], v[146:149], v[172:175], v[110:113]
	v_mfma_f32_16x16x32_bf16 v[106:109], v[154:157], v[172:175], v[106:109]
	v_mfma_f32_16x16x32_bf16 v[94:97], v[146:149], v[180:183], v[94:97]
	v_mfma_f32_16x16x32_bf16 v[90:93], v[154:157], v[180:183], v[90:93]
	v_mfma_f32_16x16x32_bf16 v[78:81], v[146:149], v[188:191], v[78:81]
	v_mfma_f32_16x16x32_bf16 v[74:77], v[154:157], v[188:191], v[74:77]
	v_mfma_f32_16x16x32_bf16 v[126:129], v[150:153], v[168:171], v[126:129]
	v_mfma_f32_16x16x32_bf16 v[122:125], v[160:163], v[168:171], v[122:125]
	v_mfma_f32_16x16x32_bf16 v[110:113], v[150:153], v[176:179], v[110:113]
	v_mfma_f32_16x16x32_bf16 v[106:109], v[160:163], v[176:179], v[106:109]
	v_mfma_f32_16x16x32_bf16 v[94:97], v[150:153], v[184:187], v[94:97]
	v_mfma_f32_16x16x32_bf16 v[90:93], v[160:163], v[184:187], v[90:93]
	v_mfma_f32_16x16x32_bf16 v[78:81], v[150:153], v[192:195], v[78:81]
	v_mfma_f32_16x16x32_bf16 v[74:77], v[160:163], v[192:195], v[74:77]
	v_mfma_f32_16x16x32_bf16 v[118:121], v[196:199], v[164:167], v[118:121]
	v_mfma_f32_16x16x32_bf16 v[114:117], v[204:207], v[164:167], v[114:117]
	v_mfma_f32_16x16x32_bf16 v[102:105], v[196:199], v[172:175], v[102:105]
	v_mfma_f32_16x16x32_bf16 v[98:101], v[204:207], v[172:175], v[98:101]
	v_mfma_f32_16x16x32_bf16 v[86:89], v[196:199], v[180:183], v[86:89]
	v_mfma_f32_16x16x32_bf16 v[82:85], v[204:207], v[180:183], v[82:85]
	v_mfma_f32_16x16x32_bf16 v[70:73], v[196:199], v[188:191], v[70:73]
	v_mfma_f32_16x16x32_bf16 v[66:69], v[204:207], v[188:191], v[66:69]
	v_mfma_f32_16x16x32_bf16 v[118:121], v[200:203], v[168:171], v[118:121]
	v_mfma_f32_16x16x32_bf16 v[114:117], v[210:213], v[168:171], v[114:117]
	v_mfma_f32_16x16x32_bf16 v[102:105], v[200:203], v[176:179], v[102:105]
	v_mfma_f32_16x16x32_bf16 v[98:101], v[210:213], v[176:179], v[98:101]
	v_mfma_f32_16x16x32_bf16 v[86:89], v[200:203], v[184:187], v[86:89]
	v_mfma_f32_16x16x32_bf16 v[82:85], v[210:213], v[184:187], v[82:85]
	v_mfma_f32_16x16x32_bf16 v[70:73], v[200:203], v[192:195], v[70:73]
	v_mfma_f32_16x16x32_bf16 v[66:69], v[210:213], v[192:195], v[66:69]
	s_setprio 1
	s_barrier
	s_add_i32 s38, s74, s56
	v_lshl_add_u64 v[140:141], v[140:141], 0, s[36:37]
	s_mov_b32 m0, s38
	s_nop 0
	global_load_lds_dwordx4 v[140:141], off
	v_lshl_add_u64 v[140:141], v[214:215], 0, s[36:37]
	s_add_i32 m0, s38, 0x2000
	s_nop 0
	global_load_lds_dwordx4 v[140:141], off
	s_mov_b32 m0, s64
	v_lshl_add_u64 v[140:141], v[216:217], 0, s[36:37]
	global_load_lds_dwordx4 v[140:141], off
	v_lshl_add_u64 v[140:141], v[224:225], 0, s[36:37]
	s_mov_b32 m0, s65
	s_nop 0
	global_load_lds_dwordx4 v[140:141], off
	ds_read_b128 v[164:167], v145 offset:49152
	ds_read_b128 v[168:171], v145 offset:50176
	ds_read_b128 v[172:175], v145 offset:51200
	ds_read_b128 v[176:179], v145 offset:52224
	ds_read_b128 v[180:183], v145 offset:53248
	ds_read_b128 v[184:187], v145 offset:54272
	ds_read_b128 v[188:191], v145 offset:55296
	ds_read_b128 v[192:195], v145 offset:56320
	s_waitcnt vmcnt(4)
	s_waitcnt lgkmcnt(0)
	s_barrier
; __device__ __forceinline__ unsigned cvt_pk_bf16(float lo, float hi) { unsigned r; asm("v_cvt_pk_bf16_f32 %0, %1, %2" : "=v"(r) : "v"(lo), "v"(hi)); return r; }
; #define PG8_STAGE(bufoff, gbase, voff) do { _Pragma("unroll") for (int _i = 0; _i < 2; ++_i) \
;         __builtin_amdgcn_global_load_lds((const unsigned*)((const char*)(gbase) + (voff)[_i]), (LAS unsigned*)(lds + (bufoff) + ldsw + _i * 8192), 16, 0, 0); } while (0)
; #define PG8_LDA(dst, b, h) do { _Pragma("unroll") for (int m = 0; m < 4; ++m) _Pragma("unroll") for (int k = 0; k < 2; ++k) dst[m][k] = *(const LAS bf16x8*)(lds + PG8_SA(b, h) + aoff + m * 2048 + k * 1024); } while (0)
; #define PG8_WAIT_V(n) asm volatile("s_waitcnt vmcnt(" #n ")" ::: "memory")
;     __device__ __forceinline__ void operator()(const f32x4 (&acc)[2][2][4][2], const Unit& u, int wr, int wc, int fr, int fq) const {
;         const int row0 = u.pm * BM + wr * 64 + fr, col0 = u.pn * BM + wc * 32 + 8 * fq;
; #pragma unroll
;         for (int ai = 0; ai < 2; ++ai)
; #pragma unroll
;             for (int m = 0; m < 4; ++m) { bf16_t* rowp = O + (size_t)(row0 + ai * HALF + m * 16) * ldc + col0;
; #pragma unroll
;                 for (int bj = 0; bj < 2; ++bj) { f32x4 v0 = acc[ai][bj][m][0], v1 = acc[ai][bj][m][1];
;                     if (ACT == 1) {
; #pragma unroll
;                         for (int j = 0; j < 4; ++j) { float a = fmaxf(v0[j], 0.f), b = fmaxf(v1[j], 0.f); v0[j] = a * a; v1[j] = b * b; } }
;                     u32x4 w; w.x = cvt_pk_bf16(v0[0], v0[1]); w.y = cvt_pk_bf16(v0[2], v0[3]); w.z = cvt_pk_bf16(v1[0], v1[1]); w.w = cvt_pk_bf16(v1[2], v1[3]);
;                     if (ACT == 1) __builtin_nontemporal_store(w, (u32x4*)(rowp + bj * HALF));
;                     else *(u32x4*)(rowp + bj * HALF) = w; } }
; template <class Epi, class Sched>
; __device__ __forceinline__ void gemm_phase(LAS unsigned char* lds, const Gemm g, const Sched& S, const Epi& E) {
;     ...
;             PG8_LDB(B1, 1, 1); PG8_STAGE(PG8_SB(1, 0), b3, voffB);
;             PG8_BAR; PG8_WAIT_L(0); PG8_MMA(0, 1, At, B1); PG8_BAR;
;             PG8_LDA(At, 1, 1); PG8_STAGE(PG8_SA(1, 0), a3, voffA);
;             PG8_BAR; PG8_WAIT_L(0); PG8_MMA(1, 0, At, B0); PG8_BAR; PG8_SCHED;
;             PG8_STAGE(PG8_SB(1, 1), b3 + hstep, voffB);
;             PG8_WAIT_V(6); PG8_BAR; PG8_MMA(1, 1, At, B1); PG8_BAR;
;         }
	s_setprio 0
	v_mfma_f32_16x16x32_bf16 v[62:65], v[146:149], v[164:167], v[62:65]
	v_mfma_f32_16x16x32_bf16 v[58:61], v[154:157], v[164:167], v[58:61]
	v_mfma_f32_16x16x32_bf16 v[46:49], v[146:149], v[172:175], v[46:49]
	v_mfma_f32_16x16x32_bf16 v[42:45], v[154:157], v[172:175], v[42:45]
	v_mfma_f32_16x16x32_bf16 v[30:33], v[146:149], v[180:183], v[30:33]
	v_mfma_f32_16x16x32_bf16 v[26:29], v[154:157], v[180:183], v[26:29]
	v_mfma_f32_16x16x32_bf16 v[14:17], v[146:149], v[188:191], v[14:17]
	v_mfma_f32_16x16x32_bf16 v[10:13], v[154:157], v[188:191], v[10:13]
	v_mfma_f32_16x16x32_bf16 v[62:65], v[150:153], v[168:171], v[62:65]
	v_mfma_f32_16x16x32_bf16 v[58:61], v[160:163], v[168:171], v[58:61]
	v_mfma_f32_16x16x32_bf16 v[46:49], v[150:153], v[176:179], v[46:49]
	v_mfma_f32_16x16x32_bf16 v[42:45], v[160:163], v[176:179], v[42:45]
	v_mfma_f32_16x16x32_bf16 v[30:33], v[150:153], v[184:187], v[30:33]
	v_mfma_f32_16x16x32_bf16 v[26:29], v[160:163], v[184:187], v[26:29]
	v_mfma_f32_16x16x32_bf16 v[14:17], v[150:153], v[192:195], v[14:17]
	v_mfma_f32_16x16x32_bf16 v[10:13], v[160:163], v[192:195], v[10:13]
	s_add_u32 s38, s48, 0x80080
	s_addc_u32 s39, s49, 0
	s_add_i32 s48, s50, s56
	v_lshl_add_u64 v[140:141], s[38:39], 0, v[0:1]
	s_mov_b32 m0, s48
	s_nop 0
	global_load_lds_dwordx4 v[140:141], off
	v_lshl_add_u64 v[140:141], s[38:39], 0, v[130:131]
	s_add_i32 m0, s48, 0x2000
	s_nop 0
	global_load_lds_dwordx4 v[140:141], off
	v_mfma_f32_16x16x32_bf16 v[54:57], v[196:199], v[164:167], v[54:57]
	v_mfma_f32_16x16x32_bf16 v[50:53], v[204:207], v[164:167], v[50:53]
	v_mfma_f32_16x16x32_bf16 v[38:41], v[196:199], v[172:175], v[38:41]
	v_mfma_f32_16x16x32_bf16 v[34:37], v[204:207], v[172:175], v[34:37]
	v_mfma_f32_16x16x32_bf16 v[22:25], v[196:199], v[180:183], v[22:25]
	v_mfma_f32_16x16x32_bf16 v[18:21], v[204:207], v[180:183], v[18:21]
	v_mfma_f32_16x16x32_bf16 v[6:9], v[196:199], v[188:191], v[6:9]
	v_mfma_f32_16x16x32_bf16 v[2:5], v[204:207], v[188:191], v[2:5]
	v_mfma_f32_16x16x32_bf16 v[54:57], v[200:203], v[168:171], v[54:57]
	v_mfma_f32_16x16x32_bf16 v[50:53], v[210:213], v[168:171], v[50:53]
	v_mfma_f32_16x16x32_bf16 v[38:41], v[200:203], v[176:179], v[38:41]
	v_mfma_f32_16x16x32_bf16 v[34:37], v[210:213], v[176:179], v[34:37]
	v_mfma_f32_16x16x32_bf16 v[22:25], v[200:203], v[184:187], v[22:25]
	v_mfma_f32_16x16x32_bf16 v[18:21], v[210:213], v[184:187], v[18:21]
	v_mfma_f32_16x16x32_bf16 v[6:9], v[200:203], v[192:195], v[6:9]
	v_mfma_f32_16x16x32_bf16 v[2:5], v[210:213], v[192:195], v[2:5]
	s_setprio 1
	s_add_i32 s73, s73, 2
	s_add_u32 s71, s71, 0x100
	s_addc_u32 s72, s72, 0
	s_add_u32 s46, s46, 0x100
	s_addc_u32 s47, s47, 0
	s_cmp_gt_u32 s73, 29
	s_barrier
	s_cbranch_scc0 .LBB0_73
	v_lshl_add_u32 v146, s8, 8, v142
	v_max_f32_e32 v122, v122, v122
	v_ashrrev_i32_e32 v147, 31, v146
	v_max_f32_e32 v122, 0, v122
	v_max_f32_e32 v123, v123, v123
	v_max_f32_e32 v124, v124, v124
	v_lshl_or_b32 v140, s68, 8, v144
	v_lshlrev_b64 v[148:149], 14, v[146:147]
	v_mul_f32_e32 v147, v122, v122
	v_max_f32_e32 v122, v127, v127
	v_max_f32_e32 v123, 0, v123
	v_max_f32_e32 v124, 0, v124
	v_ashrrev_i32_e32 v141, 31, v140
	v_max_f32_e32 v126, v126, v126
	v_max_f32_e32 v122, 0, v122
	v_mul_f32_e32 v127, v123, v123
	v_max_f32_e32 v123, v128, v128
	v_mul_f32_e32 v128, v124, v124
	v_max_f32_e32 v124, v129, v129
	v_max_f32_e32 v125, v125, v125
	v_lshl_add_u64 v[148:149], s[24:25], 0, v[148:149]
	v_lshlrev_b64 v[150:151], 1, v[140:141]
	v_max_f32_e32 v126, 0, v126
	v_mul_f32_e32 v122, v122, v122
	v_max_f32_e32 v123, 0, v123
	v_max_f32_e32 v124, 0, v124
	v_max_f32_e32 v125, 0, v125
	v_max_f32_e32 v114, v114, v114
	v_lshl_add_u64 v[140:141], v[148:149], 0, v[150:151]
	v_mul_f32_e32 v126, v126, v126
	v_mul_f32_e32 v123, v123, v123
	v_mul_f32_e32 v124, v124, v124
	v_mul_f32_e32 v125, v125, v125
	v_cvt_pk_bf16_f32 v122, v126, v122
	v_max_f32_e32 v114, 0, v114
	v_max_f32_e32 v115, v115, v115
	v_max_f32_e32 v116, v116, v116
	v_cvt_pk_bf16_f32 v123, v123, v124
	v_cvt_pk_bf16_f32 v124, v147, v127
	v_cvt_pk_bf16_f32 v125, v128, v125
	global_store_dwordx4 v[140:141], v[122:125], off nt
	v_max_f32_e32 v115, 0, v115
	v_max_f32_e32 v116, 0, v116
	v_mul_f32_e32 v122, v114, v114
	v_max_f32_e32 v114, v119, v119
	v_max_f32_e32 v118, v118, v118
	v_max_f32_e32 v114, 0, v114
	v_mul_f32_e32 v119, v115, v115
	v_max_f32_e32 v115, v120, v120
	v_mul_f32_e32 v120, v116, v116
	v_max_f32_e32 v116, v121, v121
	v_max_f32_e32 v117, v117, v117
	v_max_f32_e32 v118, 0, v118
	v_mul_f32_e32 v114, v114, v114
	v_max_f32_e32 v115, 0, v115
	v_max_f32_e32 v116, 0, v116
	v_max_f32_e32 v117, 0, v117
	v_mul_f32_e32 v118, v118, v118
	v_mul_f32_e32 v115, v115, v115
	v_mul_f32_e32 v116, v116, v116
	v_mul_f32_e32 v117, v117, v117
	v_cvt_pk_bf16_f32 v114, v118, v114
	v_max_f32_e32 v106, v106, v106
	v_cvt_pk_bf16_f32 v115, v115, v116
	v_cvt_pk_bf16_f32 v116, v122, v119
	v_cvt_pk_bf16_f32 v117, v120, v117
	global_store_dwordx4 v[140:141], v[114:117], off offset:256 nt
	v_max_f32_e32 v106, 0, v106
	v_max_f32_e32 v107, v107, v107
	v_or_b32_e32 v114, 16, v146
	v_max_f32_e32 v108, v108, v108
	v_ashrrev_i32_e32 v115, 31, v114
	v_mul_f32_e32 v116, v106, v106
	v_max_f32_e32 v106, v111, v111
	v_max_f32_e32 v107, 0, v107
	v_max_f32_e32 v108, 0, v108
	v_lshlrev_b64 v[114:115], 14, v[114:115]
	v_max_f32_e32 v110, v110, v110
	v_max_f32_e32 v106, 0, v106
	v_mul_f32_e32 v111, v107, v107
	v_max_f32_e32 v107, v112, v112
	v_mul_f32_e32 v112, v108, v108
	v_max_f32_e32 v108, v113, v113
	v_max_f32_e32 v109, v109, v109
	v_lshl_add_u64 v[114:115], s[24:25], 0, v[114:115]
	v_max_f32_e32 v110, 0, v110
	v_mul_f32_e32 v106, v106, v106
; __device__ __forceinline__ unsigned cvt_pk_bf16(float lo, float hi) { unsigned r; asm("v_cvt_pk_bf16_f32 %0, %1, %2" : "=v"(r) : "v"(lo), "v"(hi)); return r; }
;     __device__ __forceinline__ void operator()(const f32x4 (&acc)[2][2][4][2], const Unit& u, int wr, int wc, int fr, int fq) const {
;         const int row0 = u.pm * BM + wr * 64 + fr, col0 = u.pn * BM + wc * 32 + 8 * fq;
; #pragma unroll
;         for (int ai = 0; ai < 2; ++ai)
; #pragma unroll
;             for (int m = 0; m < 4; ++m) { bf16_t* rowp = O + (size_t)(row0 + ai * HALF + m * 16) * ldc + col0;
; #pragma unroll
;                 for (int bj = 0; bj < 2; ++bj) { f32x4 v0 = acc[ai][bj][m][0], v1 = acc[ai][bj][m][1];
;                     if (ACT == 1) {
; #pragma unroll
;                         for (int j = 0; j < 4; ++j) { float a = fmaxf(v0[j], 0.f), b = fmaxf(v1[j], 0.f); v0[j] = a * a; v1[j] = b * b; } }
;                     u32x4 w; w.x = cvt_pk_bf16(v0[0], v0[1]); w.y = cvt_pk_bf16(v0[2], v0[3]); w.z = cvt_pk_bf16(v1[0], v1[1]); w.w = cvt_pk_bf16(v1[2], v1[3]);
;                     if (ACT == 1) __builtin_nontemporal_store(w, (u32x4*)(rowp + bj * HALF));
;                     else *(u32x4*)(rowp + bj * HALF) = w; } }
	v_max_f32_e32 v107, 0, v107
	v_max_f32_e32 v108, 0, v108
	v_max_f32_e32 v109, 0, v109
	v_max_f32_e32 v98, v98, v98
	v_lshl_add_u64 v[114:115], v[114:115], 0, v[150:151]
	v_mul_f32_e32 v110, v110, v110
	v_mul_f32_e32 v107, v107, v107
	v_mul_f32_e32 v108, v108, v108
	v_mul_f32_e32 v109, v109, v109
	v_cvt_pk_bf16_f32 v106, v110, v106
	v_max_f32_e32 v98, 0, v98
	v_max_f32_e32 v99, v99, v99
	v_max_f32_e32 v100, v100, v100
	v_cvt_pk_bf16_f32 v107, v107, v108
	v_cvt_pk_bf16_f32 v108, v116, v111
	v_cvt_pk_bf16_f32 v109, v112, v109
	global_store_dwordx4 v[114:115], v[106:109], off nt
	v_max_f32_e32 v99, 0, v99
	v_max_f32_e32 v100, 0, v100
	v_mul_f32_e32 v106, v98, v98
	v_max_f32_e32 v98, v103, v103
	v_max_f32_e32 v102, v102, v102
	v_max_f32_e32 v98, 0, v98
	v_mul_f32_e32 v103, v99, v99
	v_max_f32_e32 v99, v104, v104
	v_mul_f32_e32 v104, v100, v100
	v_max_f32_e32 v100, v105, v105
	v_max_f32_e32 v101, v101, v101
	v_max_f32_e32 v102, 0, v102
	v_mul_f32_e32 v98, v98, v98
	v_max_f32_e32 v99, 0, v99
	v_max_f32_e32 v100, 0, v100
	v_max_f32_e32 v101, 0, v101
	v_mul_f32_e32 v102, v102, v102
	v_mul_f32_e32 v99, v99, v99
	v_mul_f32_e32 v100, v100, v100
	v_mul_f32_e32 v101, v101, v101
	v_cvt_pk_bf16_f32 v98, v102, v98
	v_max_f32_e32 v90, v90, v90
	v_cvt_pk_bf16_f32 v99, v99, v100
	v_cvt_pk_bf16_f32 v100, v106, v103
	v_cvt_pk_bf16_f32 v101, v104, v101
	global_store_dwordx4 v[114:115], v[98:101], off offset:256 nt
	v_max_f32_e32 v90, 0, v90
	v_max_f32_e32 v91, v91, v91
	v_or_b32_e32 v98, 32, v146
	v_max_f32_e32 v92, v92, v92
	v_ashrrev_i32_e32 v99, 31, v98
	v_mul_f32_e32 v100, v90, v90
	v_max_f32_e32 v90, v95, v95
	v_max_f32_e32 v91, 0, v91
	v_max_f32_e32 v92, 0, v92
	v_lshlrev_b64 v[98:99], 14, v[98:99]
	v_max_f32_e32 v94, v94, v94
	v_max_f32_e32 v90, 0, v90
	v_mul_f32_e32 v95, v91, v91
	v_max_f32_e32 v91, v96, v96
	v_mul_f32_e32 v96, v92, v92
	v_max_f32_e32 v92, v97, v97
	v_max_f32_e32 v93, v93, v93
	v_lshl_add_u64 v[98:99], s[24:25], 0, v[98:99]
	v_max_f32_e32 v94, 0, v94
	v_mul_f32_e32 v90, v90, v90
	v_max_f32_e32 v91, 0, v91
	v_max_f32_e32 v92, 0, v92
	v_max_f32_e32 v93, 0, v93
	v_max_f32_e32 v82, v82, v82
	v_lshl_add_u64 v[98:99], v[98:99], 0, v[150:151]
	v_mul_f32_e32 v94, v94, v94
	v_mul_f32_e32 v91, v91, v91
	v_mul_f32_e32 v92, v92, v92
	v_mul_f32_e32 v93, v93, v93
	v_cvt_pk_bf16_f32 v90, v94, v90
	v_max_f32_e32 v82, 0, v82
	v_max_f32_e32 v83, v83, v83
	v_max_f32_e32 v84, v84, v84
	v_cvt_pk_bf16_f32 v91, v91, v92
	v_cvt_pk_bf16_f32 v92, v100, v95
	v_cvt_pk_bf16_f32 v93, v96, v93
	global_store_dwordx4 v[98:99], v[90:93], off nt
	v_max_f32_e32 v83, 0, v83
	v_max_f32_e32 v84, 0, v84
	v_mul_f32_e32 v90, v82, v82
	v_max_f32_e32 v82, v87, v87
	v_max_f32_e32 v86, v86, v86
	v_max_f32_e32 v82, 0, v82
	v_mul_f32_e32 v87, v83, v83
	v_max_f32_e32 v83, v88, v88
	v_mul_f32_e32 v88, v84, v84
	v_max_f32_e32 v84, v89, v89
	v_max_f32_e32 v85, v85, v85
	v_max_f32_e32 v86, 0, v86
	v_mul_f32_e32 v82, v82, v82
	v_max_f32_e32 v83, 0, v83
	v_max_f32_e32 v84, 0, v84
	v_max_f32_e32 v85, 0, v85
	v_mul_f32_e32 v86, v86, v86
	v_mul_f32_e32 v83, v83, v83
	v_mul_f32_e32 v84, v84, v84
	v_mul_f32_e32 v85, v85, v85
	v_cvt_pk_bf16_f32 v82, v86, v82
	v_max_f32_e32 v74, v74, v74
	v_cvt_pk_bf16_f32 v83, v83, v84
	v_cvt_pk_bf16_f32 v84, v90, v87
	v_cvt_pk_bf16_f32 v85, v88, v85
	global_store_dwordx4 v[98:99], v[82:85], off offset:256 nt
	v_max_f32_e32 v74, 0, v74
	v_max_f32_e32 v75, v75, v75
	v_or_b32_e32 v82, 48, v146
	v_max_f32_e32 v76, v76, v76
	v_ashrrev_i32_e32 v83, 31, v82
	v_mul_f32_e32 v84, v74, v74
	v_max_f32_e32 v74, v79, v79
	v_max_f32_e32 v75, 0, v75
	v_max_f32_e32 v76, 0, v76
	v_lshlrev_b64 v[82:83], 14, v[82:83]
	v_max_f32_e32 v78, v78, v78
	v_max_f32_e32 v74, 0, v74
	v_mul_f32_e32 v79, v75, v75
	v_max_f32_e32 v75, v80, v80
	v_mul_f32_e32 v80, v76, v76
	v_max_f32_e32 v76, v81, v81
	v_max_f32_e32 v77, v77, v77
	v_lshl_add_u64 v[82:83], s[24:25], 0, v[82:83]
	v_max_f32_e32 v78, 0, v78
	v_mul_f32_e32 v74, v74, v74
	v_max_f32_e32 v75, 0, v75
	v_max_f32_e32 v76, 0, v76
	v_max_f32_e32 v77, 0, v77
	v_max_f32_e32 v66, v66, v66
	v_max_f32_e32 v67, v67, v67
	v_max_f32_e32 v68, v68, v68
	v_lshl_add_u64 v[82:83], v[82:83], 0, v[150:151]
	v_mul_f32_e32 v78, v78, v78
	v_mul_f32_e32 v75, v75, v75
	v_mul_f32_e32 v76, v76, v76
	v_mul_f32_e32 v77, v77, v77
	v_cvt_pk_bf16_f32 v74, v78, v74
	v_max_f32_e32 v66, 0, v66
	v_max_f32_e32 v67, 0, v67
	v_max_f32_e32 v68, 0, v68
	v_cvt_pk_bf16_f32 v75, v75, v76
	v_cvt_pk_bf16_f32 v76, v84, v79
	v_cvt_pk_bf16_f32 v77, v80, v77
	global_store_dwordx4 v[82:83], v[74:77], off nt
	v_max_f32_e32 v69, v69, v69
	v_max_f32_e32 v70, v70, v70
	v_mul_f32_e32 v74, v66, v66
	v_max_f32_e32 v66, v71, v71
	v_mul_f32_e32 v71, v67, v67
	v_max_f32_e32 v67, v72, v72
	v_mul_f32_e32 v72, v68, v68
	v_max_f32_e32 v68, v73, v73
	v_max_f32_e32 v67, 0, v67
	v_max_f32_e32 v68, 0, v68
	v_max_f32_e32 v66, 0, v66
	v_mul_f32_e32 v67, v67, v67
	v_max_f32_e32 v69, 0, v69
	v_mul_f32_e32 v68, v68, v68
	v_max_f32_e32 v58, v58, v58
	v_max_f32_e32 v70, 0, v70
	v_mul_f32_e32 v66, v66, v66
	v_mul_f32_e32 v69, v69, v69
	v_cvt_pk_bf16_f32 v67, v67, v68
	v_cvt_pk_bf16_f32 v68, v74, v71
	v_max_f32_e32 v58, 0, v58
	v_max_f32_e32 v59, v59, v59
	v_max_f32_e32 v60, v60, v60
	v_mul_f32_e32 v70, v70, v70
	v_cvt_pk_bf16_f32 v66, v70, v66
	v_cvt_pk_bf16_f32 v69, v72, v69
	global_store_dwordx4 v[82:83], v[66:69], off offset:256 nt
	v_max_f32_e32 v62, v62, v62
	v_max_f32_e32 v59, 0, v59
	v_mul_f32_e32 v68, v58, v58
	v_max_f32_e32 v58, v63, v63
	v_max_f32_e32 v60, 0, v60
	v_max_f32_e32 v62, 0, v62
	v_max_f32_e32 v58, 0, v58
	v_mul_f32_e32 v63, v59, v59
	v_max_f32_e32 v59, v64, v64
	v_mul_f32_e32 v64, v60, v60
; __device__ __forceinline__ unsigned cvt_pk_bf16(float lo, float hi) { unsigned r; asm("v_cvt_pk_bf16_f32 %0, %1, %2" : "=v"(r) : "v"(lo), "v"(hi)); return r; }
;     __device__ __forceinline__ void operator()(const f32x4 (&acc)[2][2][4][2], const Unit& u, int wr, int wc, int fr, int fq) const {
;         const int row0 = u.pm * BM + wr * 64 + fr, col0 = u.pn * BM + wc * 32 + 8 * fq;
; #pragma unroll
;         for (int ai = 0; ai < 2; ++ai)
; #pragma unroll
;             for (int m = 0; m < 4; ++m) { bf16_t* rowp = O + (size_t)(row0 + ai * HALF + m * 16) * ldc + col0;
; #pragma unroll
;                 for (int bj = 0; bj < 2; ++bj) { f32x4 v0 = acc[ai][bj][m][0], v1 = acc[ai][bj][m][1];
;                     if (ACT == 1) {
; #pragma unroll
;                         for (int j = 0; j < 4; ++j) { float a = fmaxf(v0[j], 0.f), b = fmaxf(v1[j], 0.f); v0[j] = a * a; v1[j] = b * b; } }
;                     u32x4 w; w.x = cvt_pk_bf16(v0[0], v0[1]); w.y = cvt_pk_bf16(v0[2], v0[3]); w.z = cvt_pk_bf16(v1[0], v1[1]); w.w = cvt_pk_bf16(v1[2], v1[3]);
;                     if (ACT == 1) __builtin_nontemporal_store(w, (u32x4*)(rowp + bj * HALF));
;                     else *(u32x4*)(rowp + bj * HALF) = w; } }
	v_max_f32_e32 v60, v65, v65
	v_mul_f32_e32 v62, v62, v62
	v_mul_f32_e32 v58, v58, v58
	v_max_f32_e32 v59, 0, v59
	v_max_f32_e32 v60, 0, v60
	v_max_f32_e32 v61, v61, v61
	s_mov_b32 s8, 0x200000
	v_mul_f32_e32 v59, v59, v59
	v_max_f32_e32 v61, 0, v61
	v_mul_f32_e32 v60, v60, v60
	v_cvt_pk_bf16_f32 v58, v62, v58
	v_add_co_u32_e32 v62, vcc, s8, v140
	v_max_f32_e32 v50, v50, v50
	v_max_f32_e32 v51, v51, v51
	v_max_f32_e32 v52, v52, v52
	v_mul_f32_e32 v61, v61, v61
	v_cvt_pk_bf16_f32 v59, v59, v60
	v_cvt_pk_bf16_f32 v60, v68, v63
	v_addc_co_u32_e32 v63, vcc, 0, v141, vcc
	v_max_f32_e32 v50, 0, v50
	v_max_f32_e32 v51, 0, v51
	v_max_f32_e32 v52, 0, v52
	v_cvt_pk_bf16_f32 v61, v64, v61
	global_store_dwordx4 v[62:63], v[58:61], off nt
	v_max_f32_e32 v53, v53, v53
	s_mov_b64 s[38:39], 0x200000
	v_mul_f32_e32 v58, v50, v50
	v_max_f32_e32 v50, v55, v55
	v_mul_f32_e32 v55, v51, v51
	v_max_f32_e32 v51, v56, v56
	v_mul_f32_e32 v56, v52, v52
	v_max_f32_e32 v52, v57, v57
	v_max_f32_e32 v51, 0, v51
	v_max_f32_e32 v52, 0, v52
	v_max_f32_e32 v54, v54, v54
	v_max_f32_e32 v50, 0, v50
	v_mul_f32_e32 v51, v51, v51
	v_max_f32_e32 v53, 0, v53
	v_mul_f32_e32 v52, v52, v52
	v_max_f32_e32 v42, v42, v42
	v_lshl_add_u64 v[66:67], v[140:141], 0, s[38:39]
	v_max_f32_e32 v54, 0, v54
	v_mul_f32_e32 v50, v50, v50
	v_mul_f32_e32 v53, v53, v53
	v_cvt_pk_bf16_f32 v51, v51, v52
	v_cvt_pk_bf16_f32 v52, v58, v55
	v_max_f32_e32 v42, 0, v42
	v_max_f32_e32 v43, v43, v43
	v_max_f32_e32 v44, v44, v44
	v_mul_f32_e32 v54, v54, v54
	v_cvt_pk_bf16_f32 v50, v54, v50
	v_cvt_pk_bf16_f32 v53, v56, v53
	global_store_dwordx4 v[66:67], v[50:53], off offset:256 nt
	v_max_f32_e32 v46, v46, v46
	v_max_f32_e32 v43, 0, v43
	v_mul_f32_e32 v52, v42, v42
	v_max_f32_e32 v42, v47, v47
	v_max_f32_e32 v44, 0, v44
	v_max_f32_e32 v46, 0, v46
	v_max_f32_e32 v42, 0, v42
	v_mul_f32_e32 v47, v43, v43
	v_max_f32_e32 v43, v48, v48
	v_mul_f32_e32 v48, v44, v44
	v_max_f32_e32 v44, v49, v49
	v_mul_f32_e32 v46, v46, v46
	v_mul_f32_e32 v42, v42, v42
	v_max_f32_e32 v43, 0, v43
	v_max_f32_e32 v44, 0, v44
	v_max_f32_e32 v45, v45, v45
	s_mov_b32 s8, 0x240000
	v_mul_f32_e32 v43, v43, v43
	v_max_f32_e32 v45, 0, v45
	v_mul_f32_e32 v44, v44, v44
	v_cvt_pk_bf16_f32 v42, v46, v42
	v_add_co_u32_e32 v46, vcc, s8, v140
	v_max_f32_e32 v34, v34, v34
	v_max_f32_e32 v35, v35, v35
	v_max_f32_e32 v36, v36, v36
	v_mul_f32_e32 v45, v45, v45
	v_cvt_pk_bf16_f32 v43, v43, v44
	v_cvt_pk_bf16_f32 v44, v52, v47
	v_addc_co_u32_e32 v47, vcc, 0, v141, vcc
	v_max_f32_e32 v34, 0, v34
	v_max_f32_e32 v35, 0, v35
	v_max_f32_e32 v36, 0, v36
	v_cvt_pk_bf16_f32 v45, v48, v45
	global_store_dwordx4 v[46:47], v[42:45], off nt
	v_max_f32_e32 v37, v37, v37
	s_mov_b64 s[38:39], 0x240000
	v_mul_f32_e32 v42, v34, v34
	v_max_f32_e32 v34, v39, v39
	v_mul_f32_e32 v39, v35, v35
	v_max_f32_e32 v35, v40, v40
	v_mul_f32_e32 v40, v36, v36
	v_max_f32_e32 v36, v41, v41
	v_max_f32_e32 v35, 0, v35
	v_max_f32_e32 v36, 0, v36
	v_max_f32_e32 v38, v38, v38
	v_max_f32_e32 v34, 0, v34
	v_mul_f32_e32 v35, v35, v35
	v_max_f32_e32 v37, 0, v37
	v_mul_f32_e32 v36, v36, v36
	v_max_f32_e32 v26, v26, v26
	v_lshl_add_u64 v[50:51], v[140:141], 0, s[38:39]
	v_max_f32_e32 v38, 0, v38
	v_mul_f32_e32 v34, v34, v34
	v_mul_f32_e32 v37, v37, v37
	v_cvt_pk_bf16_f32 v35, v35, v36
	v_cvt_pk_bf16_f32 v36, v42, v39
	v_max_f32_e32 v26, 0, v26
	v_max_f32_e32 v27, v27, v27
	v_max_f32_e32 v28, v28, v28
	v_mul_f32_e32 v38, v38, v38
	v_cvt_pk_bf16_f32 v34, v38, v34
	v_cvt_pk_bf16_f32 v37, v40, v37
	global_store_dwordx4 v[50:51], v[34:37], off offset:256 nt
	v_max_f32_e32 v30, v30, v30
	v_max_f32_e32 v27, 0, v27
	v_mul_f32_e32 v36, v26, v26
	v_max_f32_e32 v26, v31, v31
	v_max_f32_e32 v28, 0, v28
	v_max_f32_e32 v30, 0, v30
; __device__ __forceinline__ unsigned cvt_pk_bf16(float lo, float hi) { unsigned r; asm("v_cvt_pk_bf16_f32 %0, %1, %2" : "=v"(r) : "v"(lo), "v"(hi)); return r; }
; #define PG8_WAIT_V(n) asm volatile("s_waitcnt vmcnt(" #n ")" ::: "memory")
; #define PG8_BAR __builtin_amdgcn_s_barrier()
;     __device__ __forceinline__ void operator()(const f32x4 (&acc)[2][2][4][2], const Unit& u, int wr, int wc, int fr, int fq) const {
;         const int row0 = u.pm * BM + wr * 64 + fr, col0 = u.pn * BM + wc * 32 + 8 * fq;
; #pragma unroll
;         for (int ai = 0; ai < 2; ++ai)
; #pragma unroll
;             for (int m = 0; m < 4; ++m) { bf16_t* rowp = O + (size_t)(row0 + ai * HALF + m * 16) * ldc + col0;
; #pragma unroll
;                 for (int bj = 0; bj < 2; ++bj) { f32x4 v0 = acc[ai][bj][m][0], v1 = acc[ai][bj][m][1];
;                     if (ACT == 1) {
; #pragma unroll
;                         for (int j = 0; j < 4; ++j) { float a = fmaxf(v0[j], 0.f), b = fmaxf(v1[j], 0.f); v0[j] = a * a; v1[j] = b * b; } }
;                     u32x4 w; w.x = cvt_pk_bf16(v0[0], v0[1]); w.y = cvt_pk_bf16(v0[2], v0[3]); w.z = cvt_pk_bf16(v1[0], v1[1]); w.w = cvt_pk_bf16(v1[2], v1[3]);
;                     if (ACT == 1) __builtin_nontemporal_store(w, (u32x4*)(rowp + bj * HALF));
;                     else *(u32x4*)(rowp + bj * HALF) = w; } }
; template <class Epi, class Sched>
; __device__ __forceinline__ void gemm_phase(LAS unsigned char* lds, const Gemm g, const Sched& S, const Epi& E) {
;     ...
;         E(acc, cur, wr, wc, fr, fq);
;         if (!has_next) break;
; #pragma unroll
;         for (int a = 0; a < 2; ++a)
; #pragma unroll
;             for (int b = 0; b < 2; ++b)
; #pragma unroll
;                 for (int m = 0; m < 4; ++m)
; #pragma unroll
;                     for (int n = 0; n < 2; ++n) acc[a][b][m][n] = (f32x4){0.f, 0.f, 0.f, 0.f};
;         cur = nxt; cA = nA; cB = nB; ++ui;
;     }
;     PG8_WAIT_V(0);
;     if (wr == 0) PG8_BAR;
;     PG8_BAR;
	v_max_f32_e32 v26, 0, v26
	v_mul_f32_e32 v31, v27, v27
	v_max_f32_e32 v27, v32, v32
	v_mul_f32_e32 v32, v28, v28
	v_max_f32_e32 v28, v33, v33
	v_mul_f32_e32 v30, v30, v30
	v_mul_f32_e32 v26, v26, v26
	v_max_f32_e32 v27, 0, v27
	v_max_f32_e32 v28, 0, v28
	v_max_f32_e32 v29, v29, v29
	s_mov_b32 s8, 0x280000
	v_mul_f32_e32 v27, v27, v27
	v_max_f32_e32 v29, 0, v29
	v_mul_f32_e32 v28, v28, v28
	v_cvt_pk_bf16_f32 v26, v30, v26
	v_add_co_u32_e32 v30, vcc, s8, v140
	v_max_f32_e32 v18, v18, v18
	v_max_f32_e32 v19, v19, v19
	v_max_f32_e32 v20, v20, v20
	v_mul_f32_e32 v29, v29, v29
	v_cvt_pk_bf16_f32 v27, v27, v28
	v_cvt_pk_bf16_f32 v28, v36, v31
	v_addc_co_u32_e32 v31, vcc, 0, v141, vcc
	v_max_f32_e32 v18, 0, v18
	v_max_f32_e32 v19, 0, v19
	v_max_f32_e32 v20, 0, v20
	v_cvt_pk_bf16_f32 v29, v32, v29
	global_store_dwordx4 v[30:31], v[26:29], off nt
	v_max_f32_e32 v21, v21, v21
	s_mov_b64 s[38:39], 0x280000
	v_mul_f32_e32 v26, v18, v18
	v_max_f32_e32 v18, v23, v23
	v_mul_f32_e32 v23, v19, v19
	v_max_f32_e32 v19, v24, v24
	v_mul_f32_e32 v24, v20, v20
	v_max_f32_e32 v20, v25, v25
	v_max_f32_e32 v19, 0, v19
	v_max_f32_e32 v20, 0, v20
	v_max_f32_e32 v22, v22, v22
	v_max_f32_e32 v18, 0, v18
	v_mul_f32_e32 v19, v19, v19
	v_max_f32_e32 v21, 0, v21
	v_mul_f32_e32 v20, v20, v20
	v_max_f32_e32 v10, v10, v10
	v_lshl_add_u64 v[34:35], v[140:141], 0, s[38:39]
	v_max_f32_e32 v22, 0, v22
	v_mul_f32_e32 v18, v18, v18
	v_mul_f32_e32 v21, v21, v21
	v_cvt_pk_bf16_f32 v19, v19, v20
	v_cvt_pk_bf16_f32 v20, v26, v23
	v_max_f32_e32 v10, 0, v10
	v_max_f32_e32 v11, v11, v11
	v_max_f32_e32 v12, v12, v12
	v_mul_f32_e32 v22, v22, v22
	v_cvt_pk_bf16_f32 v18, v22, v18
	v_cvt_pk_bf16_f32 v21, v24, v21
	global_store_dwordx4 v[34:35], v[18:21], off offset:256 nt
	v_max_f32_e32 v14, v14, v14
	v_max_f32_e32 v11, 0, v11
	v_mul_f32_e32 v20, v10, v10
	v_max_f32_e32 v10, v15, v15
	v_max_f32_e32 v12, 0, v12
	v_max_f32_e32 v14, 0, v14
	v_max_f32_e32 v10, 0, v10
	v_mul_f32_e32 v15, v11, v11
	v_max_f32_e32 v11, v16, v16
	v_mul_f32_e32 v16, v12, v12
	v_max_f32_e32 v12, v17, v17
	v_mul_f32_e32 v14, v14, v14
	v_mul_f32_e32 v10, v10, v10
	v_max_f32_e32 v11, 0, v11
	v_max_f32_e32 v12, 0, v12
	v_max_f32_e32 v13, v13, v13
	s_mov_b32 s8, 0x2c0000
	v_mul_f32_e32 v11, v11, v11
	v_max_f32_e32 v13, 0, v13
	v_mul_f32_e32 v12, v12, v12
	v_cvt_pk_bf16_f32 v10, v14, v10
	v_add_co_u32_e32 v14, vcc, s8, v140
	v_max_f32_e32 v2, v2, v2
	v_max_f32_e32 v3, v3, v3
	v_max_f32_e32 v4, v4, v4
	v_mul_f32_e32 v13, v13, v13
	v_cvt_pk_bf16_f32 v11, v11, v12
	v_cvt_pk_bf16_f32 v12, v20, v15
	v_addc_co_u32_e32 v15, vcc, 0, v141, vcc
	v_max_f32_e32 v2, 0, v2
	v_max_f32_e32 v3, 0, v3
	v_max_f32_e32 v4, 0, v4
	v_cvt_pk_bf16_f32 v13, v16, v13
	global_store_dwordx4 v[14:15], v[10:13], off nt
	v_max_f32_e32 v5, v5, v5
	s_mov_b64 s[38:39], 0x2c0000
	v_mul_f32_e32 v10, v2, v2
	v_max_f32_e32 v2, v7, v7
	v_mul_f32_e32 v7, v3, v3
	v_max_f32_e32 v3, v8, v8
	v_mul_f32_e32 v8, v4, v4
	v_max_f32_e32 v4, v9, v9
	v_max_f32_e32 v6, v6, v6
	v_max_f32_e32 v2, 0, v2
	v_max_f32_e32 v3, 0, v3
	v_max_f32_e32 v4, 0, v4
	v_max_f32_e32 v5, 0, v5
	v_lshl_add_u64 v[18:19], v[140:141], 0, s[38:39]
	v_max_f32_e32 v6, 0, v6
	v_mul_f32_e32 v2, v2, v2
	v_mul_f32_e32 v3, v3, v3
	v_mul_f32_e32 v4, v4, v4
	v_mul_f32_e32 v5, v5, v5
	s_and_b64 vcc, exec, s[40:41]
	s_mov_b32 s68, s26
	s_mov_b32 s8, s28
	s_mov_b64 s[46:47], s[44:45]
	s_mov_b64 s[48:49], s[42:43]
	v_mul_f32_e32 v6, v6, v6
	v_cvt_pk_bf16_f32 v2, v6, v2
	v_cvt_pk_bf16_f32 v3, v3, v4
	v_cvt_pk_bf16_f32 v4, v10, v7
	v_cvt_pk_bf16_f32 v5, v8, v5
	global_store_dwordx4 v[18:19], v[2:5], off offset:256 nt
	s_cbranch_vccz .LBB0_70
	s_waitcnt vmcnt(0)
	s_cmpk_gt_u32 s52, 0xff
	s_cbranch_scc1 .LBB0_77
	s_barrier

; #define PG8_STAGE(bufoff, gbase, voff) do { _Pragma("unroll") for (int _i = 0; _i < 2; ++_i) \
;         __builtin_amdgcn_global_load_lds((const unsigned*)((const char*)(gbase) + (voff)[_i]), (LAS unsigned*)(lds + (bufoff) + ldsw + _i * 8192), 16, 0, 0); } while (0)
; #define PG8_LDA(dst, b, h) do { _Pragma("unroll") for (int m = 0; m < 4; ++m) _Pragma("unroll") for (int k = 0; k < 2; ++k) dst[m][k] = *(const LAS bf16x8*)(lds + PG8_SA(b, h) + aoff + m * 2048 + k * 1024); } while (0)
; #define PG8_LDB(dst, b, h) do { _Pragma("unroll") for (int n = 0; n < 2; ++n) _Pragma("unroll") for (int k = 0; k < 2; ++k) dst[n][k] = *(const LAS bf16x8*)(lds + PG8_SB(b, h) + boff + n * 2048 + k * 1024); } while (0)
; #define PG8_MMA(ai, bj, At, Bt) do { __builtin_amdgcn_s_setprio(1); _Pragma("unroll") for (int m = 0; m < 4; ++m) _Pragma("unroll") for (int n = 0; n < 2; ++n) _Pragma("unroll") for (int k = 0; k < 2; ++k) \
;         acc[ai][bj][m][n] = __builtin_amdgcn_mfma_f32_16x16x32_bf16(Bt[n][k], At[m][k], acc[ai][bj][m][n], 0, 0, 0); __builtin_amdgcn_s_setprio(0); } while (0)
; #define PG8_WAIT_V(n) asm volatile("s_waitcnt vmcnt(" #n ")" ::: "memory")
; #define PG8_WAIT_L(n) asm volatile("s_waitcnt lgkmcnt(" #n ")" ::: "memory")
; template <class Epi, class Sched>
; __device__ __forceinline__ void gemm_phase(LAS unsigned char* lds, const Gemm g, const Sched& S, const Epi& E) {
;     ...
;         for (int t = 0; t < nt; t += 2) {
;             const bool last = (t == nt - 2);
;             const char* a1 = cA + (size_t)(t + 1) * kstep;
;             const char* a2 = last ? nA : cA + (size_t)(t + 2) * kstep; const char* b2 = last ? nB : cB + (size_t)(t + 2) * kstep;
;             const char* a3 = a2 + kstep; const char* b3 = b2 + kstep;
;             PG8_LDB(B0, 0, 0); PG8_SCHED; PG8_LDA(At, 0, 0); PG8_STAGE(PG8_SA(1, 1), a1 + hstep, voffA);
;             PG8_WAIT_L(8); PG8_BAR; PG8_WAIT_L(0); PG8_MMA(0, 0, At, B0); PG8_BAR; PG8_SCHED;
;             PG8_LDB(B1, 0, 1); PG8_STAGE(PG8_SB(0, 0), b2, voffB);
;             PG8_BAR; PG8_WAIT_L(0); PG8_MMA(0, 1, At, B1); PG8_BAR;
;             PG8_LDA(At, 0, 1); PG8_STAGE(PG8_SA(0, 0), a2, voffA);
;             PG8_BAR; PG8_WAIT_L(0); PG8_MMA(1, 0, At, B0); PG8_BAR; PG8_SCHED;
;             PG8_STAGE(PG8_SB(0, 1), b2 + hstep, voffB);
;             PG8_WAIT_V(6); PG8_BAR; PG8_MMA(1, 1, At, B1); PG8_BAR;
.LBB0_99:
	s_add_u32 s56, s28, 0x100
	s_addc_u32 s57, s29, 0
	s_cmp_eq_u32 s81, 28
	s_cselect_b32 s61, s51, s57
	s_cselect_b32 s60, s77, s56
	s_cselect_b32 s59, s49, s80
	s_cselect_b32 s58, s78, s79
	v_lshl_add_u64 v[156:157], s[28:29], 0, v[150:151]
	s_add_i32 m0, s9, 0xc000
	s_nop 0
	global_load_lds_dwordx4 v[156:157], off
	v_lshl_add_u64 v[156:157], s[28:29], 0, v[148:149]
	s_add_i32 m0, s9, 0xe000
	s_nop 0
	global_load_lds_dwordx4 v[156:157], off
	s_add_i32 s38, 0, 0x10000
	v_add_u32_e32 v110, s38, v169
	ds_read_b128 v[98:101], v110
	ds_read_b128 v[102:105], v110 offset:1024
	ds_read_b128 v[106:109], v110 offset:2048
	ds_read_b128 v[110:113], v110 offset:3072
	ds_read_b128 v[152:155], v171
	ds_read_b128 v[160:163], v171 offset:1024
	ds_read_b128 v[164:167], v171 offset:2048
	ds_read_b128 v[172:175], v171 offset:3072
	ds_read_b128 v[176:179], v171 offset:4096
	ds_read_b128 v[180:183], v171 offset:5120
	ds_read_b128 v[184:187], v171 offset:6144
	ds_read_b128 v[188:191], v171 offset:7168
	s_add_i32 s39, 0, 0x14000
	v_add_u32_e32 v156, s39, v169
	ds_read_b128 v[192:195], v156
	ds_read_b128 v[196:199], v156 offset:1024
	ds_read_b128 v[200:203], v156 offset:2048
	ds_read_b128 v[204:207], v156 offset:3072
	s_waitcnt lgkmcnt(4)
	s_barrier
	s_waitcnt lgkmcnt(0)
	s_setprio 0
	v_mfma_f32_16x16x32_bf16 v[142:145], v[98:101], v[152:155], v[142:145]
	v_mfma_f32_16x16x32_bf16 v[138:141], v[106:109], v[152:155], v[138:141]
	v_mfma_f32_16x16x32_bf16 v[126:129], v[98:101], v[164:167], v[126:129]
	v_mfma_f32_16x16x32_bf16 v[122:125], v[106:109], v[164:167], v[122:125]
	v_mfma_f32_16x16x32_bf16 v[94:97], v[98:101], v[176:179], v[94:97]
	v_mfma_f32_16x16x32_bf16 v[90:93], v[106:109], v[176:179], v[90:93]
	v_mfma_f32_16x16x32_bf16 v[86:89], v[98:101], v[184:187], v[86:89]
	v_mfma_f32_16x16x32_bf16 v[82:85], v[106:109], v[184:187], v[82:85]
	v_mfma_f32_16x16x32_bf16 v[142:145], v[102:105], v[160:163], v[142:145]
	v_mfma_f32_16x16x32_bf16 v[138:141], v[110:113], v[160:163], v[138:141]
	v_mfma_f32_16x16x32_bf16 v[126:129], v[102:105], v[172:175], v[126:129]
	v_mfma_f32_16x16x32_bf16 v[122:125], v[110:113], v[172:175], v[122:125]
	v_mfma_f32_16x16x32_bf16 v[94:97], v[102:105], v[180:183], v[94:97]
	v_mfma_f32_16x16x32_bf16 v[90:93], v[110:113], v[180:183], v[90:93]
	v_mfma_f32_16x16x32_bf16 v[86:89], v[102:105], v[188:191], v[86:89]
	v_mfma_f32_16x16x32_bf16 v[82:85], v[110:113], v[188:191], v[82:85]
	v_mfma_f32_16x16x32_bf16 v[134:137], v[192:195], v[152:155], v[134:137]
	v_mfma_f32_16x16x32_bf16 v[130:133], v[200:203], v[152:155], v[130:133]
	v_mfma_f32_16x16x32_bf16 v[118:121], v[192:195], v[164:167], v[118:121]
	v_mfma_f32_16x16x32_bf16 v[114:117], v[200:203], v[164:167], v[114:117]
	v_mfma_f32_16x16x32_bf16 v[78:81], v[192:195], v[176:179], v[78:81]
	v_mfma_f32_16x16x32_bf16 v[74:77], v[200:203], v[176:179], v[74:77]
	v_mfma_f32_16x16x32_bf16 v[70:73], v[192:195], v[184:187], v[70:73]
	v_mfma_f32_16x16x32_bf16 v[66:69], v[200:203], v[184:187], v[66:69]
	v_mfma_f32_16x16x32_bf16 v[134:137], v[196:199], v[160:163], v[134:137]
	v_mfma_f32_16x16x32_bf16 v[130:133], v[204:207], v[160:163], v[130:133]
	v_mfma_f32_16x16x32_bf16 v[118:121], v[196:199], v[172:175], v[118:121]
	v_mfma_f32_16x16x32_bf16 v[114:117], v[204:207], v[172:175], v[114:117]
	v_mfma_f32_16x16x32_bf16 v[78:81], v[196:199], v[180:183], v[78:81]
	v_mfma_f32_16x16x32_bf16 v[74:77], v[204:207], v[180:183], v[74:77]
	v_mfma_f32_16x16x32_bf16 v[70:73], v[196:199], v[188:191], v[70:73]
	v_mfma_f32_16x16x32_bf16 v[66:69], v[204:207], v[188:191], v[66:69]
	s_setprio 1
	s_barrier
	s_add_i32 s28, s38, s67
	v_lshl_add_u64 v[156:157], s[58:59], 0, v[0:1]
	s_mov_b32 m0, s28
	v_lshl_add_u64 v[210:211], s[58:59], 0, v[146:147]
	global_load_lds_dwordx4 v[156:157], off
	s_add_i32 m0, s28, 0x2000
	s_nop 0
	global_load_lds_dwordx4 v[210:211], off
	s_mov_b32 m0, s9
	v_lshl_add_u64 v[212:213], s[60:61], 0, v[0:1]
	global_load_lds_dwordx4 v[212:213], off
	v_lshl_add_u64 v[214:215], s[60:61], 0, v[146:147]
	s_mov_b32 m0, s68
	s_nop 0
	global_load_lds_dwordx4 v[214:215], off
	ds_read_b128 v[152:155], v171 offset:16384
	ds_read_b128 v[160:163], v171 offset:17408
	ds_read_b128 v[164:167], v171 offset:18432
	ds_read_b128 v[172:175], v171 offset:19456
	ds_read_b128 v[176:179], v171 offset:20480
	ds_read_b128 v[180:183], v171 offset:21504
	ds_read_b128 v[184:187], v171 offset:22528
	ds_read_b128 v[188:191], v171 offset:23552
	s_waitcnt vmcnt(4)
	s_waitcnt lgkmcnt(0)
	s_barrier
	s_setprio 0
	v_mfma_f32_16x16x32_bf16 v[62:65], v[98:101], v[152:155], v[62:65]
	v_mfma_f32_16x16x32_bf16 v[58:61], v[106:109], v[152:155], v[58:61]
	v_mfma_f32_16x16x32_bf16 v[46:49], v[98:101], v[164:167], v[46:49]
	v_mfma_f32_16x16x32_bf16 v[42:45], v[106:109], v[164:167], v[42:45]
	v_mfma_f32_16x16x32_bf16 v[30:33], v[98:101], v[176:179], v[30:33]
	v_mfma_f32_16x16x32_bf16 v[26:29], v[106:109], v[176:179], v[26:29]
	v_mfma_f32_16x16x32_bf16 v[22:25], v[98:101], v[184:187], v[22:25]
	v_mfma_f32_16x16x32_bf16 v[18:21], v[106:109], v[184:187], v[18:21]
	v_mfma_f32_16x16x32_bf16 v[62:65], v[102:105], v[160:163], v[62:65]
	v_mfma_f32_16x16x32_bf16 v[58:61], v[110:113], v[160:163], v[58:61]
	v_mfma_f32_16x16x32_bf16 v[46:49], v[102:105], v[172:175], v[46:49]
	v_mfma_f32_16x16x32_bf16 v[42:45], v[110:113], v[172:175], v[42:45]
	v_mfma_f32_16x16x32_bf16 v[30:33], v[102:105], v[180:183], v[30:33]
	v_mfma_f32_16x16x32_bf16 v[26:29], v[110:113], v[180:183], v[26:29]
	v_mfma_f32_16x16x32_bf16 v[22:25], v[102:105], v[188:191], v[22:25]
	v_mfma_f32_16x16x32_bf16 v[18:21], v[110:113], v[188:191], v[18:21]
	v_mfma_f32_16x16x32_bf16 v[54:57], v[192:195], v[152:155], v[54:57]
	v_mfma_f32_16x16x32_bf16 v[50:53], v[200:203], v[152:155], v[50:53]
	v_mfma_f32_16x16x32_bf16 v[38:41], v[192:195], v[164:167], v[38:41]
	v_mfma_f32_16x16x32_bf16 v[34:37], v[200:203], v[164:167], v[34:37]
	v_mfma_f32_16x16x32_bf16 v[14:17], v[192:195], v[176:179], v[14:17]
	v_mfma_f32_16x16x32_bf16 v[10:13], v[200:203], v[176:179], v[10:13]
	v_mfma_f32_16x16x32_bf16 v[6:9], v[192:195], v[184:187], v[6:9]
	v_mfma_f32_16x16x32_bf16 v[2:5], v[200:203], v[184:187], v[2:5]
	v_mfma_f32_16x16x32_bf16 v[54:57], v[196:199], v[160:163], v[54:57]
	v_mfma_f32_16x16x32_bf16 v[50:53], v[204:207], v[160:163], v[50:53]
	v_mfma_f32_16x16x32_bf16 v[38:41], v[196:199], v[172:175], v[38:41]
	v_mfma_f32_16x16x32_bf16 v[34:37], v[204:207], v[172:175], v[34:37]
	v_mfma_f32_16x16x32_bf16 v[14:17], v[196:199], v[180:183], v[14:17]
	v_mfma_f32_16x16x32_bf16 v[10:13], v[204:207], v[180:183], v[10:13]
	v_mfma_f32_16x16x32_bf16 v[6:9], v[196:199], v[188:191], v[6:9]
	v_mfma_f32_16x16x32_bf16 v[2:5], v[204:207], v[188:191], v[2:5]
	s_setprio 1
	s_barrier
; #define PG8_STAGE(bufoff, gbase, voff) do { _Pragma("unroll") for (int _i = 0; _i < 2; ++_i) \
;         __builtin_amdgcn_global_load_lds((const unsigned*)((const char*)(gbase) + (voff)[_i]), (LAS unsigned*)(lds + (bufoff) + ldsw + _i * 8192), 16, 0, 0); } while (0)
; #define PG8_LDA(dst, b, h) do { _Pragma("unroll") for (int m = 0; m < 4; ++m) _Pragma("unroll") for (int k = 0; k < 2; ++k) dst[m][k] = *(const LAS bf16x8*)(lds + PG8_SA(b, h) + aoff + m * 2048 + k * 1024); } while (0)
; #define PG8_LDB(dst, b, h) do { _Pragma("unroll") for (int n = 0; n < 2; ++n) _Pragma("unroll") for (int k = 0; k < 2; ++k) dst[n][k] = *(const LAS bf16x8*)(lds + PG8_SB(b, h) + boff + n * 2048 + k * 1024); } while (0)
; #define PG8_MMA(ai, bj, At, Bt) do { __builtin_amdgcn_s_setprio(1); _Pragma("unroll") for (int m = 0; m < 4; ++m) _Pragma("unroll") for (int n = 0; n < 2; ++n) _Pragma("unroll") for (int k = 0; k < 2; ++k) \
;         acc[ai][bj][m][n] = __builtin_amdgcn_mfma_f32_16x16x32_bf16(Bt[n][k], At[m][k], acc[ai][bj][m][n], 0, 0, 0); __builtin_amdgcn_s_setprio(0); } while (0)
; #define PG8_WAIT_V(n) asm volatile("s_waitcnt vmcnt(" #n ")" ::: "memory")
; #define PG8_WAIT_L(n) asm volatile("s_waitcnt lgkmcnt(" #n ")" ::: "memory")
; #define PG8_BAR __builtin_amdgcn_s_barrier()
; #define PG8_SCHED __builtin_amdgcn_sched_barrier(0)
; template <class Epi, class Sched>
; __device__ __forceinline__ void gemm_phase(LAS unsigned char* lds, const Gemm g, const Sched& S, const Epi& E) {
;     ...
;             PG8_STAGE(PG8_SB(0, 1), b2 + hstep, voffB);
;             PG8_WAIT_V(6); PG8_BAR; PG8_MMA(1, 1, At, B1); PG8_BAR;
;             PG8_LDB(B0, 1, 0); PG8_SCHED; PG8_LDA(At, 1, 0); PG8_STAGE(PG8_SA(0, 1), a2 + hstep, voffA);
;             PG8_WAIT_L(8); PG8_BAR; PG8_WAIT_L(0); PG8_MMA(0, 0, At, B0); PG8_BAR; PG8_SCHED;
;             PG8_LDB(B1, 1, 1); PG8_STAGE(PG8_SB(1, 0), b3, voffB);
;             PG8_BAR; PG8_WAIT_L(0); PG8_MMA(0, 1, At, B1); PG8_BAR;
	s_add_u32 s28, s58, 0x80000
	s_addc_u32 s29, s59, 0
	s_add_i32 s38, s39, s67
	v_lshl_add_u64 v[98:99], s[28:29], 0, v[0:1]
	s_mov_b32 m0, s38
	s_nop 0
	global_load_lds_dwordx4 v[98:99], off
	v_lshl_add_u64 v[98:99], s[28:29], 0, v[146:147]
	s_add_i32 m0, s38, 0x2000
	s_nop 0
	global_load_lds_dwordx4 v[98:99], off
	s_add_u32 s28, s60, 0x80000
	s_addc_u32 s29, s61, 0
	s_mov_b32 m0, s69
	v_lshl_add_u64 v[192:193], s[28:29], 0, v[0:1]
	global_load_lds_dwordx4 v[192:193], off
	v_lshl_add_u64 v[192:193], s[28:29], 0, v[146:147]
	s_mov_b32 m0, s70
	s_nop 0
	global_load_lds_dwordx4 v[192:193], off
	s_add_i32 s38, 0, 0x18000
	v_add_u32_e32 v110, s38, v169
	ds_read_b128 v[98:101], v110
	ds_read_b128 v[102:105], v110 offset:1024
	ds_read_b128 v[106:109], v110 offset:2048
	ds_read_b128 v[110:113], v110 offset:3072
	ds_read_b128 v[152:155], v171 offset:32768
	ds_read_b128 v[160:163], v171 offset:33792
	ds_read_b128 v[164:167], v171 offset:34816
	ds_read_b128 v[172:175], v171 offset:35840
	ds_read_b128 v[176:179], v171 offset:36864
	ds_read_b128 v[180:183], v171 offset:37888
	ds_read_b128 v[184:187], v171 offset:38912
	ds_read_b128 v[188:191], v171 offset:39936
	s_add_i32 s39, 0, 0x1c000
	v_add_u32_e32 v204, s39, v169
	ds_read_b128 v[192:195], v204
	ds_read_b128 v[196:199], v204 offset:1024
	ds_read_b128 v[200:203], v204 offset:2048
	ds_read_b128 v[204:207], v204 offset:3072
	s_waitcnt lgkmcnt(4)
	s_barrier
	s_waitcnt lgkmcnt(0)
	s_setprio 0
	v_mfma_f32_16x16x32_bf16 v[142:145], v[98:101], v[152:155], v[142:145]
	v_mfma_f32_16x16x32_bf16 v[138:141], v[106:109], v[152:155], v[138:141]
	v_mfma_f32_16x16x32_bf16 v[126:129], v[98:101], v[164:167], v[126:129]
	v_mfma_f32_16x16x32_bf16 v[122:125], v[106:109], v[164:167], v[122:125]
	v_mfma_f32_16x16x32_bf16 v[94:97], v[98:101], v[176:179], v[94:97]
	v_mfma_f32_16x16x32_bf16 v[90:93], v[106:109], v[176:179], v[90:93]
	v_mfma_f32_16x16x32_bf16 v[86:89], v[98:101], v[184:187], v[86:89]
	v_mfma_f32_16x16x32_bf16 v[82:85], v[106:109], v[184:187], v[82:85]
	v_mfma_f32_16x16x32_bf16 v[142:145], v[102:105], v[160:163], v[142:145]
	v_mfma_f32_16x16x32_bf16 v[138:141], v[110:113], v[160:163], v[138:141]
	v_mfma_f32_16x16x32_bf16 v[126:129], v[102:105], v[172:175], v[126:129]
	v_mfma_f32_16x16x32_bf16 v[122:125], v[110:113], v[172:175], v[122:125]
	v_mfma_f32_16x16x32_bf16 v[94:97], v[102:105], v[180:183], v[94:97]
	v_mfma_f32_16x16x32_bf16 v[90:93], v[110:113], v[180:183], v[90:93]
	v_mfma_f32_16x16x32_bf16 v[86:89], v[102:105], v[188:191], v[86:89]
	v_mfma_f32_16x16x32_bf16 v[82:85], v[110:113], v[188:191], v[82:85]
	v_mfma_f32_16x16x32_bf16 v[134:137], v[192:195], v[152:155], v[134:137]
	v_mfma_f32_16x16x32_bf16 v[130:133], v[200:203], v[152:155], v[130:133]
	v_mfma_f32_16x16x32_bf16 v[118:121], v[192:195], v[164:167], v[118:121]
	v_mfma_f32_16x16x32_bf16 v[114:117], v[200:203], v[164:167], v[114:117]
	v_mfma_f32_16x16x32_bf16 v[78:81], v[192:195], v[176:179], v[78:81]
	v_mfma_f32_16x16x32_bf16 v[74:77], v[200:203], v[176:179], v[74:77]
	v_mfma_f32_16x16x32_bf16 v[70:73], v[192:195], v[184:187], v[70:73]
	v_mfma_f32_16x16x32_bf16 v[66:69], v[200:203], v[184:187], v[66:69]
	v_mfma_f32_16x16x32_bf16 v[134:137], v[196:199], v[160:163], v[134:137]
	v_mfma_f32_16x16x32_bf16 v[130:133], v[204:207], v[160:163], v[130:133]
	v_mfma_f32_16x16x32_bf16 v[118:121], v[196:199], v[172:175], v[118:121]
	v_mfma_f32_16x16x32_bf16 v[114:117], v[204:207], v[172:175], v[114:117]
	v_mfma_f32_16x16x32_bf16 v[78:81], v[196:199], v[180:183], v[78:81]
	v_mfma_f32_16x16x32_bf16 v[74:77], v[204:207], v[180:183], v[74:77]
	v_mfma_f32_16x16x32_bf16 v[70:73], v[196:199], v[188:191], v[70:73]
	v_mfma_f32_16x16x32_bf16 v[66:69], v[204:207], v[188:191], v[66:69]
	s_setprio 1
	s_barrier
; #define PG8_STAGE(bufoff, gbase, voff) do { _Pragma("unroll") for (int _i = 0; _i < 2; ++_i) \
;         __builtin_amdgcn_global_load_lds((const unsigned*)((const char*)(gbase) + (voff)[_i]), (LAS unsigned*)(lds + (bufoff) + ldsw + _i * 8192), 16, 0, 0); } while (0)
; #define PG8_LDA(dst, b, h) do { _Pragma("unroll") for (int m = 0; m < 4; ++m) _Pragma("unroll") for (int k = 0; k < 2; ++k) dst[m][k] = *(const LAS bf16x8*)(lds + PG8_SA(b, h) + aoff + m * 2048 + k * 1024); } while (0)
; #define PG8_LDB(dst, b, h) do { _Pragma("unroll") for (int n = 0; n < 2; ++n) _Pragma("unroll") for (int k = 0; k < 2; ++k) dst[n][k] = *(const LAS bf16x8*)(lds + PG8_SB(b, h) + boff + n * 2048 + k * 1024); } while (0)
; #define PG8_MMA(ai, bj, At, Bt) do { __builtin_amdgcn_s_setprio(1); _Pragma("unroll") for (int m = 0; m < 4; ++m) _Pragma("unroll") for (int n = 0; n < 2; ++n) _Pragma("unroll") for (int k = 0; k < 2; ++k) \
;         acc[ai][bj][m][n] = __builtin_amdgcn_mfma_f32_16x16x32_bf16(Bt[n][k], At[m][k], acc[ai][bj][m][n], 0, 0, 0); __builtin_amdgcn_s_setprio(0); } while (0)
; #define PG8_WAIT_V(n) asm volatile("s_waitcnt vmcnt(" #n ")" ::: "memory")
; #define PG8_WAIT_L(n) asm volatile("s_waitcnt lgkmcnt(" #n ")" ::: "memory")
; #define PG8_BAR __builtin_amdgcn_s_barrier()
; #define PG8_SCHED __builtin_amdgcn_sched_barrier(0)
; template <class Epi, class Sched>
; __device__ __forceinline__ void gemm_phase(LAS unsigned char* lds, const Gemm g, const Sched& S, const Epi& E) {
;     ...
;             PG8_LDB(B1, 1, 1); PG8_STAGE(PG8_SB(1, 0), b3, voffB);
;             PG8_BAR; PG8_WAIT_L(0); PG8_MMA(0, 1, At, B1); PG8_BAR;
;             PG8_LDA(At, 1, 1); PG8_STAGE(PG8_SA(1, 0), a3, voffA);
;             PG8_BAR; PG8_WAIT_L(0); PG8_MMA(1, 0, At, B0); PG8_BAR; PG8_SCHED;
;             PG8_STAGE(PG8_SB(1, 1), b3 + hstep, voffB);
;             PG8_WAIT_V(6); PG8_BAR; PG8_MMA(1, 1, At, B1); PG8_BAR;
;         }
;         E(acc, cur, wr, wc, fr, fq);
;         if (!has_next) break;
	s_add_i32 s28, s38, s67
	v_lshl_add_u64 v[156:157], v[156:157], 0, s[36:37]
	s_mov_b32 m0, s28
	s_nop 0
	global_load_lds_dwordx4 v[156:157], off
	v_lshl_add_u64 v[156:157], v[210:211], 0, s[36:37]
	s_add_i32 m0, s28, 0x2000
	s_nop 0
	global_load_lds_dwordx4 v[156:157], off
	s_mov_b32 m0, s72
	v_lshl_add_u64 v[156:157], v[212:213], 0, s[36:37]
	global_load_lds_dwordx4 v[156:157], off
	v_lshl_add_u64 v[156:157], v[214:215], 0, s[36:37]
	s_mov_b32 m0, s73
	s_nop 0
	global_load_lds_dwordx4 v[156:157], off
	ds_read_b128 v[152:155], v171 offset:49152
	ds_read_b128 v[160:163], v171 offset:50176
	ds_read_b128 v[164:167], v171 offset:51200
	ds_read_b128 v[172:175], v171 offset:52224
	ds_read_b128 v[176:179], v171 offset:53248
	ds_read_b128 v[180:183], v171 offset:54272
	ds_read_b128 v[184:187], v171 offset:55296
	ds_read_b128 v[188:191], v171 offset:56320
	s_waitcnt vmcnt(4)
	s_waitcnt lgkmcnt(0)
	s_barrier
	s_setprio 0
	v_mfma_f32_16x16x32_bf16 v[62:65], v[98:101], v[152:155], v[62:65]
	v_mfma_f32_16x16x32_bf16 v[58:61], v[106:109], v[152:155], v[58:61]
	v_mfma_f32_16x16x32_bf16 v[46:49], v[98:101], v[164:167], v[46:49]
	v_mfma_f32_16x16x32_bf16 v[42:45], v[106:109], v[164:167], v[42:45]
	v_mfma_f32_16x16x32_bf16 v[30:33], v[98:101], v[176:179], v[30:33]
	v_mfma_f32_16x16x32_bf16 v[26:29], v[106:109], v[176:179], v[26:29]
	v_mfma_f32_16x16x32_bf16 v[22:25], v[98:101], v[184:187], v[22:25]
	v_mfma_f32_16x16x32_bf16 v[18:21], v[106:109], v[184:187], v[18:21]
	v_mfma_f32_16x16x32_bf16 v[62:65], v[102:105], v[160:163], v[62:65]
	v_mfma_f32_16x16x32_bf16 v[58:61], v[110:113], v[160:163], v[58:61]
	v_mfma_f32_16x16x32_bf16 v[46:49], v[102:105], v[172:175], v[46:49]
	v_mfma_f32_16x16x32_bf16 v[42:45], v[110:113], v[172:175], v[42:45]
	v_mfma_f32_16x16x32_bf16 v[30:33], v[102:105], v[180:183], v[30:33]
	v_mfma_f32_16x16x32_bf16 v[26:29], v[110:113], v[180:183], v[26:29]
	v_mfma_f32_16x16x32_bf16 v[22:25], v[102:105], v[188:191], v[22:25]
	v_mfma_f32_16x16x32_bf16 v[18:21], v[110:113], v[188:191], v[18:21]
	s_add_u32 s28, s58, 0x80080
	s_addc_u32 s29, s59, 0
	s_add_i32 s38, s39, s67
	v_lshl_add_u64 v[98:99], s[28:29], 0, v[0:1]
	s_mov_b32 m0, s38
	s_nop 0
	global_load_lds_dwordx4 v[98:99], off
	v_lshl_add_u64 v[98:99], s[28:29], 0, v[146:147]
	s_add_i32 m0, s38, 0x2000
	s_nop 0
	global_load_lds_dwordx4 v[98:99], off
	v_mfma_f32_16x16x32_bf16 v[54:57], v[192:195], v[152:155], v[54:57]
	v_mfma_f32_16x16x32_bf16 v[50:53], v[200:203], v[152:155], v[50:53]
	v_mfma_f32_16x16x32_bf16 v[38:41], v[192:195], v[164:167], v[38:41]
	v_mfma_f32_16x16x32_bf16 v[34:37], v[200:203], v[164:167], v[34:37]
	v_mfma_f32_16x16x32_bf16 v[14:17], v[192:195], v[176:179], v[14:17]
	v_mfma_f32_16x16x32_bf16 v[10:13], v[200:203], v[176:179], v[10:13]
	v_mfma_f32_16x16x32_bf16 v[6:9], v[192:195], v[184:187], v[6:9]
	v_mfma_f32_16x16x32_bf16 v[2:5], v[200:203], v[184:187], v[2:5]
	v_mfma_f32_16x16x32_bf16 v[54:57], v[196:199], v[160:163], v[54:57]
	v_mfma_f32_16x16x32_bf16 v[50:53], v[204:207], v[160:163], v[50:53]
	v_mfma_f32_16x16x32_bf16 v[38:41], v[196:199], v[172:175], v[38:41]
	v_mfma_f32_16x16x32_bf16 v[34:37], v[204:207], v[172:175], v[34:37]
	v_mfma_f32_16x16x32_bf16 v[14:17], v[196:199], v[180:183], v[14:17]
	v_mfma_f32_16x16x32_bf16 v[10:13], v[204:207], v[180:183], v[10:13]
	v_mfma_f32_16x16x32_bf16 v[6:9], v[196:199], v[188:191], v[6:9]
	v_mfma_f32_16x16x32_bf16 v[2:5], v[204:207], v[188:191], v[2:5]
	s_setprio 1
	s_add_i32 s81, s81, 2
	s_add_u32 s79, s79, 0x100
	s_addc_u32 s80, s80, 0
	s_cmp_gt_u32 s81, 29
	s_mov_b64 s[28:29], s[56:57]
	s_barrier
	s_cbranch_scc0 .LBB0_99
	s_cmp_lt_i32 s8, 64
	s_cselect_b64 s[58:59], -1, 0
	s_cmp_gt_i32 s8, 63
	s_cbranch_scc0 .LBB0_90
	s_mov_b64 s[60:61], 0x18000
	s_mov_b64 s[28:29], s[46:47]
	s_mov_b64 s[56:57], s[24:25]
	s_branch .LBB0_91

; #define PG8_STAGE(bufoff, gbase, voff) do { _Pragma("unroll") for (int _i = 0; _i < 2; ++_i) \
;         __builtin_amdgcn_global_load_lds((const unsigned*)((const char*)(gbase) + (voff)[_i]), (LAS unsigned*)(lds + (bufoff) + ldsw + _i * 8192), 16, 0, 0); } while (0)
; #define PG8_LDA(dst, b, h) do { _Pragma("unroll") for (int m = 0; m < 4; ++m) _Pragma("unroll") for (int k = 0; k < 2; ++k) dst[m][k] = *(const LAS bf16x8*)(lds + PG8_SA(b, h) + aoff + m * 2048 + k * 1024); } while (0)
; #define PG8_LDB(dst, b, h) do { _Pragma("unroll") for (int n = 0; n < 2; ++n) _Pragma("unroll") for (int k = 0; k < 2; ++k) dst[n][k] = *(const LAS bf16x8*)(lds + PG8_SB(b, h) + boff + n * 2048 + k * 1024); } while (0)
; #define PG8_MMA(ai, bj, At, Bt) do { __builtin_amdgcn_s_setprio(1); _Pragma("unroll") for (int m = 0; m < 4; ++m) _Pragma("unroll") for (int n = 0; n < 2; ++n) _Pragma("unroll") for (int k = 0; k < 2; ++k) \
;         acc[ai][bj][m][n] = __builtin_amdgcn_mfma_f32_16x16x32_bf16(Bt[n][k], At[m][k], acc[ai][bj][m][n], 0, 0, 0); __builtin_amdgcn_s_setprio(0); } while (0)
; #define PG8_WAIT_V(n) asm volatile("s_waitcnt vmcnt(" #n ")" ::: "memory")
; #define PG8_WAIT_L(n) asm volatile("s_waitcnt lgkmcnt(" #n ")" ::: "memory")
; template <class Epi, class Sched>
; __device__ __forceinline__ void gemm_phase(LAS unsigned char* lds, const Gemm g, const Sched& S, const Epi& E) {
;     ...
;         for (int t = 0; t < nt; t += 2) {
;             const bool last = (t == nt - 2);
;             const char* a1 = cA + (size_t)(t + 1) * kstep;
;             const char* a2 = last ? nA : cA + (size_t)(t + 2) * kstep; const char* b2 = last ? nB : cB + (size_t)(t + 2) * kstep;
;             const char* a3 = a2 + kstep; const char* b3 = b2 + kstep;
;             PG8_LDB(B0, 0, 0); PG8_SCHED; PG8_LDA(At, 0, 0); PG8_STAGE(PG8_SA(1, 1), a1 + hstep, voffA);
;             PG8_WAIT_L(8); PG8_BAR; PG8_WAIT_L(0); PG8_MMA(0, 0, At, B0); PG8_BAR; PG8_SCHED;
;             PG8_LDB(B1, 0, 1); PG8_STAGE(PG8_SB(0, 0), b2, voffB);
;             PG8_BAR; PG8_WAIT_L(0); PG8_MMA(0, 1, At, B1); PG8_BAR;
;             PG8_LDA(At, 0, 1); PG8_STAGE(PG8_SA(0, 0), a2, voffA);
;             PG8_BAR; PG8_WAIT_L(0); PG8_MMA(1, 0, At, B0); PG8_BAR; PG8_SCHED;
;             PG8_STAGE(PG8_SB(0, 1), b2 + hstep, voffB);
;             PG8_WAIT_V(6); PG8_BAR; PG8_MMA(1, 1, At, B1); PG8_BAR;
.LBB0_113:
	s_add_u32 s54, s52, 0x100
	s_addc_u32 s55, s53, 0
	s_cmp_eq_u32 s73, 4
	s_cselect_b32 s59, s11, s55
	s_cselect_b32 s58, s29, s54
	s_cselect_b32 s57, s41, s72
	s_cselect_b32 s56, s45, s71
	v_lshl_add_u64 v[156:157], s[52:53], 0, v[134:135]
	s_add_i32 m0, s25, 0xc000
	s_nop 0
	global_load_lds_dwordx4 v[156:157], off
	v_lshl_add_u64 v[156:157], s[52:53], 0, v[132:133]
	s_add_i32 m0, s25, 0xe000
	s_nop 0
	global_load_lds_dwordx4 v[156:157], off
	s_add_i32 s38, 0, 0x10000
	v_add_u32_e32 v152, s38, v137
	ds_read_b128 v[140:143], v152
	ds_read_b128 v[144:147], v152 offset:1024
	ds_read_b128 v[148:151], v152 offset:2048
	ds_read_b128 v[152:155], v152 offset:3072
	ds_read_b128 v[160:163], v139
	ds_read_b128 v[164:167], v139 offset:1024
	ds_read_b128 v[168:171], v139 offset:2048
	ds_read_b128 v[172:175], v139 offset:3072
	ds_read_b128 v[176:179], v139 offset:4096
	ds_read_b128 v[180:183], v139 offset:5120
	ds_read_b128 v[184:187], v139 offset:6144
	ds_read_b128 v[188:191], v139 offset:7168
	s_add_i32 s52, 0, 0x14000
	v_add_u32_e32 v156, s52, v137
	ds_read_b128 v[192:195], v156
	ds_read_b128 v[196:199], v156 offset:1024
	ds_read_b128 v[200:203], v156 offset:2048
	ds_read_b128 v[204:207], v156 offset:3072
	s_waitcnt lgkmcnt(4)
	s_barrier
	s_waitcnt lgkmcnt(0)
	s_setprio 0
	v_mfma_f32_16x16x32_bf16 v[126:129], v[140:143], v[160:163], v[126:129]
	v_mfma_f32_16x16x32_bf16 v[122:125], v[148:151], v[160:163], v[122:125]
	v_mfma_f32_16x16x32_bf16 v[118:121], v[140:143], v[168:171], v[118:121]
	v_mfma_f32_16x16x32_bf16 v[114:117], v[148:151], v[168:171], v[114:117]
	v_mfma_f32_16x16x32_bf16 v[106:109], v[140:143], v[176:179], v[106:109]
	v_mfma_f32_16x16x32_bf16 v[98:101], v[148:151], v[176:179], v[98:101]
	v_mfma_f32_16x16x32_bf16 v[90:93], v[140:143], v[184:187], v[90:93]
	v_mfma_f32_16x16x32_bf16 v[82:85], v[148:151], v[184:187], v[82:85]
	v_mfma_f32_16x16x32_bf16 v[126:129], v[144:147], v[164:167], v[126:129]
	v_mfma_f32_16x16x32_bf16 v[122:125], v[152:155], v[164:167], v[122:125]
	v_mfma_f32_16x16x32_bf16 v[118:121], v[144:147], v[172:175], v[118:121]
	v_mfma_f32_16x16x32_bf16 v[114:117], v[152:155], v[172:175], v[114:117]
	v_mfma_f32_16x16x32_bf16 v[106:109], v[144:147], v[180:183], v[106:109]
	v_mfma_f32_16x16x32_bf16 v[98:101], v[152:155], v[180:183], v[98:101]
	v_mfma_f32_16x16x32_bf16 v[90:93], v[144:147], v[188:191], v[90:93]
	v_mfma_f32_16x16x32_bf16 v[82:85], v[152:155], v[188:191], v[82:85]
	v_mfma_f32_16x16x32_bf16 v[110:113], v[192:195], v[160:163], v[110:113]
	v_mfma_f32_16x16x32_bf16 v[102:105], v[200:203], v[160:163], v[102:105]
	v_mfma_f32_16x16x32_bf16 v[94:97], v[192:195], v[168:171], v[94:97]
	v_mfma_f32_16x16x32_bf16 v[86:89], v[200:203], v[168:171], v[86:89]
	v_mfma_f32_16x16x32_bf16 v[78:81], v[192:195], v[176:179], v[78:81]
	v_mfma_f32_16x16x32_bf16 v[74:77], v[200:203], v[176:179], v[74:77]
	v_mfma_f32_16x16x32_bf16 v[70:73], v[192:195], v[184:187], v[70:73]
	v_mfma_f32_16x16x32_bf16 v[66:69], v[200:203], v[184:187], v[66:69]
	v_mfma_f32_16x16x32_bf16 v[110:113], v[196:199], v[164:167], v[110:113]
	v_mfma_f32_16x16x32_bf16 v[102:105], v[204:207], v[164:167], v[102:105]
	v_mfma_f32_16x16x32_bf16 v[94:97], v[196:199], v[172:175], v[94:97]
	v_mfma_f32_16x16x32_bf16 v[86:89], v[204:207], v[172:175], v[86:89]
	v_mfma_f32_16x16x32_bf16 v[78:81], v[196:199], v[180:183], v[78:81]
	v_mfma_f32_16x16x32_bf16 v[74:77], v[204:207], v[180:183], v[74:77]
	v_mfma_f32_16x16x32_bf16 v[70:73], v[196:199], v[188:191], v[70:73]
	v_mfma_f32_16x16x32_bf16 v[66:69], v[204:207], v[188:191], v[66:69]
	s_setprio 1
	s_barrier
	s_add_i32 s38, s38, s65
	v_lshl_add_u64 v[156:157], s[56:57], 0, v[0:1]
	s_mov_b32 m0, s38
	v_lshl_add_u64 v[210:211], s[56:57], 0, v[130:131]
	global_load_lds_dwordx4 v[156:157], off
	s_add_i32 m0, s38, 0x2000
	s_nop 0
	global_load_lds_dwordx4 v[210:211], off
	s_mov_b32 m0, s25
	v_lshl_add_u64 v[212:213], s[58:59], 0, v[0:1]
	global_load_lds_dwordx4 v[212:213], off
	v_lshl_add_u64 v[214:215], s[58:59], 0, v[130:131]
	s_mov_b32 m0, s27
	s_nop 0
	global_load_lds_dwordx4 v[214:215], off
	ds_read_b128 v[160:163], v139 offset:16384
	ds_read_b128 v[164:167], v139 offset:17408
	ds_read_b128 v[168:171], v139 offset:18432
	ds_read_b128 v[172:175], v139 offset:19456
	ds_read_b128 v[176:179], v139 offset:20480
	ds_read_b128 v[180:183], v139 offset:21504
	ds_read_b128 v[184:187], v139 offset:22528
	ds_read_b128 v[188:191], v139 offset:23552
	s_waitcnt vmcnt(4)
	s_waitcnt lgkmcnt(0)
	s_barrier
	s_setprio 0
	v_mfma_f32_16x16x32_bf16 v[62:65], v[140:143], v[160:163], v[62:65]
	v_mfma_f32_16x16x32_bf16 v[58:61], v[148:151], v[160:163], v[58:61]
	v_mfma_f32_16x16x32_bf16 v[54:57], v[140:143], v[168:171], v[54:57]
	v_mfma_f32_16x16x32_bf16 v[50:53], v[148:151], v[168:171], v[50:53]
	v_mfma_f32_16x16x32_bf16 v[38:41], v[140:143], v[176:179], v[38:41]
	v_mfma_f32_16x16x32_bf16 v[34:37], v[148:151], v[176:179], v[34:37]
	v_mfma_f32_16x16x32_bf16 v[22:25], v[140:143], v[184:187], v[22:25]
	v_mfma_f32_16x16x32_bf16 v[18:21], v[148:151], v[184:187], v[18:21]
	v_mfma_f32_16x16x32_bf16 v[62:65], v[144:147], v[164:167], v[62:65]
	v_mfma_f32_16x16x32_bf16 v[58:61], v[152:155], v[164:167], v[58:61]
	v_mfma_f32_16x16x32_bf16 v[54:57], v[144:147], v[172:175], v[54:57]
	v_mfma_f32_16x16x32_bf16 v[50:53], v[152:155], v[172:175], v[50:53]
	v_mfma_f32_16x16x32_bf16 v[38:41], v[144:147], v[180:183], v[38:41]
	v_mfma_f32_16x16x32_bf16 v[34:37], v[152:155], v[180:183], v[34:37]
	v_mfma_f32_16x16x32_bf16 v[22:25], v[144:147], v[188:191], v[22:25]
	v_mfma_f32_16x16x32_bf16 v[18:21], v[152:155], v[188:191], v[18:21]
	v_mfma_f32_16x16x32_bf16 v[46:49], v[192:195], v[160:163], v[46:49]
	v_mfma_f32_16x16x32_bf16 v[42:45], v[200:203], v[160:163], v[42:45]
	v_mfma_f32_16x16x32_bf16 v[30:33], v[192:195], v[168:171], v[30:33]
	v_mfma_f32_16x16x32_bf16 v[26:29], v[200:203], v[168:171], v[26:29]
	v_mfma_f32_16x16x32_bf16 v[14:17], v[192:195], v[176:179], v[14:17]
	v_mfma_f32_16x16x32_bf16 v[10:13], v[200:203], v[176:179], v[10:13]
	v_mfma_f32_16x16x32_bf16 v[6:9], v[192:195], v[184:187], v[6:9]
	v_mfma_f32_16x16x32_bf16 v[2:5], v[200:203], v[184:187], v[2:5]
	v_mfma_f32_16x16x32_bf16 v[46:49], v[196:199], v[164:167], v[46:49]
	v_mfma_f32_16x16x32_bf16 v[42:45], v[204:207], v[164:167], v[42:45]
	v_mfma_f32_16x16x32_bf16 v[30:33], v[196:199], v[172:175], v[30:33]
	v_mfma_f32_16x16x32_bf16 v[26:29], v[204:207], v[172:175], v[26:29]
	v_mfma_f32_16x16x32_bf16 v[14:17], v[196:199], v[180:183], v[14:17]
	v_mfma_f32_16x16x32_bf16 v[10:13], v[204:207], v[180:183], v[10:13]
	v_mfma_f32_16x16x32_bf16 v[6:9], v[196:199], v[188:191], v[6:9]
	v_mfma_f32_16x16x32_bf16 v[2:5], v[204:207], v[188:191], v[2:5]
	s_setprio 1
	s_barrier
; #define PG8_STAGE(bufoff, gbase, voff) do { _Pragma("unroll") for (int _i = 0; _i < 2; ++_i) \
;         __builtin_amdgcn_global_load_lds((const unsigned*)((const char*)(gbase) + (voff)[_i]), (LAS unsigned*)(lds + (bufoff) + ldsw + _i * 8192), 16, 0, 0); } while (0)
; #define PG8_LDA(dst, b, h) do { _Pragma("unroll") for (int m = 0; m < 4; ++m) _Pragma("unroll") for (int k = 0; k < 2; ++k) dst[m][k] = *(const LAS bf16x8*)(lds + PG8_SA(b, h) + aoff + m * 2048 + k * 1024); } while (0)
; #define PG8_LDB(dst, b, h) do { _Pragma("unroll") for (int n = 0; n < 2; ++n) _Pragma("unroll") for (int k = 0; k < 2; ++k) dst[n][k] = *(const LAS bf16x8*)(lds + PG8_SB(b, h) + boff + n * 2048 + k * 1024); } while (0)
; #define PG8_MMA(ai, bj, At, Bt) do { __builtin_amdgcn_s_setprio(1); _Pragma("unroll") for (int m = 0; m < 4; ++m) _Pragma("unroll") for (int n = 0; n < 2; ++n) _Pragma("unroll") for (int k = 0; k < 2; ++k) \
;         acc[ai][bj][m][n] = __builtin_amdgcn_mfma_f32_16x16x32_bf16(Bt[n][k], At[m][k], acc[ai][bj][m][n], 0, 0, 0); __builtin_amdgcn_s_setprio(0); } while (0)
; #define PG8_WAIT_V(n) asm volatile("s_waitcnt vmcnt(" #n ")" ::: "memory")
; #define PG8_WAIT_L(n) asm volatile("s_waitcnt lgkmcnt(" #n ")" ::: "memory")
; #define PG8_BAR __builtin_amdgcn_s_barrier()
; #define PG8_SCHED __builtin_amdgcn_sched_barrier(0)
; template <class Epi, class Sched>
; __device__ __forceinline__ void gemm_phase(LAS unsigned char* lds, const Gemm g, const Sched& S, const Epi& E) {
;     ...
;             PG8_STAGE(PG8_SB(0, 1), b2 + hstep, voffB);
;             PG8_WAIT_V(6); PG8_BAR; PG8_MMA(1, 1, At, B1); PG8_BAR;
;             PG8_LDB(B0, 1, 0); PG8_SCHED; PG8_LDA(At, 1, 0); PG8_STAGE(PG8_SA(0, 1), a2 + hstep, voffA);
;             PG8_WAIT_L(8); PG8_BAR; PG8_WAIT_L(0); PG8_MMA(0, 0, At, B0); PG8_BAR; PG8_SCHED;
;             PG8_LDB(B1, 1, 1); PG8_STAGE(PG8_SB(1, 0), b3, voffB);
;             PG8_BAR; PG8_WAIT_L(0); PG8_MMA(0, 1, At, B1); PG8_BAR;
;             PG8_LDA(At, 1, 1); PG8_STAGE(PG8_SA(1, 0), a3, voffA);
;             PG8_BAR; PG8_WAIT_L(0); PG8_MMA(1, 0, At, B0); PG8_BAR; PG8_SCHED;
	s_add_u32 s38, s56, 0x80000
	s_addc_u32 s39, s57, 0
	s_add_i32 s52, s52, s65
	v_lshl_add_u64 v[140:141], s[38:39], 0, v[0:1]
	s_mov_b32 m0, s52
	s_nop 0
	global_load_lds_dwordx4 v[140:141], off
	v_lshl_add_u64 v[140:141], s[38:39], 0, v[130:131]
	s_add_i32 m0, s52, 0x2000
	s_nop 0
	global_load_lds_dwordx4 v[140:141], off
	s_add_u32 s38, s58, 0x80000
	s_addc_u32 s39, s59, 0
	s_mov_b32 m0, s66
	v_lshl_add_u64 v[192:193], s[38:39], 0, v[0:1]
	global_load_lds_dwordx4 v[192:193], off
	v_lshl_add_u64 v[192:193], s[38:39], 0, v[130:131]
	s_mov_b32 m0, s67
	s_nop 0
	global_load_lds_dwordx4 v[192:193], off
	s_add_i32 s52, 0, 0x18000
	v_add_u32_e32 v152, s52, v137
	ds_read_b128 v[140:143], v152
	ds_read_b128 v[144:147], v152 offset:1024
	ds_read_b128 v[148:151], v152 offset:2048
	ds_read_b128 v[152:155], v152 offset:3072
	ds_read_b128 v[160:163], v139 offset:32768
	ds_read_b128 v[164:167], v139 offset:33792
	ds_read_b128 v[168:171], v139 offset:34816
	ds_read_b128 v[172:175], v139 offset:35840
	ds_read_b128 v[176:179], v139 offset:36864
	ds_read_b128 v[180:183], v139 offset:37888
	ds_read_b128 v[184:187], v139 offset:38912
	ds_read_b128 v[188:191], v139 offset:39936
	s_add_i32 s53, 0, 0x1c000
	v_add_u32_e32 v204, s53, v137
	ds_read_b128 v[192:195], v204
	ds_read_b128 v[196:199], v204 offset:1024
	ds_read_b128 v[200:203], v204 offset:2048
	ds_read_b128 v[204:207], v204 offset:3072
	s_waitcnt lgkmcnt(4)
	s_barrier
	s_waitcnt lgkmcnt(0)
	s_setprio 0
	v_mfma_f32_16x16x32_bf16 v[126:129], v[140:143], v[160:163], v[126:129]
	v_mfma_f32_16x16x32_bf16 v[122:125], v[148:151], v[160:163], v[122:125]
	v_mfma_f32_16x16x32_bf16 v[118:121], v[140:143], v[168:171], v[118:121]
	v_mfma_f32_16x16x32_bf16 v[114:117], v[148:151], v[168:171], v[114:117]
	v_mfma_f32_16x16x32_bf16 v[106:109], v[140:143], v[176:179], v[106:109]
	v_mfma_f32_16x16x32_bf16 v[98:101], v[148:151], v[176:179], v[98:101]
	v_mfma_f32_16x16x32_bf16 v[90:93], v[140:143], v[184:187], v[90:93]
	v_mfma_f32_16x16x32_bf16 v[82:85], v[148:151], v[184:187], v[82:85]
	v_mfma_f32_16x16x32_bf16 v[126:129], v[144:147], v[164:167], v[126:129]
	v_mfma_f32_16x16x32_bf16 v[122:125], v[152:155], v[164:167], v[122:125]
	v_mfma_f32_16x16x32_bf16 v[118:121], v[144:147], v[172:175], v[118:121]
	v_mfma_f32_16x16x32_bf16 v[114:117], v[152:155], v[172:175], v[114:117]
	v_mfma_f32_16x16x32_bf16 v[106:109], v[144:147], v[180:183], v[106:109]
	v_mfma_f32_16x16x32_bf16 v[98:101], v[152:155], v[180:183], v[98:101]
	v_mfma_f32_16x16x32_bf16 v[90:93], v[144:147], v[188:191], v[90:93]
	v_mfma_f32_16x16x32_bf16 v[82:85], v[152:155], v[188:191], v[82:85]
	v_mfma_f32_16x16x32_bf16 v[110:113], v[192:195], v[160:163], v[110:113]
	v_mfma_f32_16x16x32_bf16 v[102:105], v[200:203], v[160:163], v[102:105]
	v_mfma_f32_16x16x32_bf16 v[94:97], v[192:195], v[168:171], v[94:97]
	v_mfma_f32_16x16x32_bf16 v[86:89], v[200:203], v[168:171], v[86:89]
	v_mfma_f32_16x16x32_bf16 v[78:81], v[192:195], v[176:179], v[78:81]
	v_mfma_f32_16x16x32_bf16 v[74:77], v[200:203], v[176:179], v[74:77]
	v_mfma_f32_16x16x32_bf16 v[70:73], v[192:195], v[184:187], v[70:73]
	v_mfma_f32_16x16x32_bf16 v[66:69], v[200:203], v[184:187], v[66:69]
	v_mfma_f32_16x16x32_bf16 v[110:113], v[196:199], v[164:167], v[110:113]
	v_mfma_f32_16x16x32_bf16 v[102:105], v[204:207], v[164:167], v[102:105]
	v_mfma_f32_16x16x32_bf16 v[94:97], v[196:199], v[172:175], v[94:97]
	v_mfma_f32_16x16x32_bf16 v[86:89], v[204:207], v[172:175], v[86:89]
	v_mfma_f32_16x16x32_bf16 v[78:81], v[196:199], v[180:183], v[78:81]
	v_mfma_f32_16x16x32_bf16 v[74:77], v[204:207], v[180:183], v[74:77]
	v_mfma_f32_16x16x32_bf16 v[70:73], v[196:199], v[188:191], v[70:73]
	v_mfma_f32_16x16x32_bf16 v[66:69], v[204:207], v[188:191], v[66:69]
	s_setprio 1
	s_barrier
	s_add_i32 s38, s52, s65
	v_lshl_add_u64 v[156:157], v[156:157], 0, s[36:37]
	s_mov_b32 m0, s38
	s_nop 0
	global_load_lds_dwordx4 v[156:157], off
	v_lshl_add_u64 v[156:157], v[210:211], 0, s[36:37]
	s_add_i32 m0, s38, 0x2000
	s_nop 0
	global_load_lds_dwordx4 v[156:157], off
	s_mov_b32 m0, s68
	v_lshl_add_u64 v[156:157], v[212:213], 0, s[36:37]
	global_load_lds_dwordx4 v[156:157], off
	v_lshl_add_u64 v[156:157], v[214:215], 0, s[36:37]
	s_mov_b32 m0, s69
	s_nop 0
	global_load_lds_dwordx4 v[156:157], off
	ds_read_b128 v[160:163], v139 offset:49152
	ds_read_b128 v[164:167], v139 offset:50176
	ds_read_b128 v[168:171], v139 offset:51200
	ds_read_b128 v[172:175], v139 offset:52224
	ds_read_b128 v[176:179], v139 offset:53248
	ds_read_b128 v[180:183], v139 offset:54272
	ds_read_b128 v[184:187], v139 offset:55296
	ds_read_b128 v[188:191], v139 offset:56320
	s_waitcnt vmcnt(4)
	s_waitcnt lgkmcnt(0)
	s_barrier
; #define PG8_STAGE(bufoff, gbase, voff) do { _Pragma("unroll") for (int _i = 0; _i < 2; ++_i) \
;         __builtin_amdgcn_global_load_lds((const unsigned*)((const char*)(gbase) + (voff)[_i]), (LAS unsigned*)(lds + (bufoff) + ldsw + _i * 8192), 16, 0, 0); } while (0)
; #define PG8_LDA(dst, b, h) do { _Pragma("unroll") for (int m = 0; m < 4; ++m) _Pragma("unroll") for (int k = 0; k < 2; ++k) dst[m][k] = *(const LAS bf16x8*)(lds + PG8_SA(b, h) + aoff + m * 2048 + k * 1024); } while (0)
; #define PG8_WAIT_V(n) asm volatile("s_waitcnt vmcnt(" #n ")" ::: "memory")
; #define PG8_WAIT_L(n) asm volatile("s_waitcnt lgkmcnt(" #n ")" ::: "memory")
;     __device__ __forceinline__ void operator()(const f32x4 (&acc)[2][2][4][2], const Unit& u, int wr, int wc, int fr, int fq) const {
;         const int row0 = u.pm * BM + wr * 64 + fr, col0 = u.pn * BM + wc * 32 + 4 * fq;
;         float* base = part + (size_t)u.ks * Mp * ldc;
; #pragma unroll
;         for (int ai = 0; ai < 2; ++ai)
; #pragma unroll
;             for (int m = 0; m < 4; ++m) { float* rowp = base + (size_t)(row0 + ai * HALF + m * 16) * ldc + col0;
; #pragma unroll
;                 for (int bj = 0; bj < 2; ++bj)
; #pragma unroll
;                     for (int n = 0; n < 2; ++n) *(f32x4*)(rowp + bj * HALF + n * 16) = acc[ai][bj][m][n]; }
;     }
; template <class Epi, class Sched>
; __device__ __forceinline__ void gemm_phase(LAS unsigned char* lds, const Gemm g, const Sched& S, const Epi& E) {
;     ...
;             PG8_LDB(B1, 1, 1); PG8_STAGE(PG8_SB(1, 0), b3, voffB);
;             PG8_BAR; PG8_WAIT_L(0); PG8_MMA(0, 1, At, B1); PG8_BAR;
;             PG8_LDA(At, 1, 1); PG8_STAGE(PG8_SA(1, 0), a3, voffA);
;             PG8_BAR; PG8_WAIT_L(0); PG8_MMA(1, 0, At, B0); PG8_BAR; PG8_SCHED;
;             PG8_STAGE(PG8_SB(1, 1), b3 + hstep, voffB);
;             PG8_WAIT_V(6); PG8_BAR; PG8_MMA(1, 1, At, B1); PG8_BAR;
;         }
;         E(acc, cur, wr, wc, fr, fq);
;         if (!has_next) break;
; #pragma unroll
;         for (int a = 0; a < 2; ++a)
; #pragma unroll
;             for (int b = 0; b < 2; ++b)
; #pragma unroll
;                 for (int m = 0; m < 4; ++m)
; #pragma unroll
;                     for (int n = 0; n < 2; ++n) acc[a][b][m][n] = (f32x4){0.f, 0.f, 0.f, 0.f};
;         cur = nxt; cA = nA; cB = nB; ++ui;
;     }
;     PG8_WAIT_V(0);
;     if (wr == 0) PG8_BAR;
;     PG8_BAR;
	s_setprio 0
	v_mfma_f32_16x16x32_bf16 v[62:65], v[140:143], v[160:163], v[62:65]
	v_mfma_f32_16x16x32_bf16 v[58:61], v[148:151], v[160:163], v[58:61]
	v_mfma_f32_16x16x32_bf16 v[54:57], v[140:143], v[168:171], v[54:57]
	v_mfma_f32_16x16x32_bf16 v[50:53], v[148:151], v[168:171], v[50:53]
	v_mfma_f32_16x16x32_bf16 v[38:41], v[140:143], v[176:179], v[38:41]
	v_mfma_f32_16x16x32_bf16 v[34:37], v[148:151], v[176:179], v[34:37]
	v_mfma_f32_16x16x32_bf16 v[22:25], v[140:143], v[184:187], v[22:25]
	v_mfma_f32_16x16x32_bf16 v[18:21], v[148:151], v[184:187], v[18:21]
	v_mfma_f32_16x16x32_bf16 v[62:65], v[144:147], v[164:167], v[62:65]
	v_mfma_f32_16x16x32_bf16 v[58:61], v[152:155], v[164:167], v[58:61]
	v_mfma_f32_16x16x32_bf16 v[54:57], v[144:147], v[172:175], v[54:57]
	v_mfma_f32_16x16x32_bf16 v[50:53], v[152:155], v[172:175], v[50:53]
	v_mfma_f32_16x16x32_bf16 v[38:41], v[144:147], v[180:183], v[38:41]
	v_mfma_f32_16x16x32_bf16 v[34:37], v[152:155], v[180:183], v[34:37]
	v_mfma_f32_16x16x32_bf16 v[22:25], v[144:147], v[188:191], v[22:25]
	v_mfma_f32_16x16x32_bf16 v[18:21], v[152:155], v[188:191], v[18:21]
	s_add_u32 s38, s56, 0x80080
	s_addc_u32 s39, s57, 0
	s_add_i32 s52, s53, s65
	v_lshl_add_u64 v[140:141], s[38:39], 0, v[0:1]
	s_mov_b32 m0, s52
	s_nop 0
	global_load_lds_dwordx4 v[140:141], off
	v_lshl_add_u64 v[140:141], s[38:39], 0, v[130:131]
	s_add_i32 m0, s52, 0x2000
	s_nop 0
	global_load_lds_dwordx4 v[140:141], off
	v_mfma_f32_16x16x32_bf16 v[46:49], v[192:195], v[160:163], v[46:49]
	v_mfma_f32_16x16x32_bf16 v[42:45], v[200:203], v[160:163], v[42:45]
	v_mfma_f32_16x16x32_bf16 v[30:33], v[192:195], v[168:171], v[30:33]
	v_mfma_f32_16x16x32_bf16 v[26:29], v[200:203], v[168:171], v[26:29]
	v_mfma_f32_16x16x32_bf16 v[14:17], v[192:195], v[176:179], v[14:17]
	v_mfma_f32_16x16x32_bf16 v[10:13], v[200:203], v[176:179], v[10:13]
	v_mfma_f32_16x16x32_bf16 v[6:9], v[192:195], v[184:187], v[6:9]
	v_mfma_f32_16x16x32_bf16 v[2:5], v[200:203], v[184:187], v[2:5]
	v_mfma_f32_16x16x32_bf16 v[46:49], v[196:199], v[164:167], v[46:49]
	v_mfma_f32_16x16x32_bf16 v[42:45], v[204:207], v[164:167], v[42:45]
	v_mfma_f32_16x16x32_bf16 v[30:33], v[196:199], v[172:175], v[30:33]
	v_mfma_f32_16x16x32_bf16 v[26:29], v[204:207], v[172:175], v[26:29]
	v_mfma_f32_16x16x32_bf16 v[14:17], v[196:199], v[180:183], v[14:17]
	v_mfma_f32_16x16x32_bf16 v[10:13], v[204:207], v[180:183], v[10:13]
	v_mfma_f32_16x16x32_bf16 v[6:9], v[196:199], v[188:191], v[6:9]
	v_mfma_f32_16x16x32_bf16 v[2:5], v[204:207], v[188:191], v[2:5]
	s_setprio 1
	s_add_i32 s73, s73, 2
	s_add_u32 s71, s71, 0x100
	s_addc_u32 s72, s72, 0
	s_cmp_gt_u32 s73, 5
	s_mov_b64 s[52:53], s[54:55]
	s_barrier
	s_cbranch_scc0 .LBB0_113
	s_ashr_i32 s11, s10, 31
	s_lshl_b64 s[10:11], s[10:11], 24
	v_lshl_or_b32 v140, s26, 8, v138
	s_add_u32 s10, s8, s10
	v_lshl_add_u32 v142, s24, 8, v136
	s_addc_u32 s11, s9, s11
	v_ashrrev_i32_e32 v141, 31, v140
	v_ashrrev_i32_e32 v143, 31, v142
	v_lshl_add_u64 v[140:141], v[140:141], 2, s[10:11]
	v_lshlrev_b64 v[144:145], 13, v[142:143]
	v_lshl_add_u64 v[144:145], v[140:141], 0, v[144:145]
	global_store_dwordx4 v[144:145], v[126:129], off
	global_store_dwordx4 v[144:145], v[122:125], off offset:64
	global_store_dwordx4 v[144:145], v[110:113], off offset:512
	global_store_dwordx4 v[144:145], v[102:105], off offset:576
	s_mov_b64 s[10:11], 0x100000
	s_mov_b32 s26, s40
	v_or_b32_e32 v102, 16, v142
	v_ashrrev_i32_e32 v103, 31, v102
	v_lshlrev_b64 v[102:103], 13, v[102:103]
	v_lshl_add_u64 v[102:103], v[140:141], 0, v[102:103]
	global_store_dwordx4 v[102:103], v[118:121], off
	global_store_dwordx4 v[102:103], v[114:117], off offset:64
	global_store_dwordx4 v[102:103], v[94:97], off offset:512
	global_store_dwordx4 v[102:103], v[86:89], off offset:576
	s_mov_b32 s24, s44
	s_mov_b64 s[54:55], s[50:51]
	v_or_b32_e32 v86, 32, v142
	v_ashrrev_i32_e32 v87, 31, v86
	v_lshlrev_b64 v[86:87], 13, v[86:87]
	v_lshl_add_u64 v[86:87], v[140:141], 0, v[86:87]
	global_store_dwordx4 v[86:87], v[106:109], off
	global_store_dwordx4 v[86:87], v[98:101], off offset:64
	global_store_dwordx4 v[86:87], v[78:81], off offset:512
	global_store_dwordx4 v[86:87], v[74:77], off offset:576
	s_mov_b64 s[52:53], s[48:49]
	s_nop 0
	v_or_b32_e32 v74, 48, v142
	v_ashrrev_i32_e32 v75, 31, v74
	v_lshlrev_b64 v[74:75], 13, v[74:75]
	v_lshl_add_u64 v[74:75], v[140:141], 0, v[74:75]
	global_store_dwordx4 v[74:75], v[90:93], off
	global_store_dwordx4 v[74:75], v[82:85], off offset:64
	global_store_dwordx4 v[74:75], v[70:73], off offset:512
	global_store_dwordx4 v[74:75], v[66:69], off offset:576
	s_nop 1
	v_add_co_u32_e32 v68, vcc, s93, v144
	v_lshl_add_u64 v[66:67], v[144:145], 0, s[10:11]
	s_nop 0
	v_addc_co_u32_e32 v69, vcc, 0, v145, vcc
	s_mov_b64 s[10:11], 0x120000
	global_store_dwordx4 v[68:69], v[62:65], off
	global_store_dwordx4 v[66:67], v[58:61], off offset:64
	global_store_dwordx4 v[66:67], v[46:49], off offset:512
	global_store_dwordx4 v[66:67], v[42:45], off offset:576
	s_nop 1
	v_lshl_add_u64 v[42:43], v[144:145], 0, s[10:11]
	s_mov_b32 s10, 0x120000
	v_add_co_u32_e32 v44, vcc, s10, v144
	s_mov_b64 s[10:11], 0x140000
	s_nop 0
	v_addc_co_u32_e32 v45, vcc, 0, v145, vcc
	global_store_dwordx4 v[44:45], v[54:57], off
	global_store_dwordx4 v[42:43], v[50:53], off offset:64
	global_store_dwordx4 v[42:43], v[30:33], off offset:512
	global_store_dwordx4 v[42:43], v[26:29], off offset:576
	s_nop 1
	v_lshl_add_u64 v[26:27], v[144:145], 0, s[10:11]
	s_mov_b32 s10, 0x140000
	v_add_co_u32_e32 v28, vcc, s10, v144
	s_mov_b64 s[10:11], 0x160000
	s_nop 0
	v_addc_co_u32_e32 v29, vcc, 0, v145, vcc
	global_store_dwordx4 v[28:29], v[38:41], off
	global_store_dwordx4 v[26:27], v[34:37], off offset:64
	global_store_dwordx4 v[26:27], v[14:17], off offset:512
	global_store_dwordx4 v[26:27], v[10:13], off offset:576
	s_nop 1
	v_add_co_u32_e32 v12, vcc, 0x160000, v144
	v_lshl_add_u64 v[10:11], v[144:145], 0, s[10:11]
	s_nop 0
	v_addc_co_u32_e32 v13, vcc, 0, v145, vcc
	s_and_b64 vcc, exec, s[46:47]
	s_mov_b32 s10, s28
	global_store_dwordx4 v[12:13], v[22:25], off
	global_store_dwordx4 v[10:11], v[18:21], off offset:64
	global_store_dwordx4 v[10:11], v[6:9], off offset:512
	global_store_dwordx4 v[10:11], v[2:5], off offset:576
	s_cbranch_vccz .LBB0_110
	s_waitcnt vmcnt(0)
	s_cmpk_gt_u32 s60, 0xff
	s_cbranch_scc1 .LBB0_117
	s_barrier

; #define PG8_STAGE(bufoff, gbase, voff) do { _Pragma("unroll") for (int _i = 0; _i < 2; ++_i) \
;         __builtin_amdgcn_global_load_lds((const unsigned*)((const char*)(gbase) + (voff)[_i]), (LAS unsigned*)(lds + (bufoff) + ldsw + _i * 8192), 16, 0, 0); } while (0)
; #define PG8_LDA(dst, b, h) do { _Pragma("unroll") for (int m = 0; m < 4; ++m) _Pragma("unroll") for (int k = 0; k < 2; ++k) dst[m][k] = *(const LAS bf16x8*)(lds + PG8_SA(b, h) + aoff + m * 2048 + k * 1024); } while (0)
; #define PG8_LDB(dst, b, h) do { _Pragma("unroll") for (int n = 0; n < 2; ++n) _Pragma("unroll") for (int k = 0; k < 2; ++k) dst[n][k] = *(const LAS bf16x8*)(lds + PG8_SB(b, h) + boff + n * 2048 + k * 1024); } while (0)
; #define PG8_MMA(ai, bj, At, Bt) do { __builtin_amdgcn_s_setprio(1); _Pragma("unroll") for (int m = 0; m < 4; ++m) _Pragma("unroll") for (int n = 0; n < 2; ++n) _Pragma("unroll") for (int k = 0; k < 2; ++k) \
;         acc[ai][bj][m][n] = __builtin_amdgcn_mfma_f32_16x16x32_bf16(Bt[n][k], At[m][k], acc[ai][bj][m][n], 0, 0, 0); __builtin_amdgcn_s_setprio(0); } while (0)
; #define PG8_WAIT_V(n) asm volatile("s_waitcnt vmcnt(" #n ")" ::: "memory")
; #define PG8_WAIT_L(n) asm volatile("s_waitcnt lgkmcnt(" #n ")" ::: "memory")
; template <class Epi, class Sched>
; __device__ __forceinline__ void gemm_phase(LAS unsigned char* lds, const Gemm g, const Sched& S, const Epi& E) {
;     ...
;         for (int t = 0; t < nt; t += 2) {
;             const bool last = (t == nt - 2);
;             const char* a1 = cA + (size_t)(t + 1) * kstep;
;             const char* a2 = last ? nA : cA + (size_t)(t + 2) * kstep; const char* b2 = last ? nB : cB + (size_t)(t + 2) * kstep;
;             const char* a3 = a2 + kstep; const char* b3 = b2 + kstep;
;             PG8_LDB(B0, 0, 0); PG8_SCHED; PG8_LDA(At, 0, 0); PG8_STAGE(PG8_SA(1, 1), a1 + hstep, voffA);
;             PG8_WAIT_L(8); PG8_BAR; PG8_WAIT_L(0); PG8_MMA(0, 0, At, B0); PG8_BAR; PG8_SCHED;
;             PG8_LDB(B1, 0, 1); PG8_STAGE(PG8_SB(0, 0), b2, voffB);
;             PG8_BAR; PG8_WAIT_L(0); PG8_MMA(0, 1, At, B1); PG8_BAR;
;             PG8_LDA(At, 0, 1); PG8_STAGE(PG8_SA(0, 0), a2, voffA);
;             PG8_BAR; PG8_WAIT_L(0); PG8_MMA(1, 0, At, B0); PG8_BAR; PG8_SCHED;
;             PG8_STAGE(PG8_SB(0, 1), b2 + hstep, voffB);
;             PG8_WAIT_V(6); PG8_BAR; PG8_MMA(1, 1, At, B1); PG8_BAR;
.LBB0_354:
	s_add_u32 s38, s50, 0xfff80080
	s_addc_u32 s39, s51, -1
	s_cmp_eq_u32 s70, 28
	s_cselect_b32 s55, s9, s39
	s_cselect_b32 s54, s66, s38
	s_cselect_b32 s53, s43, s69
	s_cselect_b32 s52, s67, s68
	v_lshl_add_u64 v[156:157], s[50:51], 0, v[138:139]
	s_add_i32 m0, s29, 0xc000
	s_nop 0
	global_load_lds_dwordx4 v[156:157], off
	v_lshl_add_u64 v[156:157], s[50:51], 0, v[136:137]
	s_add_i32 m0, s29, 0xe000
	s_nop 0
	global_load_lds_dwordx4 v[156:157], off
	s_add_i32 s71, 0, 0x10000
	v_add_u32_e32 v156, s71, v145
	ds_read_b128 v[140:143], v156
	ds_read_b128 v[148:151], v156 offset:1024
	ds_read_b128 v[152:155], v156 offset:2048
	ds_read_b128 v[160:163], v156 offset:3072
	ds_read_b128 v[164:167], v147
	ds_read_b128 v[168:171], v147 offset:1024
	ds_read_b128 v[172:175], v147 offset:2048
	ds_read_b128 v[176:179], v147 offset:3072
	ds_read_b128 v[180:183], v147 offset:4096
	ds_read_b128 v[184:187], v147 offset:5120
	ds_read_b128 v[188:191], v147 offset:6144
	ds_read_b128 v[192:195], v147 offset:7168
	s_add_i32 s38, 0, 0x14000
	v_add_u32_e32 v156, s38, v145
	ds_read_b128 v[196:199], v156
	ds_read_b128 v[200:203], v156 offset:1024
	ds_read_b128 v[204:207], v156 offset:2048
	ds_read_b128 v[210:213], v156 offset:3072
	s_waitcnt lgkmcnt(4)
	s_barrier
	s_waitcnt lgkmcnt(0)
	s_setprio 0
	v_mfma_f32_16x16x32_bf16 v[126:129], v[140:143], v[164:167], v[126:129]
	v_mfma_f32_16x16x32_bf16 v[122:125], v[152:155], v[164:167], v[122:125]
	v_mfma_f32_16x16x32_bf16 v[118:121], v[140:143], v[172:175], v[118:121]
	v_mfma_f32_16x16x32_bf16 v[110:113], v[152:155], v[172:175], v[110:113]
	v_mfma_f32_16x16x32_bf16 v[102:105], v[140:143], v[180:183], v[102:105]
	v_mfma_f32_16x16x32_bf16 v[94:97], v[152:155], v[180:183], v[94:97]
	v_mfma_f32_16x16x32_bf16 v[86:89], v[140:143], v[188:191], v[86:89]
	v_mfma_f32_16x16x32_bf16 v[78:81], v[152:155], v[188:191], v[78:81]
	v_mfma_f32_16x16x32_bf16 v[126:129], v[148:151], v[168:171], v[126:129]
	v_mfma_f32_16x16x32_bf16 v[122:125], v[160:163], v[168:171], v[122:125]
	v_mfma_f32_16x16x32_bf16 v[118:121], v[148:151], v[176:179], v[118:121]
	v_mfma_f32_16x16x32_bf16 v[110:113], v[160:163], v[176:179], v[110:113]
	v_mfma_f32_16x16x32_bf16 v[102:105], v[148:151], v[184:187], v[102:105]
	v_mfma_f32_16x16x32_bf16 v[94:97], v[160:163], v[184:187], v[94:97]
	v_mfma_f32_16x16x32_bf16 v[86:89], v[148:151], v[192:195], v[86:89]
	v_mfma_f32_16x16x32_bf16 v[78:81], v[160:163], v[192:195], v[78:81]
	v_mfma_f32_16x16x32_bf16 v[114:117], v[196:199], v[164:167], v[114:117]
	v_mfma_f32_16x16x32_bf16 v[106:109], v[204:207], v[164:167], v[106:109]
	v_mfma_f32_16x16x32_bf16 v[98:101], v[196:199], v[172:175], v[98:101]
	v_mfma_f32_16x16x32_bf16 v[90:93], v[204:207], v[172:175], v[90:93]
	v_mfma_f32_16x16x32_bf16 v[82:85], v[196:199], v[180:183], v[82:85]
	v_mfma_f32_16x16x32_bf16 v[74:77], v[204:207], v[180:183], v[74:77]
	v_mfma_f32_16x16x32_bf16 v[70:73], v[196:199], v[188:191], v[70:73]
	v_mfma_f32_16x16x32_bf16 v[66:69], v[204:207], v[188:191], v[66:69]
	v_mfma_f32_16x16x32_bf16 v[114:117], v[200:203], v[168:171], v[114:117]
	v_mfma_f32_16x16x32_bf16 v[106:109], v[210:213], v[168:171], v[106:109]
	v_mfma_f32_16x16x32_bf16 v[98:101], v[200:203], v[176:179], v[98:101]
	v_mfma_f32_16x16x32_bf16 v[90:93], v[210:213], v[176:179], v[90:93]
	v_mfma_f32_16x16x32_bf16 v[82:85], v[200:203], v[184:187], v[82:85]
	v_mfma_f32_16x16x32_bf16 v[74:77], v[210:213], v[184:187], v[74:77]
	v_mfma_f32_16x16x32_bf16 v[70:73], v[200:203], v[192:195], v[70:73]
	v_mfma_f32_16x16x32_bf16 v[66:69], v[210:213], v[192:195], v[66:69]
	s_setprio 1
	s_barrier
	s_add_i32 s39, s71, s56
	v_lshl_add_u64 v[156:157], s[52:53], 0, v[0:1]
	s_mov_b32 m0, s39
	v_lshl_add_u64 v[214:215], s[52:53], 0, v[134:135]
	global_load_lds_dwordx4 v[156:157], off
	s_add_i32 m0, s39, 0x2000
	s_nop 0
	global_load_lds_dwordx4 v[214:215], off
	s_mov_b32 m0, s29
	v_lshl_add_u64 v[216:217], s[54:55], 0, v[130:131]
	global_load_lds_dwordx4 v[216:217], off
	v_lshl_add_u64 v[224:225], s[54:55], 0, v[132:133]
	s_mov_b32 m0, s41
	s_nop 0
	global_load_lds_dwordx4 v[224:225], off
	ds_read_b128 v[164:167], v147 offset:16384
	ds_read_b128 v[168:171], v147 offset:17408
	ds_read_b128 v[172:175], v147 offset:18432
	ds_read_b128 v[176:179], v147 offset:19456
	ds_read_b128 v[180:183], v147 offset:20480
	ds_read_b128 v[184:187], v147 offset:21504
	ds_read_b128 v[188:191], v147 offset:22528
	ds_read_b128 v[192:195], v147 offset:23552
	s_waitcnt vmcnt(4)
	s_waitcnt lgkmcnt(0)
	s_barrier
	s_setprio 0
	v_mfma_f32_16x16x32_bf16 v[62:65], v[140:143], v[164:167], v[62:65]
	v_mfma_f32_16x16x32_bf16 v[58:61], v[152:155], v[164:167], v[58:61]
	v_mfma_f32_16x16x32_bf16 v[54:57], v[140:143], v[172:175], v[54:57]
	v_mfma_f32_16x16x32_bf16 v[46:49], v[152:155], v[172:175], v[46:49]
	v_mfma_f32_16x16x32_bf16 v[38:41], v[140:143], v[180:183], v[38:41]
	v_mfma_f32_16x16x32_bf16 v[30:33], v[152:155], v[180:183], v[30:33]
	v_mfma_f32_16x16x32_bf16 v[22:25], v[140:143], v[188:191], v[22:25]
	v_mfma_f32_16x16x32_bf16 v[14:17], v[152:155], v[188:191], v[14:17]
	v_mfma_f32_16x16x32_bf16 v[62:65], v[148:151], v[168:171], v[62:65]
	v_mfma_f32_16x16x32_bf16 v[58:61], v[160:163], v[168:171], v[58:61]
	v_mfma_f32_16x16x32_bf16 v[54:57], v[148:151], v[176:179], v[54:57]
	v_mfma_f32_16x16x32_bf16 v[46:49], v[160:163], v[176:179], v[46:49]
	v_mfma_f32_16x16x32_bf16 v[38:41], v[148:151], v[184:187], v[38:41]
	v_mfma_f32_16x16x32_bf16 v[30:33], v[160:163], v[184:187], v[30:33]
	v_mfma_f32_16x16x32_bf16 v[22:25], v[148:151], v[192:195], v[22:25]
	v_mfma_f32_16x16x32_bf16 v[14:17], v[160:163], v[192:195], v[14:17]
	v_mfma_f32_16x16x32_bf16 v[50:53], v[196:199], v[164:167], v[50:53]
	v_mfma_f32_16x16x32_bf16 v[42:45], v[204:207], v[164:167], v[42:45]
	v_mfma_f32_16x16x32_bf16 v[34:37], v[196:199], v[172:175], v[34:37]
	v_mfma_f32_16x16x32_bf16 v[26:29], v[204:207], v[172:175], v[26:29]
	v_mfma_f32_16x16x32_bf16 v[18:21], v[196:199], v[180:183], v[18:21]
	v_mfma_f32_16x16x32_bf16 v[10:13], v[204:207], v[180:183], v[10:13]
	v_mfma_f32_16x16x32_bf16 v[6:9], v[196:199], v[188:191], v[6:9]
	v_mfma_f32_16x16x32_bf16 v[2:5], v[204:207], v[188:191], v[2:5]
	v_mfma_f32_16x16x32_bf16 v[50:53], v[200:203], v[168:171], v[50:53]
	v_mfma_f32_16x16x32_bf16 v[42:45], v[210:213], v[168:171], v[42:45]
	v_mfma_f32_16x16x32_bf16 v[34:37], v[200:203], v[176:179], v[34:37]
	v_mfma_f32_16x16x32_bf16 v[26:29], v[210:213], v[176:179], v[26:29]
	v_mfma_f32_16x16x32_bf16 v[18:21], v[200:203], v[184:187], v[18:21]
	v_mfma_f32_16x16x32_bf16 v[10:13], v[210:213], v[184:187], v[10:13]
	v_mfma_f32_16x16x32_bf16 v[6:9], v[200:203], v[192:195], v[6:9]
	v_mfma_f32_16x16x32_bf16 v[2:5], v[210:213], v[192:195], v[2:5]
	s_setprio 1
	s_barrier
; #define PG8_STAGE(bufoff, gbase, voff) do { _Pragma("unroll") for (int _i = 0; _i < 2; ++_i) \
;         __builtin_amdgcn_global_load_lds((const unsigned*)((const char*)(gbase) + (voff)[_i]), (LAS unsigned*)(lds + (bufoff) + ldsw + _i * 8192), 16, 0, 0); } while (0)
; #define PG8_LDA(dst, b, h) do { _Pragma("unroll") for (int m = 0; m < 4; ++m) _Pragma("unroll") for (int k = 0; k < 2; ++k) dst[m][k] = *(const LAS bf16x8*)(lds + PG8_SA(b, h) + aoff + m * 2048 + k * 1024); } while (0)
; #define PG8_LDB(dst, b, h) do { _Pragma("unroll") for (int n = 0; n < 2; ++n) _Pragma("unroll") for (int k = 0; k < 2; ++k) dst[n][k] = *(const LAS bf16x8*)(lds + PG8_SB(b, h) + boff + n * 2048 + k * 1024); } while (0)
; #define PG8_MMA(ai, bj, At, Bt) do { __builtin_amdgcn_s_setprio(1); _Pragma("unroll") for (int m = 0; m < 4; ++m) _Pragma("unroll") for (int n = 0; n < 2; ++n) _Pragma("unroll") for (int k = 0; k < 2; ++k) \
;         acc[ai][bj][m][n] = __builtin_amdgcn_mfma_f32_16x16x32_bf16(Bt[n][k], At[m][k], acc[ai][bj][m][n], 0, 0, 0); __builtin_amdgcn_s_setprio(0); } while (0)
; #define PG8_WAIT_V(n) asm volatile("s_waitcnt vmcnt(" #n ")" ::: "memory")
; #define PG8_WAIT_L(n) asm volatile("s_waitcnt lgkmcnt(" #n ")" ::: "memory")
; #define PG8_BAR __builtin_amdgcn_s_barrier()
; #define PG8_SCHED __builtin_amdgcn_sched_barrier(0)
; template <class Epi, class Sched>
; __device__ __forceinline__ void gemm_phase(LAS unsigned char* lds, const Gemm g, const Sched& S, const Epi& E) {
;     ...
;             PG8_STAGE(PG8_SB(0, 1), b2 + hstep, voffB);
;             PG8_WAIT_V(6); PG8_BAR; PG8_MMA(1, 1, At, B1); PG8_BAR;
;             PG8_LDB(B0, 1, 0); PG8_SCHED; PG8_LDA(At, 1, 0); PG8_STAGE(PG8_SA(0, 1), a2 + hstep, voffA);
;             PG8_WAIT_L(8); PG8_BAR; PG8_WAIT_L(0); PG8_MMA(0, 0, At, B0); PG8_BAR; PG8_SCHED;
;             PG8_LDB(B1, 1, 1); PG8_STAGE(PG8_SB(1, 0), b3, voffB);
;             PG8_BAR; PG8_WAIT_L(0); PG8_MMA(0, 1, At, B1); PG8_BAR;
;             PG8_LDA(At, 1, 1); PG8_STAGE(PG8_SA(1, 0), a3, voffA);
;             PG8_BAR; PG8_WAIT_L(0); PG8_MMA(1, 0, At, B0); PG8_BAR; PG8_SCHED;
	s_add_u32 s72, s52, 0x80000
	s_addc_u32 s73, s53, 0
	s_add_i32 s38, s38, s56
	v_lshl_add_u64 v[140:141], s[72:73], 0, v[0:1]
	s_mov_b32 m0, s38
	s_nop 0
	global_load_lds_dwordx4 v[140:141], off
	v_lshl_add_u64 v[140:141], s[72:73], 0, v[134:135]
	s_add_i32 m0, s38, 0x2000
	s_nop 0
	global_load_lds_dwordx4 v[140:141], off
	s_add_u32 s54, s54, 0x80000
	s_addc_u32 s55, s55, 0
	s_mov_b32 m0, s57
	v_lshl_add_u64 v[196:197], s[54:55], 0, v[130:131]
	global_load_lds_dwordx4 v[196:197], off
	v_lshl_add_u64 v[196:197], s[54:55], 0, v[132:133]
	s_mov_b32 m0, s58
	s_nop 0
	global_load_lds_dwordx4 v[196:197], off
	s_add_i32 s38, 0, 0x18000
	v_add_u32_e32 v160, s38, v145
	ds_read_b128 v[140:143], v160
	ds_read_b128 v[148:151], v160 offset:1024
	ds_read_b128 v[152:155], v160 offset:2048
	ds_read_b128 v[160:163], v160 offset:3072
	ds_read_b128 v[164:167], v147 offset:32768
	ds_read_b128 v[168:171], v147 offset:33792
	ds_read_b128 v[172:175], v147 offset:34816
	ds_read_b128 v[176:179], v147 offset:35840
	ds_read_b128 v[180:183], v147 offset:36864
	ds_read_b128 v[184:187], v147 offset:37888
	ds_read_b128 v[188:191], v147 offset:38912
	ds_read_b128 v[192:195], v147 offset:39936
	s_add_i32 s39, 0, 0x1c000
	v_add_u32_e32 v210, s39, v145
	ds_read_b128 v[196:199], v210
	ds_read_b128 v[200:203], v210 offset:1024
	ds_read_b128 v[204:207], v210 offset:2048
	ds_read_b128 v[210:213], v210 offset:3072
	s_waitcnt lgkmcnt(4)
	s_barrier
	s_waitcnt lgkmcnt(0)
	s_setprio 0
	v_mfma_f32_16x16x32_bf16 v[126:129], v[140:143], v[164:167], v[126:129]
	v_mfma_f32_16x16x32_bf16 v[122:125], v[152:155], v[164:167], v[122:125]
	v_mfma_f32_16x16x32_bf16 v[118:121], v[140:143], v[172:175], v[118:121]
	v_mfma_f32_16x16x32_bf16 v[110:113], v[152:155], v[172:175], v[110:113]
	v_mfma_f32_16x16x32_bf16 v[102:105], v[140:143], v[180:183], v[102:105]
	v_mfma_f32_16x16x32_bf16 v[94:97], v[152:155], v[180:183], v[94:97]
	v_mfma_f32_16x16x32_bf16 v[86:89], v[140:143], v[188:191], v[86:89]
	v_mfma_f32_16x16x32_bf16 v[78:81], v[152:155], v[188:191], v[78:81]
	v_mfma_f32_16x16x32_bf16 v[126:129], v[148:151], v[168:171], v[126:129]
	v_mfma_f32_16x16x32_bf16 v[122:125], v[160:163], v[168:171], v[122:125]
	v_mfma_f32_16x16x32_bf16 v[118:121], v[148:151], v[176:179], v[118:121]
	v_mfma_f32_16x16x32_bf16 v[110:113], v[160:163], v[176:179], v[110:113]
	v_mfma_f32_16x16x32_bf16 v[102:105], v[148:151], v[184:187], v[102:105]
	v_mfma_f32_16x16x32_bf16 v[94:97], v[160:163], v[184:187], v[94:97]
	v_mfma_f32_16x16x32_bf16 v[86:89], v[148:151], v[192:195], v[86:89]
	v_mfma_f32_16x16x32_bf16 v[78:81], v[160:163], v[192:195], v[78:81]
	v_mfma_f32_16x16x32_bf16 v[114:117], v[196:199], v[164:167], v[114:117]
	v_mfma_f32_16x16x32_bf16 v[106:109], v[204:207], v[164:167], v[106:109]
	v_mfma_f32_16x16x32_bf16 v[98:101], v[196:199], v[172:175], v[98:101]
	v_mfma_f32_16x16x32_bf16 v[90:93], v[204:207], v[172:175], v[90:93]
	v_mfma_f32_16x16x32_bf16 v[82:85], v[196:199], v[180:183], v[82:85]
	v_mfma_f32_16x16x32_bf16 v[74:77], v[204:207], v[180:183], v[74:77]
	v_mfma_f32_16x16x32_bf16 v[70:73], v[196:199], v[188:191], v[70:73]
	v_mfma_f32_16x16x32_bf16 v[66:69], v[204:207], v[188:191], v[66:69]
	v_mfma_f32_16x16x32_bf16 v[114:117], v[200:203], v[168:171], v[114:117]
	v_mfma_f32_16x16x32_bf16 v[106:109], v[210:213], v[168:171], v[106:109]
	v_mfma_f32_16x16x32_bf16 v[98:101], v[200:203], v[176:179], v[98:101]
	v_mfma_f32_16x16x32_bf16 v[90:93], v[210:213], v[176:179], v[90:93]
	v_mfma_f32_16x16x32_bf16 v[82:85], v[200:203], v[184:187], v[82:85]
	v_mfma_f32_16x16x32_bf16 v[74:77], v[210:213], v[184:187], v[74:77]
	v_mfma_f32_16x16x32_bf16 v[70:73], v[200:203], v[192:195], v[70:73]
	v_mfma_f32_16x16x32_bf16 v[66:69], v[210:213], v[192:195], v[66:69]
	s_setprio 1
	s_barrier
	s_add_i32 s38, s38, s56
	v_lshl_add_u64 v[156:157], v[156:157], 0, s[36:37]
	s_mov_b32 m0, s38
	s_nop 0
	global_load_lds_dwordx4 v[156:157], off
	v_lshl_add_u64 v[156:157], v[214:215], 0, s[36:37]
	s_add_i32 m0, s38, 0x2000
	s_nop 0
	global_load_lds_dwordx4 v[156:157], off
	s_mov_b32 m0, s59
	v_lshl_add_u64 v[156:157], v[216:217], 0, s[36:37]
	global_load_lds_dwordx4 v[156:157], off
	v_lshl_add_u64 v[156:157], v[224:225], 0, s[36:37]
	s_mov_b32 m0, s60
	s_nop 0
	global_load_lds_dwordx4 v[156:157], off
	ds_read_b128 v[164:167], v147 offset:49152
	ds_read_b128 v[168:171], v147 offset:50176
	ds_read_b128 v[172:175], v147 offset:51200
	ds_read_b128 v[176:179], v147 offset:52224
	ds_read_b128 v[180:183], v147 offset:53248
	ds_read_b128 v[184:187], v147 offset:54272
	ds_read_b128 v[188:191], v147 offset:55296
	ds_read_b128 v[192:195], v147 offset:56320
	s_waitcnt vmcnt(4)
	s_waitcnt lgkmcnt(0)
	s_barrier
; #define PG8_STAGE(bufoff, gbase, voff) do { _Pragma("unroll") for (int _i = 0; _i < 2; ++_i) \
;         __builtin_amdgcn_global_load_lds((const unsigned*)((const char*)(gbase) + (voff)[_i]), (LAS unsigned*)(lds + (bufoff) + ldsw + _i * 8192), 16, 0, 0); } while (0)
; #define PG8_LDA(dst, b, h) do { _Pragma("unroll") for (int m = 0; m < 4; ++m) _Pragma("unroll") for (int k = 0; k < 2; ++k) dst[m][k] = *(const LAS bf16x8*)(lds + PG8_SA(b, h) + aoff + m * 2048 + k * 1024); } while (0)
; #define PG8_LDB(dst, b, h) do { _Pragma("unroll") for (int n = 0; n < 2; ++n) _Pragma("unroll") for (int k = 0; k < 2; ++k) dst[n][k] = *(const LAS bf16x8*)(lds + PG8_SB(b, h) + boff + n * 2048 + k * 1024); } while (0)
; #define PG8_MMA(ai, bj, At, Bt) do { __builtin_amdgcn_s_setprio(1); _Pragma("unroll") for (int m = 0; m < 4; ++m) _Pragma("unroll") for (int n = 0; n < 2; ++n) _Pragma("unroll") for (int k = 0; k < 2; ++k) \
;         acc[ai][bj][m][n] = __builtin_amdgcn_mfma_f32_16x16x32_bf16(Bt[n][k], At[m][k], acc[ai][bj][m][n], 0, 0, 0); __builtin_amdgcn_s_setprio(0); } while (0)
; #define PG8_WAIT_V(n) asm volatile("s_waitcnt vmcnt(" #n ")" ::: "memory")
; #define PG8_WAIT_L(n) asm volatile("s_waitcnt lgkmcnt(" #n ")" ::: "memory")
; #define PG8_BAR __builtin_amdgcn_s_barrier()
; #define PG8_SCHED __builtin_amdgcn_sched_barrier(0)
; template <class Epi, class Sched>
; __device__ __forceinline__ void gemm_phase(LAS unsigned char* lds, const Gemm g, const Sched& S, const Epi& E) {
;     ...
;             PG8_LDB(B1, 1, 1); PG8_STAGE(PG8_SB(1, 0), b3, voffB);
;             PG8_BAR; PG8_WAIT_L(0); PG8_MMA(0, 1, At, B1); PG8_BAR;
;             PG8_LDA(At, 1, 1); PG8_STAGE(PG8_SA(1, 0), a3, voffA);
;             PG8_BAR; PG8_WAIT_L(0); PG8_MMA(1, 0, At, B0); PG8_BAR; PG8_SCHED;
;             PG8_STAGE(PG8_SB(1, 1), b3 + hstep, voffB);
;             PG8_WAIT_V(6); PG8_BAR; PG8_MMA(1, 1, At, B1); PG8_BAR;
;         }
	s_setprio 0
	v_mfma_f32_16x16x32_bf16 v[62:65], v[140:143], v[164:167], v[62:65]
	v_mfma_f32_16x16x32_bf16 v[58:61], v[152:155], v[164:167], v[58:61]
	v_mfma_f32_16x16x32_bf16 v[54:57], v[140:143], v[172:175], v[54:57]
	v_mfma_f32_16x16x32_bf16 v[46:49], v[152:155], v[172:175], v[46:49]
	v_mfma_f32_16x16x32_bf16 v[38:41], v[140:143], v[180:183], v[38:41]
	v_mfma_f32_16x16x32_bf16 v[30:33], v[152:155], v[180:183], v[30:33]
	v_mfma_f32_16x16x32_bf16 v[22:25], v[140:143], v[188:191], v[22:25]
	v_mfma_f32_16x16x32_bf16 v[14:17], v[152:155], v[188:191], v[14:17]
	v_mfma_f32_16x16x32_bf16 v[62:65], v[148:151], v[168:171], v[62:65]
	v_mfma_f32_16x16x32_bf16 v[58:61], v[160:163], v[168:171], v[58:61]
	v_mfma_f32_16x16x32_bf16 v[54:57], v[148:151], v[176:179], v[54:57]
	v_mfma_f32_16x16x32_bf16 v[46:49], v[160:163], v[176:179], v[46:49]
	v_mfma_f32_16x16x32_bf16 v[38:41], v[148:151], v[184:187], v[38:41]
	v_mfma_f32_16x16x32_bf16 v[30:33], v[160:163], v[184:187], v[30:33]
	v_mfma_f32_16x16x32_bf16 v[22:25], v[148:151], v[192:195], v[22:25]
	v_mfma_f32_16x16x32_bf16 v[14:17], v[160:163], v[192:195], v[14:17]
	s_add_u32 s52, s52, 0x80080
	s_addc_u32 s53, s53, 0
	s_add_i32 s38, s39, s56
	v_lshl_add_u64 v[140:141], s[52:53], 0, v[0:1]
	s_mov_b32 m0, s38
	s_nop 0
	global_load_lds_dwordx4 v[140:141], off
	v_lshl_add_u64 v[140:141], s[52:53], 0, v[134:135]
	s_add_i32 m0, s38, 0x2000
	s_nop 0
	global_load_lds_dwordx4 v[140:141], off
	v_mfma_f32_16x16x32_bf16 v[50:53], v[196:199], v[164:167], v[50:53]
	v_mfma_f32_16x16x32_bf16 v[42:45], v[204:207], v[164:167], v[42:45]
	v_mfma_f32_16x16x32_bf16 v[34:37], v[196:199], v[172:175], v[34:37]
	v_mfma_f32_16x16x32_bf16 v[26:29], v[204:207], v[172:175], v[26:29]
	v_mfma_f32_16x16x32_bf16 v[18:21], v[196:199], v[180:183], v[18:21]
	v_mfma_f32_16x16x32_bf16 v[10:13], v[204:207], v[180:183], v[10:13]
	v_mfma_f32_16x16x32_bf16 v[6:9], v[196:199], v[188:191], v[6:9]
	v_mfma_f32_16x16x32_bf16 v[2:5], v[204:207], v[188:191], v[2:5]
	v_mfma_f32_16x16x32_bf16 v[50:53], v[200:203], v[168:171], v[50:53]
	v_mfma_f32_16x16x32_bf16 v[42:45], v[210:213], v[168:171], v[42:45]
	v_mfma_f32_16x16x32_bf16 v[34:37], v[200:203], v[176:179], v[34:37]
	v_mfma_f32_16x16x32_bf16 v[26:29], v[210:213], v[176:179], v[26:29]
	v_mfma_f32_16x16x32_bf16 v[18:21], v[200:203], v[184:187], v[18:21]
	v_mfma_f32_16x16x32_bf16 v[10:13], v[210:213], v[184:187], v[10:13]
	v_mfma_f32_16x16x32_bf16 v[6:9], v[200:203], v[192:195], v[6:9]
	v_mfma_f32_16x16x32_bf16 v[2:5], v[210:213], v[192:195], v[2:5]
	s_setprio 1
	s_add_i32 s70, s70, 2
	s_add_u32 s68, s68, 0x100
	s_addc_u32 s69, s69, 0
	s_add_u32 s50, s50, 0x100
	s_addc_u32 s51, s51, 0
	s_cmp_gt_u32 s70, 29
	s_barrier
	s_cbranch_scc0 .LBB0_354
; __device__ __forceinline__ unsigned cvt_pk_bf16(float lo, float hi) { unsigned r; asm("v_cvt_pk_bf16_f32 %0, %1, %2" : "=v"(r) : "v"(lo), "v"(hi)); return r; }
; #define PG8_WAIT_V(n) asm volatile("s_waitcnt vmcnt(" #n ")" ::: "memory")
; #define PG8_BAR __builtin_amdgcn_s_barrier()
;     __device__ __forceinline__ void operator()(const f32x4 (&acc)[2][2][4][2], const Unit& u, int wr, int wc, int fr, int fq) const {
;         const int row0 = u.pm * BM + wr * 64 + fr, col0 = u.pn * BM + wc * 32 + 8 * fq;
; #pragma unroll
;         for (int ai = 0; ai < 2; ++ai)
; #pragma unroll
;             for (int m = 0; m < 4; ++m) { bf16_t* rowp = O + (size_t)(row0 + ai * HALF + m * 16) * ldc + col0;
; #pragma unroll
;                 for (int bj = 0; bj < 2; ++bj) { f32x4 v0 = acc[ai][bj][m][0], v1 = acc[ai][bj][m][1];
;                     if (ACT == 1) {
; #pragma unroll
;                         for (int j = 0; j < 4; ++j) { float a = fmaxf(v0[j], 0.f), b = fmaxf(v1[j], 0.f); v0[j] = a * a; v1[j] = b * b; } }
;                     u32x4 w; w.x = cvt_pk_bf16(v0[0], v0[1]); w.y = cvt_pk_bf16(v0[2], v0[3]); w.z = cvt_pk_bf16(v1[0], v1[1]); w.w = cvt_pk_bf16(v1[2], v1[3]);
;                     if (ACT == 1) __builtin_nontemporal_store(w, (u32x4*)(rowp + bj * HALF));
;                     else *(u32x4*)(rowp + bj * HALF) = w; } }
; template <class Epi, class Sched>
; __device__ __forceinline__ void gemm_phase(LAS unsigned char* lds, const Gemm g, const Sched& S, const Epi& E) {
;     ...
;         E(acc, cur, wr, wc, fr, fq);
;         if (!has_next) break;
; #pragma unroll
;         for (int a = 0; a < 2; ++a)
; #pragma unroll
;             for (int b = 0; b < 2; ++b)
; #pragma unroll
;                 for (int m = 0; m < 4; ++m)
; #pragma unroll
;                     for (int n = 0; n < 2; ++n) acc[a][b][m][n] = (f32x4){0.f, 0.f, 0.f, 0.f};
;         cur = nxt; cA = nA; cB = nB; ++ui;
;     }
;     PG8_WAIT_V(0);
;     if (wr == 0) PG8_BAR;
;     PG8_BAR;
	s_load_dwordx2 s[50:51], s[0:1], 0xc0
	v_lshl_add_u32 v150, s28, 8, v144
	v_lshl_or_b32 v142, s40, 8, v146
	v_ashrrev_i32_e32 v143, 31, v142
	v_cvt_pk_bf16_f32 v70, v70, v71
	s_waitcnt lgkmcnt(0)
	v_mov_b64_e32 v[140:141], s[50:51]
	v_cvt_pk_bf16_f32 v71, v72, v73
	v_cvt_pk_bf16_f32 v72, v66, v67
	v_add_u32_e32 v66, 0x80, v150
	v_mad_i64_i32 v[148:149], s[50:51], v150, s17, v[140:141]
	v_lshlrev_b64 v[142:143], 1, v[142:143]
	v_cvt_pk_bf16_f32 v114, v114, v115
	v_cvt_pk_bf16_f32 v115, v116, v117
	v_cvt_pk_bf16_f32 v116, v106, v107
	v_or_b32_e32 v106, 16, v150
	v_mad_i64_i32 v[66:67], s[50:51], v66, s17, v[140:141]
	v_cvt_pk_bf16_f32 v50, v50, v51
	v_cvt_pk_bf16_f32 v51, v52, v53
	v_cvt_pk_bf16_f32 v52, v42, v43
	v_add_u32_e32 v42, 0x90, v150
	v_lshl_add_u64 v[148:149], v[148:149], 0, v[142:143]
	v_mad_i64_i32 v[106:107], s[50:51], v106, s17, v[140:141]
	v_cvt_pk_bf16_f32 v98, v98, v99
	v_cvt_pk_bf16_f32 v99, v100, v101
	v_cvt_pk_bf16_f32 v100, v90, v91
	v_or_b32_e32 v90, 32, v150
	v_lshl_add_u64 v[66:67], v[66:67], 0, v[142:143]
	v_mad_i64_i32 v[42:43], s[50:51], v42, s17, v[140:141]
	v_cvt_pk_bf16_f32 v34, v34, v35
	v_cvt_pk_bf16_f32 v35, v36, v37
	v_cvt_pk_bf16_f32 v36, v26, v27
	v_add_u32_e32 v26, 0xa0, v150
	v_cvt_pk_bf16_f32 v117, v108, v109
	global_store_dwordx4 v[148:149], v[114:117], off offset:256
	v_mad_i64_i32 v[90:91], s[50:51], v90, s17, v[140:141]
	s_nop 0
	v_lshl_add_u64 v[114:115], v[106:107], 0, v[142:143]
	v_cvt_pk_bf16_f32 v82, v82, v83
	v_cvt_pk_bf16_f32 v83, v84, v85
	v_cvt_pk_bf16_f32 v84, v74, v75
	v_or_b32_e32 v74, 48, v150
	v_cvt_pk_bf16_f32 v53, v44, v45
	global_store_dwordx4 v[66:67], v[50:53], off offset:256
	v_mad_i64_i32 v[26:27], s[50:51], v26, s17, v[140:141]
	s_nop 0
	v_lshl_add_u64 v[50:51], v[42:43], 0, v[142:143]
	v_cvt_pk_bf16_f32 v18, v18, v19
	v_cvt_pk_bf16_f32 v19, v20, v21
	v_cvt_pk_bf16_f32 v20, v10, v11
	v_add_u32_e32 v10, 0xb0, v150
	v_cvt_pk_bf16_f32 v101, v92, v93
	global_store_dwordx4 v[114:115], v[98:101], off offset:256
	v_mad_i64_i32 v[74:75], s[50:51], v74, s17, v[140:141]
	s_nop 0
	v_lshl_add_u64 v[98:99], v[90:91], 0, v[142:143]
	v_cvt_pk_bf16_f32 v37, v28, v29
	global_store_dwordx4 v[50:51], v[34:37], off offset:256
	v_mad_i64_i32 v[10:11], s[50:51], v10, s17, v[140:141]
	s_nop 0
	v_lshl_add_u64 v[34:35], v[26:27], 0, v[142:143]
	v_cvt_pk_bf16_f32 v85, v76, v77
	global_store_dwordx4 v[98:99], v[82:85], off offset:256
	v_cvt_pk_bf16_f32 v21, v12, v13
	global_store_dwordx4 v[34:35], v[18:21], off offset:256
	s_and_b64 vcc, exec, s[46:47]
	v_lshl_add_u64 v[82:83], v[74:75], 0, v[142:143]
	v_lshl_add_u64 v[18:19], v[10:11], 0, v[142:143]
	s_mov_b32 s40, s42
	s_mov_b32 s28, s8
	s_mov_b32 s43, s42
	s_mov_b32 s46, s8
	s_mov_b64 s[50:51], s[48:49]
	s_mov_b64 s[52:53], s[44:45]
	v_cvt_pk_bf16_f32 v126, v126, v127
	v_cvt_pk_bf16_f32 v127, v128, v129
	v_cvt_pk_bf16_f32 v128, v122, v123
	v_cvt_pk_bf16_f32 v129, v124, v125
	global_store_dwordx4 v[148:149], v[126:129], off
	v_cvt_pk_bf16_f32 v106, v118, v119
	v_cvt_pk_bf16_f32 v107, v120, v121
	v_cvt_pk_bf16_f32 v108, v110, v111
	v_cvt_pk_bf16_f32 v109, v112, v113
	global_store_dwordx4 v[114:115], v[106:109], off
	v_cvt_pk_bf16_f32 v90, v102, v103
	v_cvt_pk_bf16_f32 v91, v104, v105
	v_cvt_pk_bf16_f32 v92, v94, v95
	v_cvt_pk_bf16_f32 v93, v96, v97
	global_store_dwordx4 v[98:99], v[90:93], off
	v_cvt_pk_bf16_f32 v74, v86, v87
	v_cvt_pk_bf16_f32 v75, v88, v89
	v_cvt_pk_bf16_f32 v76, v78, v79
	v_cvt_pk_bf16_f32 v77, v80, v81
	global_store_dwordx4 v[82:83], v[74:77], off
	v_cvt_pk_bf16_f32 v73, v68, v69
	global_store_dwordx4 v[82:83], v[70:73], off offset:256
	v_cvt_pk_bf16_f32 v62, v62, v63
	v_cvt_pk_bf16_f32 v63, v64, v65
	v_cvt_pk_bf16_f32 v64, v58, v59
	v_cvt_pk_bf16_f32 v65, v60, v61
	global_store_dwordx4 v[66:67], v[62:65], off
	v_cvt_pk_bf16_f32 v42, v54, v55
	v_cvt_pk_bf16_f32 v43, v56, v57
	v_cvt_pk_bf16_f32 v44, v46, v47
	v_cvt_pk_bf16_f32 v45, v48, v49
	global_store_dwordx4 v[50:51], v[42:45], off
	v_cvt_pk_bf16_f32 v26, v38, v39
	v_cvt_pk_bf16_f32 v27, v40, v41
	v_cvt_pk_bf16_f32 v28, v30, v31
	v_cvt_pk_bf16_f32 v29, v32, v33
	global_store_dwordx4 v[34:35], v[26:29], off
	v_cvt_pk_bf16_f32 v10, v22, v23
	v_cvt_pk_bf16_f32 v11, v24, v25
	v_cvt_pk_bf16_f32 v12, v14, v15
	v_cvt_pk_bf16_f32 v13, v16, v17
	global_store_dwordx4 v[18:19], v[10:13], off
	v_cvt_pk_bf16_f32 v6, v6, v7
	v_cvt_pk_bf16_f32 v7, v8, v9
	v_cvt_pk_bf16_f32 v8, v2, v3
	v_cvt_pk_bf16_f32 v9, v4, v5
	global_store_dwordx4 v[18:19], v[6:9], off offset:256
	s_cbranch_vccz .LBB0_346
	s_waitcnt vmcnt(0)
	s_cmpk_gt_u32 s25, 0xff
	s_cbranch_scc1 .LBB0_358
	s_barrier
